# MFMA order inside every 32-MFMA K-loop segment changed from (k,m,n) to (k,n,m): the weight fragment (srcA) is held for 4 consecutive MFMAs instead of alternating; accumulation order per accumulator un
# baseline (speedup 1.0000x reference)
; #define PG8_STAGE(bufoff, gbase, voff) do { _Pragma("unroll") for (int _i = 0; _i < 2; ++_i) \
;         __builtin_amdgcn_global_load_lds((const unsigned*)((const char*)(gbase) + (voff)[_i]), (PG8_LAS unsigned*)(lds + (bufoff) + ldsw + _i * 8192), 16, 0, 0); } while (0)
; #define PG8_LDA(dst, b, h) do { _Pragma("unroll") for (int m = 0; m < 4; ++m) _Pragma("unroll") for (int k = 0; k < 2; ++k) dst[m][k] = *(const PG8_LAS bf16x8*)(lds + PG8_SA(b, h) + aoff + m * 2048 + k * 1024); } while (0)
; #define PG8_LDB(dst, b, h) do { _Pragma("unroll") for (int n = 0; n < 2; ++n) _Pragma("unroll") for (int k = 0; k < 2; ++k) dst[n][k] = *(const PG8_LAS bf16x8*)(lds + PG8_SB(b, h) + boff + n * 2048 + k * 1024); } while (0)
; #define PG8_MMA(ai, bj, At, Bt) do { __builtin_amdgcn_s_setprio(1); _Pragma("unroll") for (int m = 0; m < 4; ++m) _Pragma("unroll") for (int n = 0; n < 2; ++n) _Pragma("unroll") for (int k = 0; k < 2; ++k) \
;         acc[ai][bj][m][n] = __builtin_amdgcn_mfma_f32_16x16x32_bf16(Bt[n][k], At[m][k], acc[ai][bj][m][n], 0, 0, 0); __builtin_amdgcn_s_setprio(0); } while (0)
; #define PG8_WAIT_V(n) asm volatile("s_waitcnt vmcnt(" #n ")" ::: "memory")
; #define PG8_WAIT_L(n) asm volatile("s_waitcnt lgkmcnt(" #n ")" ::: "memory")
; template <class Epi, class Sched, bool ALIGN_EPI = false, bool SP2 = false>
; __device__ __forceinline__ void gemm_phase(PG8_LAS unsigned char* lds, const Gemm g, const Sched& S, const Epi& E) {
;     ...
;             const bool last = (t == nt - 2);
;             const char* a1 = cA + (size_t)(t + 1) * kstep;
;             const char* a2 = last ? nA : cA + (size_t)(t + 2) * kstep; const char* b2 = last ? nB : cB + (size_t)(t + 2) * kstep;
;             const char* a3 = a2 + kstep; const char* b3 = b2 + kstep;
;             if (last && has_next) S.a_ready(nxt);
;             if constexpr (SP2) {
;             PG8_LDB(B0, 0, 0); PG8_LDB(B1, 0, 1); PG8_SCHED; PG8_LDA(At, 0, 0); PG8_STAGE(PG8_SA(1, 1), a1 + hstep, voffA);
;             PG8_WAIT_V(8); PG8_WAIT_L(0); PG8_BAR; PG8_MMA(0, 0, At, B0); PG8_MMA(0, 1, At, B1); PG8_BAR; PG8_SCHED;
;             PG8_LDA(At, 0, 1); PG8_STAGE(PG8_SB(0, 0), b2, voffB); PG8_STAGE(PG8_SB(0, 1), b2 + hstep, voffB); PG8_STAGE(PG8_SA(0, 0), a2, voffA);
;             PG8_WAIT_V(8); PG8_WAIT_L(0); PG8_BAR; PG8_MMA(1, 0, At, B0); PG8_MMA(1, 1, At, B1); PG8_BAR; PG8_SCHED;
.Labo_peel:
	ds_read_b128 v[68:71], v254
	ds_read_b128 v[72:75], v254 offset:1024
	ds_read_b128 v[76:79], v254 offset:2048
	ds_read_b128 v[80:83], v254 offset:3072
	ds_read_b128 v[174:177], v254 offset:16384
	ds_read_b128 v[182:185], v254 offset:17408
	ds_read_b128 v[186:189], v254 offset:18432
	ds_read_b128 v[210:213], v254 offset:19456
	s_add_u32 s2, s0, 0xfffc0080
	s_addc_u32 s3, s1, -1
	s_cmp_eq_u32 s56, 12
	s_cselect_b32 s5, s27, s3
	s_cselect_b32 s4, s52, s2
	s_cselect_b32 s3, s25, s55
	s_cselect_b32 s2, s53, s54
	s_add_i32 m0, s29, 0xc000
	ds_read_b128 v[214:217], v179
	ds_read_b128 v[218:221], v179 offset:1024
	ds_read_b128 v[222:225], v179 offset:2048
	ds_read_b128 v[226:229], v179 offset:3072
	ds_read_b128 v[230:233], v179 offset:4096
	ds_read_b128 v[234:237], v179 offset:5120
	ds_read_b128 v[238:241], v179 offset:6144
	ds_read_b128 v[242:245], v179 offset:7168
	global_load_lds_dwordx4 v170, s[0:1]
	s_add_i32 m0, s29, 0xe000
	s_nop 0
	global_load_lds_dwordx4 v172, s[0:1]
	s_waitcnt vmcnt(8)
	s_waitcnt lgkmcnt(0)
	s_barrier
	s_setprio 1
	v_mfma_f32_16x16x32_bf16 v[140:143], v[68:71], v[214:217], 0
	v_mfma_f32_16x16x32_bf16 v[124:127], v[68:71], v[222:225], 0
	v_mfma_f32_16x16x32_bf16 v[108:111], v[68:71], v[230:233], 0
	v_mfma_f32_16x16x32_bf16 v[92:95], v[68:71], v[238:241], 0
	v_mfma_f32_16x16x32_bf16 v[136:139], v[76:79], v[214:217], 0
	v_mfma_f32_16x16x32_bf16 v[120:123], v[76:79], v[222:225], 0
	v_mfma_f32_16x16x32_bf16 v[104:107], v[76:79], v[230:233], 0
	v_mfma_f32_16x16x32_bf16 v[88:91], v[76:79], v[238:241], 0
	v_mfma_f32_16x16x32_bf16 v[140:143], v[72:75], v[218:221], v[140:143]
	v_mfma_f32_16x16x32_bf16 v[124:127], v[72:75], v[226:229], v[124:127]
	v_mfma_f32_16x16x32_bf16 v[108:111], v[72:75], v[234:237], v[108:111]
	v_mfma_f32_16x16x32_bf16 v[92:95], v[72:75], v[242:245], v[92:95]
	v_mfma_f32_16x16x32_bf16 v[136:139], v[80:83], v[218:221], v[136:139]
	v_mfma_f32_16x16x32_bf16 v[120:123], v[80:83], v[226:229], v[120:123]
	v_mfma_f32_16x16x32_bf16 v[104:107], v[80:83], v[234:237], v[104:107]
	v_mfma_f32_16x16x32_bf16 v[88:91], v[80:83], v[242:245], v[88:91]
	v_mfma_f32_16x16x32_bf16 v[132:135], v[174:177], v[214:217], 0
	v_mfma_f32_16x16x32_bf16 v[116:119], v[174:177], v[222:225], 0
	v_mfma_f32_16x16x32_bf16 v[100:103], v[174:177], v[230:233], 0
	v_mfma_f32_16x16x32_bf16 v[84:87], v[174:177], v[238:241], 0
	v_mfma_f32_16x16x32_bf16 v[128:131], v[186:189], v[214:217], 0
	v_mfma_f32_16x16x32_bf16 v[112:115], v[186:189], v[222:225], 0
	v_mfma_f32_16x16x32_bf16 v[96:99], v[186:189], v[230:233], 0
	v_mfma_f32_16x16x32_bf16 v[64:67], v[186:189], v[238:241], 0
	v_mfma_f32_16x16x32_bf16 v[132:135], v[182:185], v[218:221], v[132:135]
	v_mfma_f32_16x16x32_bf16 v[116:119], v[182:185], v[226:229], v[116:119]
	v_mfma_f32_16x16x32_bf16 v[100:103], v[182:185], v[234:237], v[100:103]
	v_mfma_f32_16x16x32_bf16 v[84:87], v[182:185], v[242:245], v[84:87]
	v_mfma_f32_16x16x32_bf16 v[128:131], v[210:213], v[218:221], v[128:131]
	v_mfma_f32_16x16x32_bf16 v[112:115], v[210:213], v[226:229], v[112:115]
	v_mfma_f32_16x16x32_bf16 v[96:99], v[210:213], v[234:237], v[96:99]
	v_mfma_f32_16x16x32_bf16 v[64:67], v[210:213], v[242:245], v[64:67]
	s_setprio 0
	s_barrier
	s_mov_b32 m0, s30
	s_add_u32 s58, s2, 0x40000
	s_addc_u32 s59, s3, 0
	ds_read_b128 v[214:217], v179 offset:16384
	ds_read_b128 v[218:221], v179 offset:17408
	ds_read_b128 v[222:225], v179 offset:18432
	ds_read_b128 v[226:229], v179 offset:19456
	ds_read_b128 v[230:233], v179 offset:20480
	ds_read_b128 v[234:237], v179 offset:21504
	ds_read_b128 v[238:241], v179 offset:22528
	ds_read_b128 v[242:245], v179 offset:23552
	global_load_lds_dwordx4 v166, s[2:3]
	s_mov_b32 m0, s31
	s_nop 0
	global_load_lds_dwordx4 v162, s[2:3]
	s_mov_b32 m0, s33
	s_nop 0
	global_load_lds_dwordx4 v166, s[58:59]
	s_mov_b32 m0, s34
	s_nop 0
	global_load_lds_dwordx4 v162, s[58:59]
	s_mov_b32 m0, s29
	s_nop 0
	global_load_lds_dwordx4 v168, s[4:5]
	s_mov_b32 m0, s35
	s_nop 0
	global_load_lds_dwordx4 v164, s[4:5]
	s_waitcnt vmcnt(8)
	s_waitcnt lgkmcnt(0)
	s_barrier
	s_setprio 1
	v_mfma_f32_16x16x32_bf16 v[60:63], v[68:71], v[214:217], 0
	v_mfma_f32_16x16x32_bf16 v[44:47], v[68:71], v[222:225], 0
	v_mfma_f32_16x16x32_bf16 v[28:31], v[68:71], v[230:233], 0
	v_mfma_f32_16x16x32_bf16 v[12:15], v[68:71], v[238:241], 0
	v_mfma_f32_16x16x32_bf16 v[56:59], v[76:79], v[214:217], 0
	v_mfma_f32_16x16x32_bf16 v[40:43], v[76:79], v[222:225], 0
	v_mfma_f32_16x16x32_bf16 v[24:27], v[76:79], v[230:233], 0
	v_mfma_f32_16x16x32_bf16 v[8:11], v[76:79], v[238:241], 0
	v_mfma_f32_16x16x32_bf16 v[60:63], v[72:75], v[218:221], v[60:63]
	v_mfma_f32_16x16x32_bf16 v[44:47], v[72:75], v[226:229], v[44:47]
	v_mfma_f32_16x16x32_bf16 v[28:31], v[72:75], v[234:237], v[28:31]
	v_mfma_f32_16x16x32_bf16 v[12:15], v[72:75], v[242:245], v[12:15]
	v_mfma_f32_16x16x32_bf16 v[56:59], v[80:83], v[218:221], v[56:59]
	v_mfma_f32_16x16x32_bf16 v[40:43], v[80:83], v[226:229], v[40:43]
	v_mfma_f32_16x16x32_bf16 v[24:27], v[80:83], v[234:237], v[24:27]
	v_mfma_f32_16x16x32_bf16 v[8:11], v[80:83], v[242:245], v[8:11]
	v_mfma_f32_16x16x32_bf16 v[52:55], v[174:177], v[214:217], 0
	v_mfma_f32_16x16x32_bf16 v[36:39], v[174:177], v[222:225], 0
	v_mfma_f32_16x16x32_bf16 v[20:23], v[174:177], v[230:233], 0
	v_mfma_f32_16x16x32_bf16 v[4:7], v[174:177], v[238:241], 0
	v_mfma_f32_16x16x32_bf16 v[48:51], v[186:189], v[214:217], 0
	v_mfma_f32_16x16x32_bf16 v[32:35], v[186:189], v[222:225], 0
	v_mfma_f32_16x16x32_bf16 v[16:19], v[186:189], v[230:233], 0
	v_mfma_f32_16x16x32_bf16 v[0:3], v[186:189], v[238:241], 0
	v_mfma_f32_16x16x32_bf16 v[52:55], v[182:185], v[218:221], v[52:55]
	v_mfma_f32_16x16x32_bf16 v[36:39], v[182:185], v[226:229], v[36:39]
	v_mfma_f32_16x16x32_bf16 v[20:23], v[182:185], v[234:237], v[20:23]
	v_mfma_f32_16x16x32_bf16 v[4:7], v[182:185], v[242:245], v[4:7]
	v_mfma_f32_16x16x32_bf16 v[48:51], v[210:213], v[218:221], v[48:51]
	v_mfma_f32_16x16x32_bf16 v[32:35], v[210:213], v[226:229], v[32:35]
	v_mfma_f32_16x16x32_bf16 v[16:19], v[210:213], v[234:237], v[16:19]
	v_mfma_f32_16x16x32_bf16 v[0:3], v[210:213], v[242:245], v[0:3]
	s_setprio 0
	s_barrier
; #define PG8_STAGE(bufoff, gbase, voff) do { _Pragma("unroll") for (int _i = 0; _i < 2; ++_i) \
;         __builtin_amdgcn_global_load_lds((const unsigned*)((const char*)(gbase) + (voff)[_i]), (PG8_LAS unsigned*)(lds + (bufoff) + ldsw + _i * 8192), 16, 0, 0); } while (0)
; #define PG8_LDA(dst, b, h) do { _Pragma("unroll") for (int m = 0; m < 4; ++m) _Pragma("unroll") for (int k = 0; k < 2; ++k) dst[m][k] = *(const PG8_LAS bf16x8*)(lds + PG8_SA(b, h) + aoff + m * 2048 + k * 1024); } while (0)
; #define PG8_LDB(dst, b, h) do { _Pragma("unroll") for (int n = 0; n < 2; ++n) _Pragma("unroll") for (int k = 0; k < 2; ++k) dst[n][k] = *(const PG8_LAS bf16x8*)(lds + PG8_SB(b, h) + boff + n * 2048 + k * 1024); } while (0)
; #define PG8_MMA(ai, bj, At, Bt) do { __builtin_amdgcn_s_setprio(1); _Pragma("unroll") for (int m = 0; m < 4; ++m) _Pragma("unroll") for (int n = 0; n < 2; ++n) _Pragma("unroll") for (int k = 0; k < 2; ++k) \
;         acc[ai][bj][m][n] = __builtin_amdgcn_mfma_f32_16x16x32_bf16(Bt[n][k], At[m][k], acc[ai][bj][m][n], 0, 0, 0); __builtin_amdgcn_s_setprio(0); } while (0)
; #define PG8_WAIT_V(n) asm volatile("s_waitcnt vmcnt(" #n ")" ::: "memory")
; #define PG8_WAIT_L(n) asm volatile("s_waitcnt lgkmcnt(" #n ")" ::: "memory")
; #define PG8_BAR __builtin_amdgcn_s_barrier()
; #define PG8_SCHED __builtin_amdgcn_sched_barrier(0)
; template <class Epi, class Sched, bool ALIGN_EPI = false, bool SP2 = false>
; __device__ __forceinline__ void gemm_phase(PG8_LAS unsigned char* lds, const Gemm g, const Sched& S, const Epi& E) {
;     ...
;             PG8_LDB(B0, 1, 0); PG8_LDB(B1, 1, 1); PG8_SCHED; PG8_LDA(At, 1, 0); PG8_STAGE(PG8_SA(0, 1), a2 + hstep, voffA);
;             PG8_WAIT_V(8); PG8_WAIT_L(0); PG8_BAR; PG8_MMA(0, 0, At, B0); PG8_MMA(0, 1, At, B1); PG8_BAR; PG8_SCHED;
;             PG8_LDA(At, 1, 1); PG8_STAGE(PG8_SB(1, 0), b3, voffB); PG8_STAGE(PG8_SB(1, 1), b3 + hstep, voffB); PG8_STAGE(PG8_SA(1, 0), a3, voffA);
;             PG8_WAIT_V(8); PG8_WAIT_L(0); PG8_BAR; PG8_MMA(1, 0, At, B0); PG8_MMA(1, 1, At, B1); PG8_BAR; PG8_SCHED;
	ds_read_b128 v[68:71], v254 offset:32768
	ds_read_b128 v[72:75], v254 offset:33792
	ds_read_b128 v[76:79], v254 offset:34816
	ds_read_b128 v[80:83], v254 offset:35840
	ds_read_b128 v[174:177], v254 offset:49152
	ds_read_b128 v[182:185], v254 offset:50176
	ds_read_b128 v[186:189], v254 offset:51200
	ds_read_b128 v[210:213], v254 offset:52224
	s_add_u32 s4, s4, 0x40000
	s_addc_u32 s5, s5, 0
	s_mov_b32 m0, s40
	ds_read_b128 v[214:217], v179 offset:32768
	ds_read_b128 v[218:221], v179 offset:33792
	ds_read_b128 v[222:225], v179 offset:34816
	ds_read_b128 v[226:229], v179 offset:35840
	ds_read_b128 v[230:233], v179 offset:36864
	ds_read_b128 v[234:237], v179 offset:37888
	ds_read_b128 v[238:241], v179 offset:38912
	ds_read_b128 v[242:245], v179 offset:39936
	global_load_lds_dwordx4 v168, s[4:5]
	s_mov_b32 m0, s41
	s_nop 0
	global_load_lds_dwordx4 v164, s[4:5]
	s_waitcnt vmcnt(8)
	s_waitcnt lgkmcnt(0)
	s_barrier
	s_setprio 1
	v_mfma_f32_16x16x32_bf16 v[140:143], v[68:71], v[214:217], v[140:143]
	v_mfma_f32_16x16x32_bf16 v[124:127], v[68:71], v[222:225], v[124:127]
	v_mfma_f32_16x16x32_bf16 v[108:111], v[68:71], v[230:233], v[108:111]
	v_mfma_f32_16x16x32_bf16 v[92:95], v[68:71], v[238:241], v[92:95]
	v_mfma_f32_16x16x32_bf16 v[136:139], v[76:79], v[214:217], v[136:139]
	v_mfma_f32_16x16x32_bf16 v[120:123], v[76:79], v[222:225], v[120:123]
	v_mfma_f32_16x16x32_bf16 v[104:107], v[76:79], v[230:233], v[104:107]
	v_mfma_f32_16x16x32_bf16 v[88:91], v[76:79], v[238:241], v[88:91]
	v_mfma_f32_16x16x32_bf16 v[140:143], v[72:75], v[218:221], v[140:143]
	v_mfma_f32_16x16x32_bf16 v[124:127], v[72:75], v[226:229], v[124:127]
	v_mfma_f32_16x16x32_bf16 v[108:111], v[72:75], v[234:237], v[108:111]
	v_mfma_f32_16x16x32_bf16 v[92:95], v[72:75], v[242:245], v[92:95]
	v_mfma_f32_16x16x32_bf16 v[136:139], v[80:83], v[218:221], v[136:139]
	v_mfma_f32_16x16x32_bf16 v[120:123], v[80:83], v[226:229], v[120:123]
	v_mfma_f32_16x16x32_bf16 v[104:107], v[80:83], v[234:237], v[104:107]
	v_mfma_f32_16x16x32_bf16 v[88:91], v[80:83], v[242:245], v[88:91]
	v_mfma_f32_16x16x32_bf16 v[132:135], v[174:177], v[214:217], v[132:135]
	v_mfma_f32_16x16x32_bf16 v[116:119], v[174:177], v[222:225], v[116:119]
	v_mfma_f32_16x16x32_bf16 v[100:103], v[174:177], v[230:233], v[100:103]
	v_mfma_f32_16x16x32_bf16 v[84:87], v[174:177], v[238:241], v[84:87]
	v_mfma_f32_16x16x32_bf16 v[128:131], v[186:189], v[214:217], v[128:131]
	v_mfma_f32_16x16x32_bf16 v[112:115], v[186:189], v[222:225], v[112:115]
	v_mfma_f32_16x16x32_bf16 v[96:99], v[186:189], v[230:233], v[96:99]
	v_mfma_f32_16x16x32_bf16 v[64:67], v[186:189], v[238:241], v[64:67]
	v_mfma_f32_16x16x32_bf16 v[132:135], v[182:185], v[218:221], v[132:135]
	v_mfma_f32_16x16x32_bf16 v[116:119], v[182:185], v[226:229], v[116:119]
	v_mfma_f32_16x16x32_bf16 v[100:103], v[182:185], v[234:237], v[100:103]
	v_mfma_f32_16x16x32_bf16 v[84:87], v[182:185], v[242:245], v[84:87]
	v_mfma_f32_16x16x32_bf16 v[128:131], v[210:213], v[218:221], v[128:131]
	v_mfma_f32_16x16x32_bf16 v[112:115], v[210:213], v[226:229], v[112:115]
	v_mfma_f32_16x16x32_bf16 v[96:99], v[210:213], v[234:237], v[96:99]
	v_mfma_f32_16x16x32_bf16 v[64:67], v[210:213], v[242:245], v[64:67]
	s_setprio 0
	s_barrier
	s_mov_b32 m0, s45
	s_add_u32 s2, s2, 0x40080
	s_addc_u32 s3, s3, 0
	ds_read_b128 v[214:217], v179 offset:49152
	ds_read_b128 v[218:221], v179 offset:50176
	ds_read_b128 v[222:225], v179 offset:51200
	ds_read_b128 v[226:229], v179 offset:52224
	ds_read_b128 v[230:233], v179 offset:53248
	ds_read_b128 v[234:237], v179 offset:54272
	ds_read_b128 v[238:241], v179 offset:55296
	ds_read_b128 v[242:245], v179 offset:56320
	s_add_u32 s98, s2, 0xfffc0000
	s_addc_u32 s99, s3, -1
	global_load_lds_dwordx4 v166, s[98:99]
	s_mov_b32 m0, s46
	s_nop 0
	global_load_lds_dwordx4 v162, s[98:99]
	s_mov_b32 m0, s49
	s_nop 0
	global_load_lds_dwordx4 v166, s[2:3]
	s_mov_b32 m0, s50
	s_nop 0
	global_load_lds_dwordx4 v162, s[2:3]
	s_mov_b32 m0, s47
	s_nop 0
	s_add_u32 s100, s4, 0xfffc0080
	s_addc_u32 s101, s5, -1
	global_load_lds_dwordx4 v168, s[100:101]
	s_mov_b32 m0, s48
	s_nop 0
	global_load_lds_dwordx4 v164, s[100:101]
	s_waitcnt vmcnt(8)
	s_waitcnt lgkmcnt(0)
	s_barrier
	s_setprio 1
	v_mfma_f32_16x16x32_bf16 v[60:63], v[68:71], v[214:217], v[60:63]
	v_mfma_f32_16x16x32_bf16 v[44:47], v[68:71], v[222:225], v[44:47]
	v_mfma_f32_16x16x32_bf16 v[28:31], v[68:71], v[230:233], v[28:31]
	v_mfma_f32_16x16x32_bf16 v[12:15], v[68:71], v[238:241], v[12:15]
	v_mfma_f32_16x16x32_bf16 v[56:59], v[76:79], v[214:217], v[56:59]
	v_mfma_f32_16x16x32_bf16 v[40:43], v[76:79], v[222:225], v[40:43]
	v_mfma_f32_16x16x32_bf16 v[24:27], v[76:79], v[230:233], v[24:27]
	v_mfma_f32_16x16x32_bf16 v[8:11], v[76:79], v[238:241], v[8:11]
	v_mfma_f32_16x16x32_bf16 v[60:63], v[72:75], v[218:221], v[60:63]
	v_mfma_f32_16x16x32_bf16 v[44:47], v[72:75], v[226:229], v[44:47]
	v_mfma_f32_16x16x32_bf16 v[28:31], v[72:75], v[234:237], v[28:31]
	v_mfma_f32_16x16x32_bf16 v[12:15], v[72:75], v[242:245], v[12:15]
	v_mfma_f32_16x16x32_bf16 v[56:59], v[80:83], v[218:221], v[56:59]
	v_mfma_f32_16x16x32_bf16 v[40:43], v[80:83], v[226:229], v[40:43]
	v_mfma_f32_16x16x32_bf16 v[24:27], v[80:83], v[234:237], v[24:27]
	v_mfma_f32_16x16x32_bf16 v[8:11], v[80:83], v[242:245], v[8:11]
	v_mfma_f32_16x16x32_bf16 v[52:55], v[174:177], v[214:217], v[52:55]
	v_mfma_f32_16x16x32_bf16 v[36:39], v[174:177], v[222:225], v[36:39]
	v_mfma_f32_16x16x32_bf16 v[20:23], v[174:177], v[230:233], v[20:23]
	v_mfma_f32_16x16x32_bf16 v[4:7], v[174:177], v[238:241], v[4:7]
	v_mfma_f32_16x16x32_bf16 v[48:51], v[186:189], v[214:217], v[48:51]
	v_mfma_f32_16x16x32_bf16 v[32:35], v[186:189], v[222:225], v[32:35]
	v_mfma_f32_16x16x32_bf16 v[16:19], v[186:189], v[230:233], v[16:19]
	v_mfma_f32_16x16x32_bf16 v[0:3], v[186:189], v[238:241], v[0:3]
	v_mfma_f32_16x16x32_bf16 v[52:55], v[182:185], v[218:221], v[52:55]
	v_mfma_f32_16x16x32_bf16 v[36:39], v[182:185], v[226:229], v[36:39]
	v_mfma_f32_16x16x32_bf16 v[20:23], v[182:185], v[234:237], v[20:23]
	v_mfma_f32_16x16x32_bf16 v[4:7], v[182:185], v[242:245], v[4:7]
	v_mfma_f32_16x16x32_bf16 v[48:51], v[210:213], v[218:221], v[48:51]
	v_mfma_f32_16x16x32_bf16 v[32:35], v[210:213], v[226:229], v[32:35]
	v_mfma_f32_16x16x32_bf16 v[16:19], v[210:213], v[234:237], v[16:19]
	v_mfma_f32_16x16x32_bf16 v[0:3], v[210:213], v[242:245], v[0:3]
	s_setprio 0
	s_barrier
	s_add_i32 s56, s56, 2
	s_add_u32 s0, s0, 0x100
	s_addc_u32 s1, s1, 0
	s_add_u32 s54, s54, 0x100
	s_addc_u32 s55, s55, 0
	s_cmp_gt_u32 s56, 13
; #define PG8_STAGE(bufoff, gbase, voff) do { _Pragma("unroll") for (int _i = 0; _i < 2; ++_i) \
;         __builtin_amdgcn_global_load_lds((const unsigned*)((const char*)(gbase) + (voff)[_i]), (PG8_LAS unsigned*)(lds + (bufoff) + ldsw + _i * 8192), 16, 0, 0); } while (0)
; #define PG8_LDA(dst, b, h) do { _Pragma("unroll") for (int m = 0; m < 4; ++m) _Pragma("unroll") for (int k = 0; k < 2; ++k) dst[m][k] = *(const PG8_LAS bf16x8*)(lds + PG8_SA(b, h) + aoff + m * 2048 + k * 1024); } while (0)
; #define PG8_LDB(dst, b, h) do { _Pragma("unroll") for (int n = 0; n < 2; ++n) _Pragma("unroll") for (int k = 0; k < 2; ++k) dst[n][k] = *(const PG8_LAS bf16x8*)(lds + PG8_SB(b, h) + boff + n * 2048 + k * 1024); } while (0)
; #define PG8_MMA(ai, bj, At, Bt) do { __builtin_amdgcn_s_setprio(1); _Pragma("unroll") for (int m = 0; m < 4; ++m) _Pragma("unroll") for (int n = 0; n < 2; ++n) _Pragma("unroll") for (int k = 0; k < 2; ++k) \
;         acc[ai][bj][m][n] = __builtin_amdgcn_mfma_f32_16x16x32_bf16(Bt[n][k], At[m][k], acc[ai][bj][m][n], 0, 0, 0); __builtin_amdgcn_s_setprio(0); } while (0)
; #define PG8_WAIT_V(n) asm volatile("s_waitcnt vmcnt(" #n ")" ::: "memory")
; #define PG8_WAIT_L(n) asm volatile("s_waitcnt lgkmcnt(" #n ")" ::: "memory")
; template <class Epi, class Sched, bool ALIGN_EPI = false, bool SP2 = false>
; __device__ __forceinline__ void gemm_phase(PG8_LAS unsigned char* lds, const Gemm g, const Sched& S, const Epi& E) {
;     ...
;             const bool last = (t == nt - 2);
;             const char* a1 = cA + (size_t)(t + 1) * kstep;
;             const char* a2 = last ? nA : cA + (size_t)(t + 2) * kstep; const char* b2 = last ? nB : cB + (size_t)(t + 2) * kstep;
;             const char* a3 = a2 + kstep; const char* b3 = b2 + kstep;
;             if (last && has_next) S.a_ready(nxt);
;             if constexpr (SP2) {
;             PG8_LDB(B0, 0, 0); PG8_LDB(B1, 0, 1); PG8_SCHED; PG8_LDA(At, 0, 0); PG8_STAGE(PG8_SA(1, 1), a1 + hstep, voffA);
;             PG8_WAIT_V(8); PG8_WAIT_L(0); PG8_BAR; PG8_MMA(0, 0, At, B0); PG8_MMA(0, 1, At, B1); PG8_BAR; PG8_SCHED;
;             PG8_LDA(At, 0, 1); PG8_STAGE(PG8_SB(0, 0), b2, voffB); PG8_STAGE(PG8_SB(0, 1), b2 + hstep, voffB); PG8_STAGE(PG8_SA(0, 0), a2, voffA);
;             PG8_WAIT_V(8); PG8_WAIT_L(0); PG8_BAR; PG8_MMA(1, 0, At, B0); PG8_MMA(1, 1, At, B1); PG8_BAR; PG8_SCHED;
.LBB0_327:
	ds_read_b128 v[68:71], v254
	ds_read_b128 v[72:75], v254 offset:1024
	ds_read_b128 v[76:79], v254 offset:2048
	ds_read_b128 v[80:83], v254 offset:3072
	ds_read_b128 v[174:177], v254 offset:16384
	ds_read_b128 v[182:185], v254 offset:17408
	ds_read_b128 v[186:189], v254 offset:18432
	ds_read_b128 v[210:213], v254 offset:19456
	s_add_u32 s2, s0, 0xfffc0080
	s_addc_u32 s3, s1, -1
	s_cmp_eq_u32 s56, 12
	s_cselect_b32 s5, s27, s3
	s_cselect_b32 s4, s52, s2
	s_cselect_b32 s3, s25, s55
	s_cselect_b32 s2, s53, s54
	s_add_i32 m0, s29, 0xc000
	ds_read_b128 v[214:217], v179
	ds_read_b128 v[218:221], v179 offset:1024
	ds_read_b128 v[222:225], v179 offset:2048
	ds_read_b128 v[226:229], v179 offset:3072
	ds_read_b128 v[230:233], v179 offset:4096
	ds_read_b128 v[234:237], v179 offset:5120
	ds_read_b128 v[238:241], v179 offset:6144
	ds_read_b128 v[242:245], v179 offset:7168
	global_load_lds_dwordx4 v170, s[0:1]
	s_add_i32 m0, s29, 0xe000
	s_nop 0
	global_load_lds_dwordx4 v172, s[0:1]
	s_waitcnt vmcnt(8)
	s_waitcnt lgkmcnt(0)
	s_barrier
	s_setprio 1
	v_mfma_f32_16x16x32_bf16 v[140:143], v[68:71], v[214:217], v[140:143]
	v_mfma_f32_16x16x32_bf16 v[124:127], v[68:71], v[222:225], v[124:127]
	v_mfma_f32_16x16x32_bf16 v[108:111], v[68:71], v[230:233], v[108:111]
	v_mfma_f32_16x16x32_bf16 v[92:95], v[68:71], v[238:241], v[92:95]
	v_mfma_f32_16x16x32_bf16 v[136:139], v[76:79], v[214:217], v[136:139]
	v_mfma_f32_16x16x32_bf16 v[120:123], v[76:79], v[222:225], v[120:123]
	v_mfma_f32_16x16x32_bf16 v[104:107], v[76:79], v[230:233], v[104:107]
	v_mfma_f32_16x16x32_bf16 v[88:91], v[76:79], v[238:241], v[88:91]
	v_mfma_f32_16x16x32_bf16 v[140:143], v[72:75], v[218:221], v[140:143]
	v_mfma_f32_16x16x32_bf16 v[124:127], v[72:75], v[226:229], v[124:127]
	v_mfma_f32_16x16x32_bf16 v[108:111], v[72:75], v[234:237], v[108:111]
	v_mfma_f32_16x16x32_bf16 v[92:95], v[72:75], v[242:245], v[92:95]
	v_mfma_f32_16x16x32_bf16 v[136:139], v[80:83], v[218:221], v[136:139]
	v_mfma_f32_16x16x32_bf16 v[120:123], v[80:83], v[226:229], v[120:123]
	v_mfma_f32_16x16x32_bf16 v[104:107], v[80:83], v[234:237], v[104:107]
	v_mfma_f32_16x16x32_bf16 v[88:91], v[80:83], v[242:245], v[88:91]
	v_mfma_f32_16x16x32_bf16 v[132:135], v[174:177], v[214:217], v[132:135]
	v_mfma_f32_16x16x32_bf16 v[116:119], v[174:177], v[222:225], v[116:119]
	v_mfma_f32_16x16x32_bf16 v[100:103], v[174:177], v[230:233], v[100:103]
	v_mfma_f32_16x16x32_bf16 v[84:87], v[174:177], v[238:241], v[84:87]
	v_mfma_f32_16x16x32_bf16 v[128:131], v[186:189], v[214:217], v[128:131]
	v_mfma_f32_16x16x32_bf16 v[112:115], v[186:189], v[222:225], v[112:115]
	v_mfma_f32_16x16x32_bf16 v[96:99], v[186:189], v[230:233], v[96:99]
	v_mfma_f32_16x16x32_bf16 v[64:67], v[186:189], v[238:241], v[64:67]
	v_mfma_f32_16x16x32_bf16 v[132:135], v[182:185], v[218:221], v[132:135]
	v_mfma_f32_16x16x32_bf16 v[116:119], v[182:185], v[226:229], v[116:119]
	v_mfma_f32_16x16x32_bf16 v[100:103], v[182:185], v[234:237], v[100:103]
	v_mfma_f32_16x16x32_bf16 v[84:87], v[182:185], v[242:245], v[84:87]
	v_mfma_f32_16x16x32_bf16 v[128:131], v[210:213], v[218:221], v[128:131]
	v_mfma_f32_16x16x32_bf16 v[112:115], v[210:213], v[226:229], v[112:115]
	v_mfma_f32_16x16x32_bf16 v[96:99], v[210:213], v[234:237], v[96:99]
	v_mfma_f32_16x16x32_bf16 v[64:67], v[210:213], v[242:245], v[64:67]
	s_setprio 0
	s_barrier
	s_mov_b32 m0, s30
	s_add_u32 s58, s2, 0x40000
	s_addc_u32 s59, s3, 0
	ds_read_b128 v[214:217], v179 offset:16384
	ds_read_b128 v[218:221], v179 offset:17408
	ds_read_b128 v[222:225], v179 offset:18432
	ds_read_b128 v[226:229], v179 offset:19456
	ds_read_b128 v[230:233], v179 offset:20480
	ds_read_b128 v[234:237], v179 offset:21504
	ds_read_b128 v[238:241], v179 offset:22528
	ds_read_b128 v[242:245], v179 offset:23552
	global_load_lds_dwordx4 v166, s[2:3]
	s_mov_b32 m0, s31
	s_nop 0
	global_load_lds_dwordx4 v162, s[2:3]
	s_mov_b32 m0, s33
	s_nop 0
	global_load_lds_dwordx4 v166, s[58:59]
	s_mov_b32 m0, s34
	s_nop 0
	global_load_lds_dwordx4 v162, s[58:59]
	s_mov_b32 m0, s29
	s_nop 0
	global_load_lds_dwordx4 v168, s[4:5]
	s_mov_b32 m0, s35
	s_nop 0
	global_load_lds_dwordx4 v164, s[4:5]
	s_waitcnt vmcnt(8)
	s_waitcnt lgkmcnt(0)
	s_barrier
	s_setprio 1
	v_mfma_f32_16x16x32_bf16 v[60:63], v[68:71], v[214:217], v[60:63]
	v_mfma_f32_16x16x32_bf16 v[44:47], v[68:71], v[222:225], v[44:47]
	v_mfma_f32_16x16x32_bf16 v[28:31], v[68:71], v[230:233], v[28:31]
	v_mfma_f32_16x16x32_bf16 v[12:15], v[68:71], v[238:241], v[12:15]
	v_mfma_f32_16x16x32_bf16 v[56:59], v[76:79], v[214:217], v[56:59]
	v_mfma_f32_16x16x32_bf16 v[40:43], v[76:79], v[222:225], v[40:43]
	v_mfma_f32_16x16x32_bf16 v[24:27], v[76:79], v[230:233], v[24:27]
	v_mfma_f32_16x16x32_bf16 v[8:11], v[76:79], v[238:241], v[8:11]
	v_mfma_f32_16x16x32_bf16 v[60:63], v[72:75], v[218:221], v[60:63]
	v_mfma_f32_16x16x32_bf16 v[44:47], v[72:75], v[226:229], v[44:47]
	v_mfma_f32_16x16x32_bf16 v[28:31], v[72:75], v[234:237], v[28:31]
	v_mfma_f32_16x16x32_bf16 v[12:15], v[72:75], v[242:245], v[12:15]
	v_mfma_f32_16x16x32_bf16 v[56:59], v[80:83], v[218:221], v[56:59]
	v_mfma_f32_16x16x32_bf16 v[40:43], v[80:83], v[226:229], v[40:43]
	v_mfma_f32_16x16x32_bf16 v[24:27], v[80:83], v[234:237], v[24:27]
	v_mfma_f32_16x16x32_bf16 v[8:11], v[80:83], v[242:245], v[8:11]
	v_mfma_f32_16x16x32_bf16 v[52:55], v[174:177], v[214:217], v[52:55]
	v_mfma_f32_16x16x32_bf16 v[36:39], v[174:177], v[222:225], v[36:39]
	v_mfma_f32_16x16x32_bf16 v[20:23], v[174:177], v[230:233], v[20:23]
	v_mfma_f32_16x16x32_bf16 v[4:7], v[174:177], v[238:241], v[4:7]
	v_mfma_f32_16x16x32_bf16 v[48:51], v[186:189], v[214:217], v[48:51]
	v_mfma_f32_16x16x32_bf16 v[32:35], v[186:189], v[222:225], v[32:35]
	v_mfma_f32_16x16x32_bf16 v[16:19], v[186:189], v[230:233], v[16:19]
	v_mfma_f32_16x16x32_bf16 v[0:3], v[186:189], v[238:241], v[0:3]
	v_mfma_f32_16x16x32_bf16 v[52:55], v[182:185], v[218:221], v[52:55]
	v_mfma_f32_16x16x32_bf16 v[36:39], v[182:185], v[226:229], v[36:39]
	v_mfma_f32_16x16x32_bf16 v[20:23], v[182:185], v[234:237], v[20:23]
	v_mfma_f32_16x16x32_bf16 v[4:7], v[182:185], v[242:245], v[4:7]
	v_mfma_f32_16x16x32_bf16 v[48:51], v[210:213], v[218:221], v[48:51]
	v_mfma_f32_16x16x32_bf16 v[32:35], v[210:213], v[226:229], v[32:35]
	v_mfma_f32_16x16x32_bf16 v[16:19], v[210:213], v[234:237], v[16:19]
	v_mfma_f32_16x16x32_bf16 v[0:3], v[210:213], v[242:245], v[0:3]
	s_setprio 0
	s_barrier
; #define PG8_STAGE(bufoff, gbase, voff) do { _Pragma("unroll") for (int _i = 0; _i < 2; ++_i) \
;         __builtin_amdgcn_global_load_lds((const unsigned*)((const char*)(gbase) + (voff)[_i]), (PG8_LAS unsigned*)(lds + (bufoff) + ldsw + _i * 8192), 16, 0, 0); } while (0)
; #define PG8_LDA(dst, b, h) do { _Pragma("unroll") for (int m = 0; m < 4; ++m) _Pragma("unroll") for (int k = 0; k < 2; ++k) dst[m][k] = *(const PG8_LAS bf16x8*)(lds + PG8_SA(b, h) + aoff + m * 2048 + k * 1024); } while (0)
; #define PG8_LDB(dst, b, h) do { _Pragma("unroll") for (int n = 0; n < 2; ++n) _Pragma("unroll") for (int k = 0; k < 2; ++k) dst[n][k] = *(const PG8_LAS bf16x8*)(lds + PG8_SB(b, h) + boff + n * 2048 + k * 1024); } while (0)
; #define PG8_MMA(ai, bj, At, Bt) do { __builtin_amdgcn_s_setprio(1); _Pragma("unroll") for (int m = 0; m < 4; ++m) _Pragma("unroll") for (int n = 0; n < 2; ++n) _Pragma("unroll") for (int k = 0; k < 2; ++k) \
;         acc[ai][bj][m][n] = __builtin_amdgcn_mfma_f32_16x16x32_bf16(Bt[n][k], At[m][k], acc[ai][bj][m][n], 0, 0, 0); __builtin_amdgcn_s_setprio(0); } while (0)
; #define PG8_WAIT_V(n) asm volatile("s_waitcnt vmcnt(" #n ")" ::: "memory")
; #define PG8_WAIT_L(n) asm volatile("s_waitcnt lgkmcnt(" #n ")" ::: "memory")
; #define PG8_BAR __builtin_amdgcn_s_barrier()
; #define PG8_SCHED __builtin_amdgcn_sched_barrier(0)
; template <class Epi, class Sched, bool ALIGN_EPI = false, bool SP2 = false>
; __device__ __forceinline__ void gemm_phase(PG8_LAS unsigned char* lds, const Gemm g, const Sched& S, const Epi& E) {
;     ...
;             PG8_LDB(B0, 1, 0); PG8_LDB(B1, 1, 1); PG8_SCHED; PG8_LDA(At, 1, 0); PG8_STAGE(PG8_SA(0, 1), a2 + hstep, voffA);
;             PG8_WAIT_V(8); PG8_WAIT_L(0); PG8_BAR; PG8_MMA(0, 0, At, B0); PG8_MMA(0, 1, At, B1); PG8_BAR; PG8_SCHED;
;             PG8_LDA(At, 1, 1); PG8_STAGE(PG8_SB(1, 0), b3, voffB); PG8_STAGE(PG8_SB(1, 1), b3 + hstep, voffB); PG8_STAGE(PG8_SA(1, 0), a3, voffA);
;             PG8_WAIT_V(8); PG8_WAIT_L(0); PG8_BAR; PG8_MMA(1, 0, At, B0); PG8_MMA(1, 1, At, B1); PG8_BAR; PG8_SCHED;
;     ...
;         if constexpr (ALIGN_EPI) { if (wr == 0) PG8_BAR; }
	ds_read_b128 v[68:71], v254 offset:32768
	ds_read_b128 v[72:75], v254 offset:33792
	ds_read_b128 v[76:79], v254 offset:34816
	ds_read_b128 v[80:83], v254 offset:35840
	ds_read_b128 v[174:177], v254 offset:49152
	ds_read_b128 v[182:185], v254 offset:50176
	ds_read_b128 v[186:189], v254 offset:51200
	ds_read_b128 v[210:213], v254 offset:52224
	s_add_u32 s4, s4, 0x40000
	s_addc_u32 s5, s5, 0
	s_mov_b32 m0, s40
	ds_read_b128 v[214:217], v179 offset:32768
	ds_read_b128 v[218:221], v179 offset:33792
	ds_read_b128 v[222:225], v179 offset:34816
	ds_read_b128 v[226:229], v179 offset:35840
	ds_read_b128 v[230:233], v179 offset:36864
	ds_read_b128 v[234:237], v179 offset:37888
	ds_read_b128 v[238:241], v179 offset:38912
	ds_read_b128 v[242:245], v179 offset:39936
	global_load_lds_dwordx4 v168, s[4:5]
	s_mov_b32 m0, s41
	s_nop 0
	global_load_lds_dwordx4 v164, s[4:5]
	s_waitcnt vmcnt(8)
	s_waitcnt lgkmcnt(0)
	s_barrier
	s_setprio 1
	v_mfma_f32_16x16x32_bf16 v[140:143], v[68:71], v[214:217], v[140:143]
	v_mfma_f32_16x16x32_bf16 v[124:127], v[68:71], v[222:225], v[124:127]
	v_mfma_f32_16x16x32_bf16 v[108:111], v[68:71], v[230:233], v[108:111]
	v_mfma_f32_16x16x32_bf16 v[92:95], v[68:71], v[238:241], v[92:95]
	v_mfma_f32_16x16x32_bf16 v[136:139], v[76:79], v[214:217], v[136:139]
	v_mfma_f32_16x16x32_bf16 v[120:123], v[76:79], v[222:225], v[120:123]
	v_mfma_f32_16x16x32_bf16 v[104:107], v[76:79], v[230:233], v[104:107]
	v_mfma_f32_16x16x32_bf16 v[88:91], v[76:79], v[238:241], v[88:91]
	v_mfma_f32_16x16x32_bf16 v[140:143], v[72:75], v[218:221], v[140:143]
	v_mfma_f32_16x16x32_bf16 v[124:127], v[72:75], v[226:229], v[124:127]
	v_mfma_f32_16x16x32_bf16 v[108:111], v[72:75], v[234:237], v[108:111]
	v_mfma_f32_16x16x32_bf16 v[92:95], v[72:75], v[242:245], v[92:95]
	v_mfma_f32_16x16x32_bf16 v[136:139], v[80:83], v[218:221], v[136:139]
	v_mfma_f32_16x16x32_bf16 v[120:123], v[80:83], v[226:229], v[120:123]
	v_mfma_f32_16x16x32_bf16 v[104:107], v[80:83], v[234:237], v[104:107]
	v_mfma_f32_16x16x32_bf16 v[88:91], v[80:83], v[242:245], v[88:91]
	v_mfma_f32_16x16x32_bf16 v[132:135], v[174:177], v[214:217], v[132:135]
	v_mfma_f32_16x16x32_bf16 v[116:119], v[174:177], v[222:225], v[116:119]
	v_mfma_f32_16x16x32_bf16 v[100:103], v[174:177], v[230:233], v[100:103]
	v_mfma_f32_16x16x32_bf16 v[84:87], v[174:177], v[238:241], v[84:87]
	v_mfma_f32_16x16x32_bf16 v[128:131], v[186:189], v[214:217], v[128:131]
	v_mfma_f32_16x16x32_bf16 v[112:115], v[186:189], v[222:225], v[112:115]
	v_mfma_f32_16x16x32_bf16 v[96:99], v[186:189], v[230:233], v[96:99]
	v_mfma_f32_16x16x32_bf16 v[64:67], v[186:189], v[238:241], v[64:67]
	v_mfma_f32_16x16x32_bf16 v[132:135], v[182:185], v[218:221], v[132:135]
	v_mfma_f32_16x16x32_bf16 v[116:119], v[182:185], v[226:229], v[116:119]
	v_mfma_f32_16x16x32_bf16 v[100:103], v[182:185], v[234:237], v[100:103]
	v_mfma_f32_16x16x32_bf16 v[84:87], v[182:185], v[242:245], v[84:87]
	v_mfma_f32_16x16x32_bf16 v[128:131], v[210:213], v[218:221], v[128:131]
	v_mfma_f32_16x16x32_bf16 v[112:115], v[210:213], v[226:229], v[112:115]
	v_mfma_f32_16x16x32_bf16 v[96:99], v[210:213], v[234:237], v[96:99]
	v_mfma_f32_16x16x32_bf16 v[64:67], v[210:213], v[242:245], v[64:67]
	s_setprio 0
	s_barrier
	s_mov_b32 m0, s45
	s_add_u32 s2, s2, 0x40080
	s_addc_u32 s3, s3, 0
	ds_read_b128 v[214:217], v179 offset:49152
	ds_read_b128 v[218:221], v179 offset:50176
	ds_read_b128 v[222:225], v179 offset:51200
	ds_read_b128 v[226:229], v179 offset:52224
	ds_read_b128 v[230:233], v179 offset:53248
	ds_read_b128 v[234:237], v179 offset:54272
	ds_read_b128 v[238:241], v179 offset:55296
	ds_read_b128 v[242:245], v179 offset:56320
	s_add_u32 s98, s2, 0xfffc0000
	s_addc_u32 s99, s3, -1
	global_load_lds_dwordx4 v166, s[98:99]
	s_mov_b32 m0, s46
	s_nop 0
	global_load_lds_dwordx4 v162, s[98:99]
	s_mov_b32 m0, s49
	s_nop 0
	global_load_lds_dwordx4 v166, s[2:3]
	s_mov_b32 m0, s50
	s_nop 0
	global_load_lds_dwordx4 v162, s[2:3]
	s_mov_b32 m0, s47
	s_nop 0
	s_add_u32 s100, s4, 0xfffc0080
	s_addc_u32 s101, s5, -1
	global_load_lds_dwordx4 v168, s[100:101]
	s_mov_b32 m0, s48
	s_nop 0
	global_load_lds_dwordx4 v164, s[100:101]
	s_waitcnt vmcnt(8)
	s_waitcnt lgkmcnt(0)
	s_barrier
	s_setprio 1
	v_mfma_f32_16x16x32_bf16 v[60:63], v[68:71], v[214:217], v[60:63]
	v_mfma_f32_16x16x32_bf16 v[44:47], v[68:71], v[222:225], v[44:47]
	v_mfma_f32_16x16x32_bf16 v[28:31], v[68:71], v[230:233], v[28:31]
	v_mfma_f32_16x16x32_bf16 v[12:15], v[68:71], v[238:241], v[12:15]
	v_mfma_f32_16x16x32_bf16 v[56:59], v[76:79], v[214:217], v[56:59]
	v_mfma_f32_16x16x32_bf16 v[40:43], v[76:79], v[222:225], v[40:43]
	v_mfma_f32_16x16x32_bf16 v[24:27], v[76:79], v[230:233], v[24:27]
	v_mfma_f32_16x16x32_bf16 v[8:11], v[76:79], v[238:241], v[8:11]
	v_mfma_f32_16x16x32_bf16 v[60:63], v[72:75], v[218:221], v[60:63]
	v_mfma_f32_16x16x32_bf16 v[44:47], v[72:75], v[226:229], v[44:47]
	v_mfma_f32_16x16x32_bf16 v[28:31], v[72:75], v[234:237], v[28:31]
	v_mfma_f32_16x16x32_bf16 v[12:15], v[72:75], v[242:245], v[12:15]
	v_mfma_f32_16x16x32_bf16 v[56:59], v[80:83], v[218:221], v[56:59]
	v_mfma_f32_16x16x32_bf16 v[40:43], v[80:83], v[226:229], v[40:43]
	v_mfma_f32_16x16x32_bf16 v[24:27], v[80:83], v[234:237], v[24:27]
	v_mfma_f32_16x16x32_bf16 v[8:11], v[80:83], v[242:245], v[8:11]
	v_mfma_f32_16x16x32_bf16 v[52:55], v[174:177], v[214:217], v[52:55]
	v_mfma_f32_16x16x32_bf16 v[36:39], v[174:177], v[222:225], v[36:39]
	v_mfma_f32_16x16x32_bf16 v[20:23], v[174:177], v[230:233], v[20:23]
	v_mfma_f32_16x16x32_bf16 v[4:7], v[174:177], v[238:241], v[4:7]
	v_mfma_f32_16x16x32_bf16 v[48:51], v[186:189], v[214:217], v[48:51]
	v_mfma_f32_16x16x32_bf16 v[32:35], v[186:189], v[222:225], v[32:35]
	v_mfma_f32_16x16x32_bf16 v[16:19], v[186:189], v[230:233], v[16:19]
	v_mfma_f32_16x16x32_bf16 v[0:3], v[186:189], v[238:241], v[0:3]
	v_mfma_f32_16x16x32_bf16 v[52:55], v[182:185], v[218:221], v[52:55]
	v_mfma_f32_16x16x32_bf16 v[36:39], v[182:185], v[226:229], v[36:39]
	v_mfma_f32_16x16x32_bf16 v[20:23], v[182:185], v[234:237], v[20:23]
	v_mfma_f32_16x16x32_bf16 v[4:7], v[182:185], v[242:245], v[4:7]
	v_mfma_f32_16x16x32_bf16 v[48:51], v[210:213], v[218:221], v[48:51]
	v_mfma_f32_16x16x32_bf16 v[32:35], v[210:213], v[226:229], v[32:35]
	v_mfma_f32_16x16x32_bf16 v[16:19], v[210:213], v[234:237], v[16:19]
	v_mfma_f32_16x16x32_bf16 v[0:3], v[210:213], v[242:245], v[0:3]
	s_setprio 0
	s_barrier
	s_add_i32 s56, s56, 2
	s_add_u32 s0, s0, 0x100
	s_addc_u32 s1, s1, 0
	s_add_u32 s54, s54, 0x100
	s_addc_u32 s55, s55, 0
	s_cmp_gt_u32 s56, 13
	s_cbranch_scc0 .LBB0_327
	s_and_b64 vcc, exec, s[22:23]
	s_cbranch_vccz .LBB0_330
	s_barrier

; #define PG8_STAGE(bufoff, gbase, voff) do { _Pragma("unroll") for (int _i = 0; _i < 2; ++_i) \
;         __builtin_amdgcn_global_load_lds((const unsigned*)((const char*)(gbase) + (voff)[_i]), (PG8_LAS unsigned*)(lds + (bufoff) + ldsw + _i * 8192), 16, 0, 0); } while (0)
; #define PG8_LDA(dst, b, h) do { _Pragma("unroll") for (int m = 0; m < 4; ++m) _Pragma("unroll") for (int k = 0; k < 2; ++k) dst[m][k] = *(const PG8_LAS bf16x8*)(lds + PG8_SA(b, h) + aoff + m * 2048 + k * 1024); } while (0)
; #define PG8_LDB(dst, b, h) do { _Pragma("unroll") for (int n = 0; n < 2; ++n) _Pragma("unroll") for (int k = 0; k < 2; ++k) dst[n][k] = *(const PG8_LAS bf16x8*)(lds + PG8_SB(b, h) + boff + n * 2048 + k * 1024); } while (0)
; #define PG8_WAIT_V(n) asm volatile("s_waitcnt vmcnt(" #n ")" ::: "memory")
; #define PG8_WAIT_L(n) asm volatile("s_waitcnt lgkmcnt(" #n ")" ::: "memory")
; #define PG8_BAR __builtin_amdgcn_s_barrier()
; #define PG8_SCHED __builtin_amdgcn_sched_barrier(0)
; template <class Epi, class Sched, bool ALIGN_EPI = false, bool SP2 = false>
; __device__ __forceinline__ void gemm_phase(PG8_LAS unsigned char* lds, const Gemm g, const Sched& S, const Epi& E) {
;     ...
;         const bool has_next = S.next(ui + 1, nxt);
;         const char* nA = has_next ? (const char*)g.A + (size_t)nxt.pm * tstep : cA; const char* nB = has_next ? (const char*)g.Bt + (size_t)nxt.pn * tstep : cB;
;         for (int t = 0; t < nt; t += 2) {
;             const bool last = (t == nt - 2);
;             const char* a1 = cA + (size_t)(t + 1) * kstep;
;             const char* a2 = last ? nA : cA + (size_t)(t + 2) * kstep; const char* b2 = last ? nB : cB + (size_t)(t + 2) * kstep;
;             const char* a3 = a2 + kstep; const char* b3 = b2 + kstep;
;             if (last && has_next) S.a_ready(nxt);
;             if constexpr (SP2) {
;             PG8_LDB(B0, 0, 0); PG8_LDB(B1, 0, 1); PG8_SCHED; PG8_LDA(At, 0, 0); PG8_STAGE(PG8_SA(1, 1), a1 + hstep, voffA);
;             PG8_WAIT_V(8); PG8_WAIT_L(0); PG8_BAR; PG8_MMA(0, 0, At, B0); PG8_MMA(0, 1, At, B1); PG8_BAR; PG8_SCHED;
;             PG8_LDA(At, 0, 1); PG8_STAGE(PG8_SB(0, 0), b2, voffB); PG8_STAGE(PG8_SB(0, 1), b2 + hstep, voffB); PG8_STAGE(PG8_SA(0, 0), a2, voffA);
;             PG8_WAIT_V(8); PG8_WAIT_L(0); PG8_BAR; PG8_MMA(1, 0, At, B0); PG8_MMA(1, 1, At, B1); PG8_BAR; PG8_SCHED;
.Lup_peel:
	ds_read_b128 v[140:143], v254
	ds_read_b128 v[168:171], v254 offset:1024
	ds_read_b128 v[172:175], v254 offset:2048
	ds_read_b128 v[176:179], v254 offset:3072
	ds_read_b128 v[180:183], v254 offset:16384
	ds_read_b128 v[184:187], v254 offset:17408
	ds_read_b128 v[188:191], v254 offset:18432
	ds_read_b128 v[210:213], v254 offset:19456
	s_add_u32 s16, s14, 0xfffc0080
	s_addc_u32 s17, s15, -1
	s_cmp_eq_u32 s53, 12
	s_cselect_b32 s19, s7, s17
	s_cselect_b32 s18, s49, s16
	s_cselect_b32 s17, s5, s52
	s_cselect_b32 s16, s50, s51
	s_mov_b32 m0, s43
	ds_read_b128 v[214:217], v165
	ds_read_b128 v[218:221], v165 offset:1024
	ds_read_b128 v[222:225], v165 offset:2048
	ds_read_b128 v[226:229], v165 offset:3072
	ds_read_b128 v[230:233], v165 offset:4096
	ds_read_b128 v[234:237], v165 offset:5120
	ds_read_b128 v[238:241], v165 offset:6144
	ds_read_b128 v[242:245], v165 offset:7168
	global_load_lds_dwordx4 v136, s[14:15]
	s_mov_b32 m0, s44
	s_nop 0
	global_load_lds_dwordx4 v138, s[14:15]
	s_waitcnt vmcnt(8)
	s_waitcnt lgkmcnt(0)
	s_barrier
	s_setprio 1
	v_mfma_f32_16x16x32_bf16 v[124:127], v[140:143], v[214:217], 0
	v_mfma_f32_16x16x32_bf16 v[108:111], v[140:143], v[222:225], 0
	v_mfma_f32_16x16x32_bf16 v[92:95], v[140:143], v[230:233], 0
	v_mfma_f32_16x16x32_bf16 v[76:79], v[140:143], v[238:241], 0
	v_mfma_f32_16x16x32_bf16 v[116:119], v[172:175], v[214:217], 0
	v_mfma_f32_16x16x32_bf16 v[100:103], v[172:175], v[222:225], 0
	v_mfma_f32_16x16x32_bf16 v[84:87], v[172:175], v[230:233], 0
	v_mfma_f32_16x16x32_bf16 v[68:71], v[172:175], v[238:241], 0
	v_mfma_f32_16x16x32_bf16 v[124:127], v[168:171], v[218:221], v[124:127]
	v_mfma_f32_16x16x32_bf16 v[108:111], v[168:171], v[226:229], v[108:111]
	v_mfma_f32_16x16x32_bf16 v[92:95], v[168:171], v[234:237], v[92:95]
	v_mfma_f32_16x16x32_bf16 v[76:79], v[168:171], v[242:245], v[76:79]
	v_mfma_f32_16x16x32_bf16 v[116:119], v[176:179], v[218:221], v[116:119]
	v_mfma_f32_16x16x32_bf16 v[100:103], v[176:179], v[226:229], v[100:103]
	v_mfma_f32_16x16x32_bf16 v[84:87], v[176:179], v[234:237], v[84:87]
	v_mfma_f32_16x16x32_bf16 v[68:71], v[176:179], v[242:245], v[68:71]
	v_mfma_f32_16x16x32_bf16 v[120:123], v[180:183], v[214:217], 0
	v_mfma_f32_16x16x32_bf16 v[104:107], v[180:183], v[222:225], 0
	v_mfma_f32_16x16x32_bf16 v[88:91], v[180:183], v[230:233], 0
	v_mfma_f32_16x16x32_bf16 v[72:75], v[180:183], v[238:241], 0
	v_mfma_f32_16x16x32_bf16 v[112:115], v[188:191], v[214:217], 0
	v_mfma_f32_16x16x32_bf16 v[96:99], v[188:191], v[222:225], 0
	v_mfma_f32_16x16x32_bf16 v[80:83], v[188:191], v[230:233], 0
	v_mfma_f32_16x16x32_bf16 v[64:67], v[188:191], v[238:241], 0
	v_mfma_f32_16x16x32_bf16 v[120:123], v[184:187], v[218:221], v[120:123]
	v_mfma_f32_16x16x32_bf16 v[104:107], v[184:187], v[226:229], v[104:107]
	v_mfma_f32_16x16x32_bf16 v[88:91], v[184:187], v[234:237], v[88:91]
	v_mfma_f32_16x16x32_bf16 v[72:75], v[184:187], v[242:245], v[72:75]
	v_mfma_f32_16x16x32_bf16 v[112:115], v[210:213], v[218:221], v[112:115]
	v_mfma_f32_16x16x32_bf16 v[96:99], v[210:213], v[226:229], v[96:99]
	v_mfma_f32_16x16x32_bf16 v[80:83], v[210:213], v[234:237], v[80:83]
	v_mfma_f32_16x16x32_bf16 v[64:67], v[210:213], v[242:245], v[64:67]
	s_setprio 0
	s_barrier
	s_mov_b32 m0, s27
	s_add_u32 s54, s16, 0x40000
	s_addc_u32 s55, s17, 0
	ds_read_b128 v[214:217], v165 offset:16384
	ds_read_b128 v[218:221], v165 offset:17408
	ds_read_b128 v[222:225], v165 offset:18432
	ds_read_b128 v[226:229], v165 offset:19456
	ds_read_b128 v[230:233], v165 offset:20480
	ds_read_b128 v[234:237], v165 offset:21504
	ds_read_b128 v[238:241], v165 offset:22528
	ds_read_b128 v[242:245], v165 offset:23552
	global_load_lds_dwordx4 v132, s[16:17]
	s_mov_b32 m0, s28
	s_nop 0
	global_load_lds_dwordx4 v128, s[16:17]
	s_mov_b32 m0, s29
	s_nop 0
	global_load_lds_dwordx4 v132, s[54:55]
	s_mov_b32 m0, s30
	s_nop 0
	global_load_lds_dwordx4 v128, s[54:55]
	s_mov_b32 m0, s22
	s_nop 0
	global_load_lds_dwordx4 v134, s[18:19]
	s_mov_b32 m0, s31
	s_nop 0
	global_load_lds_dwordx4 v130, s[18:19]
	s_waitcnt vmcnt(8)
	s_waitcnt lgkmcnt(0)
	s_barrier
	s_setprio 1
	v_mfma_f32_16x16x32_bf16 v[60:63], v[140:143], v[214:217], 0
	v_mfma_f32_16x16x32_bf16 v[44:47], v[140:143], v[222:225], 0
	v_mfma_f32_16x16x32_bf16 v[28:31], v[140:143], v[230:233], 0
	v_mfma_f32_16x16x32_bf16 v[12:15], v[140:143], v[238:241], 0
	v_mfma_f32_16x16x32_bf16 v[52:55], v[172:175], v[214:217], 0
	v_mfma_f32_16x16x32_bf16 v[36:39], v[172:175], v[222:225], 0
	v_mfma_f32_16x16x32_bf16 v[20:23], v[172:175], v[230:233], 0
	v_mfma_f32_16x16x32_bf16 v[4:7], v[172:175], v[238:241], 0
	v_mfma_f32_16x16x32_bf16 v[60:63], v[168:171], v[218:221], v[60:63]
	v_mfma_f32_16x16x32_bf16 v[44:47], v[168:171], v[226:229], v[44:47]
	v_mfma_f32_16x16x32_bf16 v[28:31], v[168:171], v[234:237], v[28:31]
	v_mfma_f32_16x16x32_bf16 v[12:15], v[168:171], v[242:245], v[12:15]
	v_mfma_f32_16x16x32_bf16 v[52:55], v[176:179], v[218:221], v[52:55]
	v_mfma_f32_16x16x32_bf16 v[36:39], v[176:179], v[226:229], v[36:39]
	v_mfma_f32_16x16x32_bf16 v[20:23], v[176:179], v[234:237], v[20:23]
	v_mfma_f32_16x16x32_bf16 v[4:7], v[176:179], v[242:245], v[4:7]
	v_mfma_f32_16x16x32_bf16 v[56:59], v[180:183], v[214:217], 0
	v_mfma_f32_16x16x32_bf16 v[40:43], v[180:183], v[222:225], 0
	v_mfma_f32_16x16x32_bf16 v[24:27], v[180:183], v[230:233], 0
	v_mfma_f32_16x16x32_bf16 v[8:11], v[180:183], v[238:241], 0
	v_mfma_f32_16x16x32_bf16 v[48:51], v[188:191], v[214:217], 0
	v_mfma_f32_16x16x32_bf16 v[32:35], v[188:191], v[222:225], 0
	v_mfma_f32_16x16x32_bf16 v[16:19], v[188:191], v[230:233], 0
	v_mfma_f32_16x16x32_bf16 v[0:3], v[188:191], v[238:241], 0
	v_mfma_f32_16x16x32_bf16 v[56:59], v[184:187], v[218:221], v[56:59]
	v_mfma_f32_16x16x32_bf16 v[40:43], v[184:187], v[226:229], v[40:43]
	v_mfma_f32_16x16x32_bf16 v[24:27], v[184:187], v[234:237], v[24:27]
	v_mfma_f32_16x16x32_bf16 v[8:11], v[184:187], v[242:245], v[8:11]
	v_mfma_f32_16x16x32_bf16 v[48:51], v[210:213], v[218:221], v[48:51]
	v_mfma_f32_16x16x32_bf16 v[32:35], v[210:213], v[226:229], v[32:35]
	v_mfma_f32_16x16x32_bf16 v[16:19], v[210:213], v[234:237], v[16:19]
	v_mfma_f32_16x16x32_bf16 v[0:3], v[210:213], v[242:245], v[0:3]
	s_setprio 0
	s_barrier
; #define PG8_STAGE(bufoff, gbase, voff) do { _Pragma("unroll") for (int _i = 0; _i < 2; ++_i) \
;         __builtin_amdgcn_global_load_lds((const unsigned*)((const char*)(gbase) + (voff)[_i]), (PG8_LAS unsigned*)(lds + (bufoff) + ldsw + _i * 8192), 16, 0, 0); } while (0)
; #define PG8_LDA(dst, b, h) do { _Pragma("unroll") for (int m = 0; m < 4; ++m) _Pragma("unroll") for (int k = 0; k < 2; ++k) dst[m][k] = *(const PG8_LAS bf16x8*)(lds + PG8_SA(b, h) + aoff + m * 2048 + k * 1024); } while (0)
; #define PG8_LDB(dst, b, h) do { _Pragma("unroll") for (int n = 0; n < 2; ++n) _Pragma("unroll") for (int k = 0; k < 2; ++k) dst[n][k] = *(const PG8_LAS bf16x8*)(lds + PG8_SB(b, h) + boff + n * 2048 + k * 1024); } while (0)
; #define PG8_MMA(ai, bj, At, Bt) do { __builtin_amdgcn_s_setprio(1); _Pragma("unroll") for (int m = 0; m < 4; ++m) _Pragma("unroll") for (int n = 0; n < 2; ++n) _Pragma("unroll") for (int k = 0; k < 2; ++k) \
;         acc[ai][bj][m][n] = __builtin_amdgcn_mfma_f32_16x16x32_bf16(Bt[n][k], At[m][k], acc[ai][bj][m][n], 0, 0, 0); __builtin_amdgcn_s_setprio(0); } while (0)
; #define PG8_WAIT_V(n) asm volatile("s_waitcnt vmcnt(" #n ")" ::: "memory")
; #define PG8_WAIT_L(n) asm volatile("s_waitcnt lgkmcnt(" #n ")" ::: "memory")
; #define PG8_BAR __builtin_amdgcn_s_barrier()
; #define PG8_SCHED __builtin_amdgcn_sched_barrier(0)
; template <class Epi, class Sched, bool ALIGN_EPI = false, bool SP2 = false>
; __device__ __forceinline__ void gemm_phase(PG8_LAS unsigned char* lds, const Gemm g, const Sched& S, const Epi& E) {
;     ...
;             PG8_LDB(B0, 1, 0); PG8_LDB(B1, 1, 1); PG8_SCHED; PG8_LDA(At, 1, 0); PG8_STAGE(PG8_SA(0, 1), a2 + hstep, voffA);
;             PG8_WAIT_V(8); PG8_WAIT_L(0); PG8_BAR; PG8_MMA(0, 0, At, B0); PG8_MMA(0, 1, At, B1); PG8_BAR; PG8_SCHED;
;             PG8_LDA(At, 1, 1); PG8_STAGE(PG8_SB(1, 0), b3, voffB); PG8_STAGE(PG8_SB(1, 1), b3 + hstep, voffB); PG8_STAGE(PG8_SA(1, 0), a3, voffA);
;             PG8_WAIT_V(8); PG8_WAIT_L(0); PG8_BAR; PG8_MMA(1, 0, At, B0); PG8_MMA(1, 1, At, B1); PG8_BAR; PG8_SCHED;
	ds_read_b128 v[140:143], v254 offset:32768
	ds_read_b128 v[168:171], v254 offset:33792
	ds_read_b128 v[172:175], v254 offset:34816
	ds_read_b128 v[176:179], v254 offset:35840
	ds_read_b128 v[180:183], v254 offset:49152
	ds_read_b128 v[184:187], v254 offset:50176
	ds_read_b128 v[188:191], v254 offset:51200
	ds_read_b128 v[210:213], v254 offset:52224
	s_add_u32 s18, s18, 0x40000
	s_addc_u32 s19, s19, 0
	s_mov_b32 m0, s33
	ds_read_b128 v[214:217], v165 offset:32768
	ds_read_b128 v[218:221], v165 offset:33792
	ds_read_b128 v[222:225], v165 offset:34816
	ds_read_b128 v[226:229], v165 offset:35840
	ds_read_b128 v[230:233], v165 offset:36864
	ds_read_b128 v[234:237], v165 offset:37888
	ds_read_b128 v[238:241], v165 offset:38912
	ds_read_b128 v[242:245], v165 offset:39936
	global_load_lds_dwordx4 v134, s[18:19]
	s_mov_b32 m0, s34
	s_nop 0
	global_load_lds_dwordx4 v130, s[18:19]
	s_waitcnt vmcnt(8)
	s_waitcnt lgkmcnt(0)
	s_barrier
	s_setprio 1
	v_mfma_f32_16x16x32_bf16 v[124:127], v[140:143], v[214:217], v[124:127]
	v_mfma_f32_16x16x32_bf16 v[108:111], v[140:143], v[222:225], v[108:111]
	v_mfma_f32_16x16x32_bf16 v[92:95], v[140:143], v[230:233], v[92:95]
	v_mfma_f32_16x16x32_bf16 v[76:79], v[140:143], v[238:241], v[76:79]
	v_mfma_f32_16x16x32_bf16 v[116:119], v[172:175], v[214:217], v[116:119]
	v_mfma_f32_16x16x32_bf16 v[100:103], v[172:175], v[222:225], v[100:103]
	v_mfma_f32_16x16x32_bf16 v[84:87], v[172:175], v[230:233], v[84:87]
	v_mfma_f32_16x16x32_bf16 v[68:71], v[172:175], v[238:241], v[68:71]
	v_mfma_f32_16x16x32_bf16 v[124:127], v[168:171], v[218:221], v[124:127]
	v_mfma_f32_16x16x32_bf16 v[108:111], v[168:171], v[226:229], v[108:111]
	v_mfma_f32_16x16x32_bf16 v[92:95], v[168:171], v[234:237], v[92:95]
	v_mfma_f32_16x16x32_bf16 v[76:79], v[168:171], v[242:245], v[76:79]
	v_mfma_f32_16x16x32_bf16 v[116:119], v[176:179], v[218:221], v[116:119]
	v_mfma_f32_16x16x32_bf16 v[100:103], v[176:179], v[226:229], v[100:103]
	v_mfma_f32_16x16x32_bf16 v[84:87], v[176:179], v[234:237], v[84:87]
	v_mfma_f32_16x16x32_bf16 v[68:71], v[176:179], v[242:245], v[68:71]
	v_mfma_f32_16x16x32_bf16 v[120:123], v[180:183], v[214:217], v[120:123]
	v_mfma_f32_16x16x32_bf16 v[104:107], v[180:183], v[222:225], v[104:107]
	v_mfma_f32_16x16x32_bf16 v[88:91], v[180:183], v[230:233], v[88:91]
	v_mfma_f32_16x16x32_bf16 v[72:75], v[180:183], v[238:241], v[72:75]
	v_mfma_f32_16x16x32_bf16 v[112:115], v[188:191], v[214:217], v[112:115]
	v_mfma_f32_16x16x32_bf16 v[96:99], v[188:191], v[222:225], v[96:99]
	v_mfma_f32_16x16x32_bf16 v[80:83], v[188:191], v[230:233], v[80:83]
	v_mfma_f32_16x16x32_bf16 v[64:67], v[188:191], v[238:241], v[64:67]
	v_mfma_f32_16x16x32_bf16 v[120:123], v[184:187], v[218:221], v[120:123]
	v_mfma_f32_16x16x32_bf16 v[104:107], v[184:187], v[226:229], v[104:107]
	v_mfma_f32_16x16x32_bf16 v[88:91], v[184:187], v[234:237], v[88:91]
	v_mfma_f32_16x16x32_bf16 v[72:75], v[184:187], v[242:245], v[72:75]
	v_mfma_f32_16x16x32_bf16 v[112:115], v[210:213], v[218:221], v[112:115]
	v_mfma_f32_16x16x32_bf16 v[96:99], v[210:213], v[226:229], v[96:99]
	v_mfma_f32_16x16x32_bf16 v[80:83], v[210:213], v[234:237], v[80:83]
	v_mfma_f32_16x16x32_bf16 v[64:67], v[210:213], v[242:245], v[64:67]
	s_setprio 0
	s_barrier
	s_mov_b32 m0, s37
	s_add_u32 s16, s16, 0x40080
	s_addc_u32 s17, s17, 0
	ds_read_b128 v[214:217], v165 offset:49152
	ds_read_b128 v[218:221], v165 offset:50176
	ds_read_b128 v[222:225], v165 offset:51200
	ds_read_b128 v[226:229], v165 offset:52224
	ds_read_b128 v[230:233], v165 offset:53248
	ds_read_b128 v[234:237], v165 offset:54272
	ds_read_b128 v[238:241], v165 offset:55296
	ds_read_b128 v[242:245], v165 offset:56320
	s_add_u32 s98, s16, 0xfffc0000
	s_addc_u32 s99, s17, -1
	global_load_lds_dwordx4 v132, s[98:99]
	s_mov_b32 m0, s38
	s_nop 0
	global_load_lds_dwordx4 v128, s[98:99]
	s_mov_b32 m0, s41
	s_nop 0
	global_load_lds_dwordx4 v132, s[16:17]
	s_mov_b32 m0, s42
	s_nop 0
	global_load_lds_dwordx4 v128, s[16:17]
	s_mov_b32 m0, s39
	s_nop 0
	s_add_u32 s100, s18, 0xfffc0080
	s_addc_u32 s101, s19, -1
	global_load_lds_dwordx4 v134, s[100:101]
	s_mov_b32 m0, s40
	s_nop 0
	global_load_lds_dwordx4 v130, s[100:101]
	s_waitcnt vmcnt(8)
	s_waitcnt lgkmcnt(0)
	s_barrier
	s_setprio 1
	v_mfma_f32_16x16x32_bf16 v[60:63], v[140:143], v[214:217], v[60:63]
	v_mfma_f32_16x16x32_bf16 v[44:47], v[140:143], v[222:225], v[44:47]
	v_mfma_f32_16x16x32_bf16 v[28:31], v[140:143], v[230:233], v[28:31]
	v_mfma_f32_16x16x32_bf16 v[12:15], v[140:143], v[238:241], v[12:15]
	v_mfma_f32_16x16x32_bf16 v[52:55], v[172:175], v[214:217], v[52:55]
	v_mfma_f32_16x16x32_bf16 v[36:39], v[172:175], v[222:225], v[36:39]
	v_mfma_f32_16x16x32_bf16 v[20:23], v[172:175], v[230:233], v[20:23]
	v_mfma_f32_16x16x32_bf16 v[4:7], v[172:175], v[238:241], v[4:7]
	v_mfma_f32_16x16x32_bf16 v[60:63], v[168:171], v[218:221], v[60:63]
	v_mfma_f32_16x16x32_bf16 v[44:47], v[168:171], v[226:229], v[44:47]
	v_mfma_f32_16x16x32_bf16 v[28:31], v[168:171], v[234:237], v[28:31]
	v_mfma_f32_16x16x32_bf16 v[12:15], v[168:171], v[242:245], v[12:15]
	v_mfma_f32_16x16x32_bf16 v[52:55], v[176:179], v[218:221], v[52:55]
	v_mfma_f32_16x16x32_bf16 v[36:39], v[176:179], v[226:229], v[36:39]
	v_mfma_f32_16x16x32_bf16 v[20:23], v[176:179], v[234:237], v[20:23]
	v_mfma_f32_16x16x32_bf16 v[4:7], v[176:179], v[242:245], v[4:7]
	v_mfma_f32_16x16x32_bf16 v[56:59], v[180:183], v[214:217], v[56:59]
	v_mfma_f32_16x16x32_bf16 v[40:43], v[180:183], v[222:225], v[40:43]
	v_mfma_f32_16x16x32_bf16 v[24:27], v[180:183], v[230:233], v[24:27]
	v_mfma_f32_16x16x32_bf16 v[8:11], v[180:183], v[238:241], v[8:11]
	v_mfma_f32_16x16x32_bf16 v[48:51], v[188:191], v[214:217], v[48:51]
	v_mfma_f32_16x16x32_bf16 v[32:35], v[188:191], v[222:225], v[32:35]
	v_mfma_f32_16x16x32_bf16 v[16:19], v[188:191], v[230:233], v[16:19]
	v_mfma_f32_16x16x32_bf16 v[0:3], v[188:191], v[238:241], v[0:3]
	v_mfma_f32_16x16x32_bf16 v[56:59], v[184:187], v[218:221], v[56:59]
	v_mfma_f32_16x16x32_bf16 v[40:43], v[184:187], v[226:229], v[40:43]
	v_mfma_f32_16x16x32_bf16 v[24:27], v[184:187], v[234:237], v[24:27]
	v_mfma_f32_16x16x32_bf16 v[8:11], v[184:187], v[242:245], v[8:11]
	v_mfma_f32_16x16x32_bf16 v[48:51], v[210:213], v[218:221], v[48:51]
	v_mfma_f32_16x16x32_bf16 v[32:35], v[210:213], v[226:229], v[32:35]
	v_mfma_f32_16x16x32_bf16 v[16:19], v[210:213], v[234:237], v[16:19]
	v_mfma_f32_16x16x32_bf16 v[0:3], v[210:213], v[242:245], v[0:3]
	s_setprio 0
	s_barrier
	s_add_i32 s53, s53, 2
	s_add_u32 s14, s14, 0x100
	s_addc_u32 s15, s15, 0
	s_add_u32 s51, s51, 0x100
	s_addc_u32 s52, s52, 0
	s_cmp_gt_u32 s53, 13
; #define PG8_STAGE(bufoff, gbase, voff) do { _Pragma("unroll") for (int _i = 0; _i < 2; ++_i) \
;         __builtin_amdgcn_global_load_lds((const unsigned*)((const char*)(gbase) + (voff)[_i]), (PG8_LAS unsigned*)(lds + (bufoff) + ldsw + _i * 8192), 16, 0, 0); } while (0)
; #define PG8_LDA(dst, b, h) do { _Pragma("unroll") for (int m = 0; m < 4; ++m) _Pragma("unroll") for (int k = 0; k < 2; ++k) dst[m][k] = *(const PG8_LAS bf16x8*)(lds + PG8_SA(b, h) + aoff + m * 2048 + k * 1024); } while (0)
; #define PG8_LDB(dst, b, h) do { _Pragma("unroll") for (int n = 0; n < 2; ++n) _Pragma("unroll") for (int k = 0; k < 2; ++k) dst[n][k] = *(const PG8_LAS bf16x8*)(lds + PG8_SB(b, h) + boff + n * 2048 + k * 1024); } while (0)
; #define PG8_MMA(ai, bj, At, Bt) do { __builtin_amdgcn_s_setprio(1); _Pragma("unroll") for (int m = 0; m < 4; ++m) _Pragma("unroll") for (int n = 0; n < 2; ++n) _Pragma("unroll") for (int k = 0; k < 2; ++k) \
;         acc[ai][bj][m][n] = __builtin_amdgcn_mfma_f32_16x16x32_bf16(Bt[n][k], At[m][k], acc[ai][bj][m][n], 0, 0, 0); __builtin_amdgcn_s_setprio(0); } while (0)
; #define PG8_WAIT_V(n) asm volatile("s_waitcnt vmcnt(" #n ")" ::: "memory")
; #define PG8_WAIT_L(n) asm volatile("s_waitcnt lgkmcnt(" #n ")" ::: "memory")
; template <class Epi, class Sched, bool ALIGN_EPI = false, bool SP2 = false>
; __device__ __forceinline__ void gemm_phase(PG8_LAS unsigned char* lds, const Gemm g, const Sched& S, const Epi& E) {
;     ...
;             const bool last = (t == nt - 2);
;             const char* a1 = cA + (size_t)(t + 1) * kstep;
;             const char* a2 = last ? nA : cA + (size_t)(t + 2) * kstep; const char* b2 = last ? nB : cB + (size_t)(t + 2) * kstep;
;             const char* a3 = a2 + kstep; const char* b3 = b2 + kstep;
;             if (last && has_next) S.a_ready(nxt);
;             if constexpr (SP2) {
;             PG8_LDB(B0, 0, 0); PG8_LDB(B1, 0, 1); PG8_SCHED; PG8_LDA(At, 0, 0); PG8_STAGE(PG8_SA(1, 1), a1 + hstep, voffA);
;             PG8_WAIT_V(8); PG8_WAIT_L(0); PG8_BAR; PG8_MMA(0, 0, At, B0); PG8_MMA(0, 1, At, B1); PG8_BAR; PG8_SCHED;
;             PG8_LDA(At, 0, 1); PG8_STAGE(PG8_SB(0, 0), b2, voffB); PG8_STAGE(PG8_SB(0, 1), b2 + hstep, voffB); PG8_STAGE(PG8_SA(0, 0), a2, voffA);
;             PG8_WAIT_V(8); PG8_WAIT_L(0); PG8_BAR; PG8_MMA(1, 0, At, B0); PG8_MMA(1, 1, At, B1); PG8_BAR; PG8_SCHED;
.LBB0_446:
	ds_read_b128 v[140:143], v254
	ds_read_b128 v[168:171], v254 offset:1024
	ds_read_b128 v[172:175], v254 offset:2048
	ds_read_b128 v[176:179], v254 offset:3072
	ds_read_b128 v[180:183], v254 offset:16384
	ds_read_b128 v[184:187], v254 offset:17408
	ds_read_b128 v[188:191], v254 offset:18432
	ds_read_b128 v[210:213], v254 offset:19456
	s_add_u32 s16, s14, 0xfffc0080
	s_addc_u32 s17, s15, -1
	s_cmp_eq_u32 s53, 12
	s_cselect_b32 s19, s7, s17
	s_cselect_b32 s18, s49, s16
	s_cselect_b32 s17, s5, s52
	s_cselect_b32 s16, s50, s51
	s_mov_b32 m0, s43
	ds_read_b128 v[214:217], v165
	ds_read_b128 v[218:221], v165 offset:1024
	ds_read_b128 v[222:225], v165 offset:2048
	ds_read_b128 v[226:229], v165 offset:3072
	ds_read_b128 v[230:233], v165 offset:4096
	ds_read_b128 v[234:237], v165 offset:5120
	ds_read_b128 v[238:241], v165 offset:6144
	ds_read_b128 v[242:245], v165 offset:7168
	global_load_lds_dwordx4 v136, s[14:15]
	s_mov_b32 m0, s44
	s_nop 0
	global_load_lds_dwordx4 v138, s[14:15]
	s_waitcnt vmcnt(8)
	s_waitcnt lgkmcnt(0)
	s_barrier
	s_setprio 1
	v_mfma_f32_16x16x32_bf16 v[124:127], v[140:143], v[214:217], v[124:127]
	v_mfma_f32_16x16x32_bf16 v[108:111], v[140:143], v[222:225], v[108:111]
	v_mfma_f32_16x16x32_bf16 v[92:95], v[140:143], v[230:233], v[92:95]
	v_mfma_f32_16x16x32_bf16 v[76:79], v[140:143], v[238:241], v[76:79]
	v_mfma_f32_16x16x32_bf16 v[116:119], v[172:175], v[214:217], v[116:119]
	v_mfma_f32_16x16x32_bf16 v[100:103], v[172:175], v[222:225], v[100:103]
	v_mfma_f32_16x16x32_bf16 v[84:87], v[172:175], v[230:233], v[84:87]
	v_mfma_f32_16x16x32_bf16 v[68:71], v[172:175], v[238:241], v[68:71]
	v_mfma_f32_16x16x32_bf16 v[124:127], v[168:171], v[218:221], v[124:127]
	v_mfma_f32_16x16x32_bf16 v[108:111], v[168:171], v[226:229], v[108:111]
	v_mfma_f32_16x16x32_bf16 v[92:95], v[168:171], v[234:237], v[92:95]
	v_mfma_f32_16x16x32_bf16 v[76:79], v[168:171], v[242:245], v[76:79]
	v_mfma_f32_16x16x32_bf16 v[116:119], v[176:179], v[218:221], v[116:119]
	v_mfma_f32_16x16x32_bf16 v[100:103], v[176:179], v[226:229], v[100:103]
	v_mfma_f32_16x16x32_bf16 v[84:87], v[176:179], v[234:237], v[84:87]
	v_mfma_f32_16x16x32_bf16 v[68:71], v[176:179], v[242:245], v[68:71]
	v_mfma_f32_16x16x32_bf16 v[120:123], v[180:183], v[214:217], v[120:123]
	v_mfma_f32_16x16x32_bf16 v[104:107], v[180:183], v[222:225], v[104:107]
	v_mfma_f32_16x16x32_bf16 v[88:91], v[180:183], v[230:233], v[88:91]
	v_mfma_f32_16x16x32_bf16 v[72:75], v[180:183], v[238:241], v[72:75]
	v_mfma_f32_16x16x32_bf16 v[112:115], v[188:191], v[214:217], v[112:115]
	v_mfma_f32_16x16x32_bf16 v[96:99], v[188:191], v[222:225], v[96:99]
	v_mfma_f32_16x16x32_bf16 v[80:83], v[188:191], v[230:233], v[80:83]
	v_mfma_f32_16x16x32_bf16 v[64:67], v[188:191], v[238:241], v[64:67]
	v_mfma_f32_16x16x32_bf16 v[120:123], v[184:187], v[218:221], v[120:123]
	v_mfma_f32_16x16x32_bf16 v[104:107], v[184:187], v[226:229], v[104:107]
	v_mfma_f32_16x16x32_bf16 v[88:91], v[184:187], v[234:237], v[88:91]
	v_mfma_f32_16x16x32_bf16 v[72:75], v[184:187], v[242:245], v[72:75]
	v_mfma_f32_16x16x32_bf16 v[112:115], v[210:213], v[218:221], v[112:115]
	v_mfma_f32_16x16x32_bf16 v[96:99], v[210:213], v[226:229], v[96:99]
	v_mfma_f32_16x16x32_bf16 v[80:83], v[210:213], v[234:237], v[80:83]
	v_mfma_f32_16x16x32_bf16 v[64:67], v[210:213], v[242:245], v[64:67]
	s_setprio 0
	s_barrier
	s_mov_b32 m0, s27
	s_add_u32 s54, s16, 0x40000
	s_addc_u32 s55, s17, 0
	ds_read_b128 v[214:217], v165 offset:16384
	ds_read_b128 v[218:221], v165 offset:17408
	ds_read_b128 v[222:225], v165 offset:18432
	ds_read_b128 v[226:229], v165 offset:19456
	ds_read_b128 v[230:233], v165 offset:20480
	ds_read_b128 v[234:237], v165 offset:21504
	ds_read_b128 v[238:241], v165 offset:22528
	ds_read_b128 v[242:245], v165 offset:23552
	global_load_lds_dwordx4 v132, s[16:17]
	s_mov_b32 m0, s28
	s_nop 0
	global_load_lds_dwordx4 v128, s[16:17]
	s_mov_b32 m0, s29
	s_nop 0
	global_load_lds_dwordx4 v132, s[54:55]
	s_mov_b32 m0, s30
	s_nop 0
	global_load_lds_dwordx4 v128, s[54:55]
	s_mov_b32 m0, s22
	s_nop 0
	global_load_lds_dwordx4 v134, s[18:19]
	s_mov_b32 m0, s31
	s_nop 0
	global_load_lds_dwordx4 v130, s[18:19]
	s_waitcnt vmcnt(8)
	s_waitcnt lgkmcnt(0)
	s_barrier
	s_setprio 1
	v_mfma_f32_16x16x32_bf16 v[60:63], v[140:143], v[214:217], v[60:63]
	v_mfma_f32_16x16x32_bf16 v[44:47], v[140:143], v[222:225], v[44:47]
	v_mfma_f32_16x16x32_bf16 v[28:31], v[140:143], v[230:233], v[28:31]
	v_mfma_f32_16x16x32_bf16 v[12:15], v[140:143], v[238:241], v[12:15]
	v_mfma_f32_16x16x32_bf16 v[52:55], v[172:175], v[214:217], v[52:55]
	v_mfma_f32_16x16x32_bf16 v[36:39], v[172:175], v[222:225], v[36:39]
	v_mfma_f32_16x16x32_bf16 v[20:23], v[172:175], v[230:233], v[20:23]
	v_mfma_f32_16x16x32_bf16 v[4:7], v[172:175], v[238:241], v[4:7]
	v_mfma_f32_16x16x32_bf16 v[60:63], v[168:171], v[218:221], v[60:63]
	v_mfma_f32_16x16x32_bf16 v[44:47], v[168:171], v[226:229], v[44:47]
	v_mfma_f32_16x16x32_bf16 v[28:31], v[168:171], v[234:237], v[28:31]
	v_mfma_f32_16x16x32_bf16 v[12:15], v[168:171], v[242:245], v[12:15]
	v_mfma_f32_16x16x32_bf16 v[52:55], v[176:179], v[218:221], v[52:55]
	v_mfma_f32_16x16x32_bf16 v[36:39], v[176:179], v[226:229], v[36:39]
	v_mfma_f32_16x16x32_bf16 v[20:23], v[176:179], v[234:237], v[20:23]
	v_mfma_f32_16x16x32_bf16 v[4:7], v[176:179], v[242:245], v[4:7]
	v_mfma_f32_16x16x32_bf16 v[56:59], v[180:183], v[214:217], v[56:59]
	v_mfma_f32_16x16x32_bf16 v[40:43], v[180:183], v[222:225], v[40:43]
	v_mfma_f32_16x16x32_bf16 v[24:27], v[180:183], v[230:233], v[24:27]
	v_mfma_f32_16x16x32_bf16 v[8:11], v[180:183], v[238:241], v[8:11]
	v_mfma_f32_16x16x32_bf16 v[48:51], v[188:191], v[214:217], v[48:51]
	v_mfma_f32_16x16x32_bf16 v[32:35], v[188:191], v[222:225], v[32:35]
	v_mfma_f32_16x16x32_bf16 v[16:19], v[188:191], v[230:233], v[16:19]
	v_mfma_f32_16x16x32_bf16 v[0:3], v[188:191], v[238:241], v[0:3]
	v_mfma_f32_16x16x32_bf16 v[56:59], v[184:187], v[218:221], v[56:59]
	v_mfma_f32_16x16x32_bf16 v[40:43], v[184:187], v[226:229], v[40:43]
	v_mfma_f32_16x16x32_bf16 v[24:27], v[184:187], v[234:237], v[24:27]
	v_mfma_f32_16x16x32_bf16 v[8:11], v[184:187], v[242:245], v[8:11]
	v_mfma_f32_16x16x32_bf16 v[48:51], v[210:213], v[218:221], v[48:51]
	v_mfma_f32_16x16x32_bf16 v[32:35], v[210:213], v[226:229], v[32:35]
	v_mfma_f32_16x16x32_bf16 v[16:19], v[210:213], v[234:237], v[16:19]
	v_mfma_f32_16x16x32_bf16 v[0:3], v[210:213], v[242:245], v[0:3]
	s_setprio 0
	s_barrier
; #define PG8_STAGE(bufoff, gbase, voff) do { _Pragma("unroll") for (int _i = 0; _i < 2; ++_i) \
;         __builtin_amdgcn_global_load_lds((const unsigned*)((const char*)(gbase) + (voff)[_i]), (PG8_LAS unsigned*)(lds + (bufoff) + ldsw + _i * 8192), 16, 0, 0); } while (0)
; #define PG8_LDA(dst, b, h) do { _Pragma("unroll") for (int m = 0; m < 4; ++m) _Pragma("unroll") for (int k = 0; k < 2; ++k) dst[m][k] = *(const PG8_LAS bf16x8*)(lds + PG8_SA(b, h) + aoff + m * 2048 + k * 1024); } while (0)
; #define PG8_LDB(dst, b, h) do { _Pragma("unroll") for (int n = 0; n < 2; ++n) _Pragma("unroll") for (int k = 0; k < 2; ++k) dst[n][k] = *(const PG8_LAS bf16x8*)(lds + PG8_SB(b, h) + boff + n * 2048 + k * 1024); } while (0)
; #define PG8_MMA(ai, bj, At, Bt) do { __builtin_amdgcn_s_setprio(1); _Pragma("unroll") for (int m = 0; m < 4; ++m) _Pragma("unroll") for (int n = 0; n < 2; ++n) _Pragma("unroll") for (int k = 0; k < 2; ++k) \
;         acc[ai][bj][m][n] = __builtin_amdgcn_mfma_f32_16x16x32_bf16(Bt[n][k], At[m][k], acc[ai][bj][m][n], 0, 0, 0); __builtin_amdgcn_s_setprio(0); } while (0)
; #define PG8_WAIT_V(n) asm volatile("s_waitcnt vmcnt(" #n ")" ::: "memory")
; #define PG8_WAIT_L(n) asm volatile("s_waitcnt lgkmcnt(" #n ")" ::: "memory")
; #define PG8_BAR __builtin_amdgcn_s_barrier()
; #define PG8_SCHED __builtin_amdgcn_sched_barrier(0)
; template <class Epi, class Sched, bool ALIGN_EPI = false, bool SP2 = false>
; __device__ __forceinline__ void gemm_phase(PG8_LAS unsigned char* lds, const Gemm g, const Sched& S, const Epi& E) {
;     ...
;             PG8_LDB(B0, 1, 0); PG8_LDB(B1, 1, 1); PG8_SCHED; PG8_LDA(At, 1, 0); PG8_STAGE(PG8_SA(0, 1), a2 + hstep, voffA);
;             PG8_WAIT_V(8); PG8_WAIT_L(0); PG8_BAR; PG8_MMA(0, 0, At, B0); PG8_MMA(0, 1, At, B1); PG8_BAR; PG8_SCHED;
;             PG8_LDA(At, 1, 1); PG8_STAGE(PG8_SB(1, 0), b3, voffB); PG8_STAGE(PG8_SB(1, 1), b3 + hstep, voffB); PG8_STAGE(PG8_SA(1, 0), a3, voffA);
;             PG8_WAIT_V(8); PG8_WAIT_L(0); PG8_BAR; PG8_MMA(1, 0, At, B0); PG8_MMA(1, 1, At, B1); PG8_BAR; PG8_SCHED;
;     ...
;         if constexpr (ALIGN_EPI) { if (wr == 0) PG8_BAR; }
	ds_read_b128 v[140:143], v254 offset:32768
	ds_read_b128 v[168:171], v254 offset:33792
	ds_read_b128 v[172:175], v254 offset:34816
	ds_read_b128 v[176:179], v254 offset:35840
	ds_read_b128 v[180:183], v254 offset:49152
	ds_read_b128 v[184:187], v254 offset:50176
	ds_read_b128 v[188:191], v254 offset:51200
	ds_read_b128 v[210:213], v254 offset:52224
	s_add_u32 s18, s18, 0x40000
	s_addc_u32 s19, s19, 0
	s_mov_b32 m0, s33
	ds_read_b128 v[214:217], v165 offset:32768
	ds_read_b128 v[218:221], v165 offset:33792
	ds_read_b128 v[222:225], v165 offset:34816
	ds_read_b128 v[226:229], v165 offset:35840
	ds_read_b128 v[230:233], v165 offset:36864
	ds_read_b128 v[234:237], v165 offset:37888
	ds_read_b128 v[238:241], v165 offset:38912
	ds_read_b128 v[242:245], v165 offset:39936
	global_load_lds_dwordx4 v134, s[18:19]
	s_mov_b32 m0, s34
	s_nop 0
	global_load_lds_dwordx4 v130, s[18:19]
	s_waitcnt vmcnt(8)
	s_waitcnt lgkmcnt(0)
	s_barrier
	s_setprio 1
	v_mfma_f32_16x16x32_bf16 v[124:127], v[140:143], v[214:217], v[124:127]
	v_mfma_f32_16x16x32_bf16 v[108:111], v[140:143], v[222:225], v[108:111]
	v_mfma_f32_16x16x32_bf16 v[92:95], v[140:143], v[230:233], v[92:95]
	v_mfma_f32_16x16x32_bf16 v[76:79], v[140:143], v[238:241], v[76:79]
	v_mfma_f32_16x16x32_bf16 v[116:119], v[172:175], v[214:217], v[116:119]
	v_mfma_f32_16x16x32_bf16 v[100:103], v[172:175], v[222:225], v[100:103]
	v_mfma_f32_16x16x32_bf16 v[84:87], v[172:175], v[230:233], v[84:87]
	v_mfma_f32_16x16x32_bf16 v[68:71], v[172:175], v[238:241], v[68:71]
	v_mfma_f32_16x16x32_bf16 v[124:127], v[168:171], v[218:221], v[124:127]
	v_mfma_f32_16x16x32_bf16 v[108:111], v[168:171], v[226:229], v[108:111]
	v_mfma_f32_16x16x32_bf16 v[92:95], v[168:171], v[234:237], v[92:95]
	v_mfma_f32_16x16x32_bf16 v[76:79], v[168:171], v[242:245], v[76:79]
	v_mfma_f32_16x16x32_bf16 v[116:119], v[176:179], v[218:221], v[116:119]
	v_mfma_f32_16x16x32_bf16 v[100:103], v[176:179], v[226:229], v[100:103]
	v_mfma_f32_16x16x32_bf16 v[84:87], v[176:179], v[234:237], v[84:87]
	v_mfma_f32_16x16x32_bf16 v[68:71], v[176:179], v[242:245], v[68:71]
	v_mfma_f32_16x16x32_bf16 v[120:123], v[180:183], v[214:217], v[120:123]
	v_mfma_f32_16x16x32_bf16 v[104:107], v[180:183], v[222:225], v[104:107]
	v_mfma_f32_16x16x32_bf16 v[88:91], v[180:183], v[230:233], v[88:91]
	v_mfma_f32_16x16x32_bf16 v[72:75], v[180:183], v[238:241], v[72:75]
	v_mfma_f32_16x16x32_bf16 v[112:115], v[188:191], v[214:217], v[112:115]
	v_mfma_f32_16x16x32_bf16 v[96:99], v[188:191], v[222:225], v[96:99]
	v_mfma_f32_16x16x32_bf16 v[80:83], v[188:191], v[230:233], v[80:83]
	v_mfma_f32_16x16x32_bf16 v[64:67], v[188:191], v[238:241], v[64:67]
	v_mfma_f32_16x16x32_bf16 v[120:123], v[184:187], v[218:221], v[120:123]
	v_mfma_f32_16x16x32_bf16 v[104:107], v[184:187], v[226:229], v[104:107]
	v_mfma_f32_16x16x32_bf16 v[88:91], v[184:187], v[234:237], v[88:91]
	v_mfma_f32_16x16x32_bf16 v[72:75], v[184:187], v[242:245], v[72:75]
	v_mfma_f32_16x16x32_bf16 v[112:115], v[210:213], v[218:221], v[112:115]
	v_mfma_f32_16x16x32_bf16 v[96:99], v[210:213], v[226:229], v[96:99]
	v_mfma_f32_16x16x32_bf16 v[80:83], v[210:213], v[234:237], v[80:83]
	v_mfma_f32_16x16x32_bf16 v[64:67], v[210:213], v[242:245], v[64:67]
	s_setprio 0
	s_barrier
	s_mov_b32 m0, s37
	s_add_u32 s16, s16, 0x40080
	s_addc_u32 s17, s17, 0
	ds_read_b128 v[214:217], v165 offset:49152
	ds_read_b128 v[218:221], v165 offset:50176
	ds_read_b128 v[222:225], v165 offset:51200
	ds_read_b128 v[226:229], v165 offset:52224
	ds_read_b128 v[230:233], v165 offset:53248
	ds_read_b128 v[234:237], v165 offset:54272
	ds_read_b128 v[238:241], v165 offset:55296
	ds_read_b128 v[242:245], v165 offset:56320
	s_add_u32 s98, s16, 0xfffc0000
	s_addc_u32 s99, s17, -1
	global_load_lds_dwordx4 v132, s[98:99]
	s_mov_b32 m0, s38
	s_nop 0
	global_load_lds_dwordx4 v128, s[98:99]
	s_mov_b32 m0, s41
	s_nop 0
	global_load_lds_dwordx4 v132, s[16:17]
	s_mov_b32 m0, s42
	s_nop 0
	global_load_lds_dwordx4 v128, s[16:17]
	s_mov_b32 m0, s39
	s_nop 0
	s_add_u32 s100, s18, 0xfffc0080
	s_addc_u32 s101, s19, -1
	global_load_lds_dwordx4 v134, s[100:101]
	s_mov_b32 m0, s40
	s_nop 0
	global_load_lds_dwordx4 v130, s[100:101]
	s_waitcnt vmcnt(8)
	s_waitcnt lgkmcnt(0)
	s_barrier
	s_setprio 1
	v_mfma_f32_16x16x32_bf16 v[60:63], v[140:143], v[214:217], v[60:63]
	v_mfma_f32_16x16x32_bf16 v[44:47], v[140:143], v[222:225], v[44:47]
	v_mfma_f32_16x16x32_bf16 v[28:31], v[140:143], v[230:233], v[28:31]
	v_mfma_f32_16x16x32_bf16 v[12:15], v[140:143], v[238:241], v[12:15]
	v_mfma_f32_16x16x32_bf16 v[52:55], v[172:175], v[214:217], v[52:55]
	v_mfma_f32_16x16x32_bf16 v[36:39], v[172:175], v[222:225], v[36:39]
	v_mfma_f32_16x16x32_bf16 v[20:23], v[172:175], v[230:233], v[20:23]
	v_mfma_f32_16x16x32_bf16 v[4:7], v[172:175], v[238:241], v[4:7]
	v_mfma_f32_16x16x32_bf16 v[60:63], v[168:171], v[218:221], v[60:63]
	v_mfma_f32_16x16x32_bf16 v[44:47], v[168:171], v[226:229], v[44:47]
	v_mfma_f32_16x16x32_bf16 v[28:31], v[168:171], v[234:237], v[28:31]
	v_mfma_f32_16x16x32_bf16 v[12:15], v[168:171], v[242:245], v[12:15]
	v_mfma_f32_16x16x32_bf16 v[52:55], v[176:179], v[218:221], v[52:55]
	v_mfma_f32_16x16x32_bf16 v[36:39], v[176:179], v[226:229], v[36:39]
	v_mfma_f32_16x16x32_bf16 v[20:23], v[176:179], v[234:237], v[20:23]
	v_mfma_f32_16x16x32_bf16 v[4:7], v[176:179], v[242:245], v[4:7]
	v_mfma_f32_16x16x32_bf16 v[56:59], v[180:183], v[214:217], v[56:59]
	v_mfma_f32_16x16x32_bf16 v[40:43], v[180:183], v[222:225], v[40:43]
	v_mfma_f32_16x16x32_bf16 v[24:27], v[180:183], v[230:233], v[24:27]
	v_mfma_f32_16x16x32_bf16 v[8:11], v[180:183], v[238:241], v[8:11]
	v_mfma_f32_16x16x32_bf16 v[48:51], v[188:191], v[214:217], v[48:51]
	v_mfma_f32_16x16x32_bf16 v[32:35], v[188:191], v[222:225], v[32:35]
	v_mfma_f32_16x16x32_bf16 v[16:19], v[188:191], v[230:233], v[16:19]
	v_mfma_f32_16x16x32_bf16 v[0:3], v[188:191], v[238:241], v[0:3]
	v_mfma_f32_16x16x32_bf16 v[56:59], v[184:187], v[218:221], v[56:59]
	v_mfma_f32_16x16x32_bf16 v[40:43], v[184:187], v[226:229], v[40:43]
	v_mfma_f32_16x16x32_bf16 v[24:27], v[184:187], v[234:237], v[24:27]
	v_mfma_f32_16x16x32_bf16 v[8:11], v[184:187], v[242:245], v[8:11]
	v_mfma_f32_16x16x32_bf16 v[48:51], v[210:213], v[218:221], v[48:51]
	v_mfma_f32_16x16x32_bf16 v[32:35], v[210:213], v[226:229], v[32:35]
	v_mfma_f32_16x16x32_bf16 v[16:19], v[210:213], v[234:237], v[16:19]
	v_mfma_f32_16x16x32_bf16 v[0:3], v[210:213], v[242:245], v[0:3]
	s_setprio 0
	s_barrier
	s_add_i32 s53, s53, 2
	s_add_u32 s14, s14, 0x100
	s_addc_u32 s15, s15, 0
	s_add_u32 s51, s51, 0x100
	s_addc_u32 s52, s52, 0
	s_cmp_gt_u32 s53, 13
	s_cbranch_scc0 .LBB0_446
	s_and_b64 vcc, exec, s[2:3]
	s_cbranch_vccz .LBB0_449
	s_barrier

; #define PG8_STAGE(bufoff, gbase, voff) do { _Pragma("unroll") for (int _i = 0; _i < 2; ++_i) \
;         __builtin_amdgcn_global_load_lds((const unsigned*)((const char*)(gbase) + (voff)[_i]), (PG8_LAS unsigned*)(lds + (bufoff) + ldsw + _i * 8192), 16, 0, 0); } while (0)
; #define PG8_LDA(dst, b, h) do { _Pragma("unroll") for (int m = 0; m < 4; ++m) _Pragma("unroll") for (int k = 0; k < 2; ++k) dst[m][k] = *(const PG8_LAS bf16x8*)(lds + PG8_SA(b, h) + aoff + m * 2048 + k * 1024); } while (0)
; #define PG8_LDB(dst, b, h) do { _Pragma("unroll") for (int n = 0; n < 2; ++n) _Pragma("unroll") for (int k = 0; k < 2; ++k) dst[n][k] = *(const PG8_LAS bf16x8*)(lds + PG8_SB(b, h) + boff + n * 2048 + k * 1024); } while (0)
; #define PG8_MMA(ai, bj, At, Bt) do { __builtin_amdgcn_s_setprio(1); _Pragma("unroll") for (int m = 0; m < 4; ++m) _Pragma("unroll") for (int n = 0; n < 2; ++n) _Pragma("unroll") for (int k = 0; k < 2; ++k) \
;         acc[ai][bj][m][n] = __builtin_amdgcn_mfma_f32_16x16x32_bf16(Bt[n][k], At[m][k], acc[ai][bj][m][n], 0, 0, 0); __builtin_amdgcn_s_setprio(0); } while (0)
; #define PG8_WAIT_V(n) asm volatile("s_waitcnt vmcnt(" #n ")" ::: "memory")
; #define PG8_WAIT_L(n) asm volatile("s_waitcnt lgkmcnt(" #n ")" ::: "memory")
; template <class Epi, class Sched, bool ALIGN_EPI = false, bool SP2 = false>
; __device__ __forceinline__ void gemm_phase(PG8_LAS unsigned char* lds, const Gemm g, const Sched& S, const Epi& E) {
;     ...
;             const bool last = (t == nt - 2);
;             const char* a1 = cA + (size_t)(t + 1) * kstep;
;             const char* a2 = last ? nA : cA + (size_t)(t + 2) * kstep; const char* b2 = last ? nB : cB + (size_t)(t + 2) * kstep;
;             const char* a3 = a2 + kstep; const char* b3 = b2 + kstep;
;             if (last && has_next) S.a_ready(nxt);
;             if constexpr (SP2) {
;             PG8_LDB(B0, 0, 0); PG8_LDB(B1, 0, 1); PG8_SCHED; PG8_LDA(At, 0, 0); PG8_STAGE(PG8_SA(1, 1), a1 + hstep, voffA);
;             PG8_WAIT_V(8); PG8_WAIT_L(0); PG8_BAR; PG8_MMA(0, 0, At, B0); PG8_MMA(0, 1, At, B1); PG8_BAR; PG8_SCHED;
;             PG8_LDA(At, 0, 1); PG8_STAGE(PG8_SB(0, 0), b2, voffB); PG8_STAGE(PG8_SB(0, 1), b2 + hstep, voffB); PG8_STAGE(PG8_SA(0, 0), a2, voffA);
;             PG8_WAIT_V(8); PG8_WAIT_L(0); PG8_BAR; PG8_MMA(1, 0, At, B0); PG8_MMA(1, 1, At, B1); PG8_BAR; PG8_SCHED;
.Ldn_peel:
	ds_read_b128 v[128:131], v254
	ds_read_b128 v[132:135], v254 offset:1024
	ds_read_b128 v[136:139], v254 offset:2048
	ds_read_b128 v[140:143], v254 offset:3072
	ds_read_b128 v[174:177], v254 offset:16384
	ds_read_b128 v[184:187], v254 offset:17408
	ds_read_b128 v[188:191], v254 offset:18432
	ds_read_b128 v[210:213], v254 offset:19456
	s_add_u32 s2, s0, 0x100
	s_addc_u32 s3, s1, 0
	s_cmp_eq_u32 s13, 40
	s_cselect_b32 s7, s27, s3
	s_cselect_b32 s6, s26, s2
	s_cselect_b32 s5, s37, s11
	s_cselect_b32 s4, s36, s10
	s_add_i32 m0, s29, 0xc000
	ds_read_b128 v[214:217], v181
	ds_read_b128 v[218:221], v181 offset:1024
	ds_read_b128 v[222:225], v181 offset:2048
	ds_read_b128 v[226:229], v181 offset:3072
	ds_read_b128 v[230:233], v181 offset:4096
	ds_read_b128 v[234:237], v181 offset:5120
	ds_read_b128 v[238:241], v181 offset:6144
	ds_read_b128 v[242:245], v181 offset:7168
	global_load_lds_dwordx4 v170, s[0:1]
	s_add_i32 m0, s29, 0xe000
	s_nop 0
	global_load_lds_dwordx4 v172, s[0:1]
	s_waitcnt vmcnt(8)
	s_waitcnt lgkmcnt(0)
	s_barrier
	s_setprio 1
	v_mfma_f32_16x16x32_bf16 v[124:127], v[128:131], v[214:217], 0
	v_mfma_f32_16x16x32_bf16 v[108:111], v[128:131], v[222:225], 0
	v_mfma_f32_16x16x32_bf16 v[92:95], v[128:131], v[230:233], 0
	v_mfma_f32_16x16x32_bf16 v[76:79], v[128:131], v[238:241], 0
	v_mfma_f32_16x16x32_bf16 v[120:123], v[136:139], v[214:217], 0
	v_mfma_f32_16x16x32_bf16 v[104:107], v[136:139], v[222:225], 0
	v_mfma_f32_16x16x32_bf16 v[88:91], v[136:139], v[230:233], 0
	v_mfma_f32_16x16x32_bf16 v[72:75], v[136:139], v[238:241], 0
	v_mfma_f32_16x16x32_bf16 v[124:127], v[132:135], v[218:221], v[124:127]
	v_mfma_f32_16x16x32_bf16 v[108:111], v[132:135], v[226:229], v[108:111]
	v_mfma_f32_16x16x32_bf16 v[92:95], v[132:135], v[234:237], v[92:95]
	v_mfma_f32_16x16x32_bf16 v[76:79], v[132:135], v[242:245], v[76:79]
	v_mfma_f32_16x16x32_bf16 v[120:123], v[140:143], v[218:221], v[120:123]
	v_mfma_f32_16x16x32_bf16 v[104:107], v[140:143], v[226:229], v[104:107]
	v_mfma_f32_16x16x32_bf16 v[88:91], v[140:143], v[234:237], v[88:91]
	v_mfma_f32_16x16x32_bf16 v[72:75], v[140:143], v[242:245], v[72:75]
	v_mfma_f32_16x16x32_bf16 v[116:119], v[174:177], v[214:217], 0
	v_mfma_f32_16x16x32_bf16 v[100:103], v[174:177], v[222:225], 0
	v_mfma_f32_16x16x32_bf16 v[84:87], v[174:177], v[230:233], 0
	v_mfma_f32_16x16x32_bf16 v[68:71], v[174:177], v[238:241], 0
	v_mfma_f32_16x16x32_bf16 v[112:115], v[188:191], v[214:217], 0
	v_mfma_f32_16x16x32_bf16 v[96:99], v[188:191], v[222:225], 0
	v_mfma_f32_16x16x32_bf16 v[80:83], v[188:191], v[230:233], 0
	v_mfma_f32_16x16x32_bf16 v[64:67], v[188:191], v[238:241], 0
	v_mfma_f32_16x16x32_bf16 v[116:119], v[184:187], v[218:221], v[116:119]
	v_mfma_f32_16x16x32_bf16 v[100:103], v[184:187], v[226:229], v[100:103]
	v_mfma_f32_16x16x32_bf16 v[84:87], v[184:187], v[234:237], v[84:87]
	v_mfma_f32_16x16x32_bf16 v[68:71], v[184:187], v[242:245], v[68:71]
	v_mfma_f32_16x16x32_bf16 v[112:115], v[210:213], v[218:221], v[112:115]
	v_mfma_f32_16x16x32_bf16 v[96:99], v[210:213], v[226:229], v[96:99]
	v_mfma_f32_16x16x32_bf16 v[80:83], v[210:213], v[234:237], v[80:83]
	v_mfma_f32_16x16x32_bf16 v[64:67], v[210:213], v[242:245], v[64:67]
	s_setprio 0
	s_barrier
	s_mov_b32 m0, s35
	s_add_u32 s0, s4, 0xb0000
	s_addc_u32 s1, s5, 0
	ds_read_b128 v[214:217], v181 offset:16384
	ds_read_b128 v[218:221], v181 offset:17408
	ds_read_b128 v[222:225], v181 offset:18432
	ds_read_b128 v[226:229], v181 offset:19456
	ds_read_b128 v[230:233], v181 offset:20480
	ds_read_b128 v[234:237], v181 offset:21504
	ds_read_b128 v[238:241], v181 offset:22528
	ds_read_b128 v[242:245], v181 offset:23552
	global_load_lds_dwordx4 v166, s[4:5]
	s_mov_b32 m0, s38
	s_nop 0
	global_load_lds_dwordx4 v162, s[4:5]
	s_mov_b32 m0, s39
	s_nop 0
	global_load_lds_dwordx4 v166, s[0:1]
	s_mov_b32 m0, s40
	s_nop 0
	global_load_lds_dwordx4 v162, s[0:1]
	s_mov_b32 m0, s29
	s_nop 0
	global_load_lds_dwordx4 v168, s[6:7]
	s_mov_b32 m0, s41
	s_nop 0
	global_load_lds_dwordx4 v164, s[6:7]
	s_waitcnt vmcnt(8)
	s_waitcnt lgkmcnt(0)
	s_barrier
	s_setprio 1
	v_mfma_f32_16x16x32_bf16 v[60:63], v[128:131], v[214:217], 0
	v_mfma_f32_16x16x32_bf16 v[44:47], v[128:131], v[222:225], 0
	v_mfma_f32_16x16x32_bf16 v[28:31], v[128:131], v[230:233], 0
	v_mfma_f32_16x16x32_bf16 v[12:15], v[128:131], v[238:241], 0
	v_mfma_f32_16x16x32_bf16 v[56:59], v[136:139], v[214:217], 0
	v_mfma_f32_16x16x32_bf16 v[40:43], v[136:139], v[222:225], 0
	v_mfma_f32_16x16x32_bf16 v[24:27], v[136:139], v[230:233], 0
	v_mfma_f32_16x16x32_bf16 v[8:11], v[136:139], v[238:241], 0
	v_mfma_f32_16x16x32_bf16 v[60:63], v[132:135], v[218:221], v[60:63]
	v_mfma_f32_16x16x32_bf16 v[44:47], v[132:135], v[226:229], v[44:47]
	v_mfma_f32_16x16x32_bf16 v[28:31], v[132:135], v[234:237], v[28:31]
	v_mfma_f32_16x16x32_bf16 v[12:15], v[132:135], v[242:245], v[12:15]
	v_mfma_f32_16x16x32_bf16 v[56:59], v[140:143], v[218:221], v[56:59]
	v_mfma_f32_16x16x32_bf16 v[40:43], v[140:143], v[226:229], v[40:43]
	v_mfma_f32_16x16x32_bf16 v[24:27], v[140:143], v[234:237], v[24:27]
	v_mfma_f32_16x16x32_bf16 v[8:11], v[140:143], v[242:245], v[8:11]
	v_mfma_f32_16x16x32_bf16 v[52:55], v[174:177], v[214:217], 0
	v_mfma_f32_16x16x32_bf16 v[36:39], v[174:177], v[222:225], 0
	v_mfma_f32_16x16x32_bf16 v[20:23], v[174:177], v[230:233], 0
	v_mfma_f32_16x16x32_bf16 v[4:7], v[174:177], v[238:241], 0
	v_mfma_f32_16x16x32_bf16 v[48:51], v[188:191], v[214:217], 0
	v_mfma_f32_16x16x32_bf16 v[32:35], v[188:191], v[222:225], 0
	v_mfma_f32_16x16x32_bf16 v[16:19], v[188:191], v[230:233], 0
	v_mfma_f32_16x16x32_bf16 v[0:3], v[188:191], v[238:241], 0
	v_mfma_f32_16x16x32_bf16 v[52:55], v[184:187], v[218:221], v[52:55]
	v_mfma_f32_16x16x32_bf16 v[36:39], v[184:187], v[226:229], v[36:39]
	v_mfma_f32_16x16x32_bf16 v[20:23], v[184:187], v[234:237], v[20:23]
	v_mfma_f32_16x16x32_bf16 v[4:7], v[184:187], v[242:245], v[4:7]
	v_mfma_f32_16x16x32_bf16 v[48:51], v[210:213], v[218:221], v[48:51]
	v_mfma_f32_16x16x32_bf16 v[32:35], v[210:213], v[226:229], v[32:35]
	v_mfma_f32_16x16x32_bf16 v[16:19], v[210:213], v[234:237], v[16:19]
	v_mfma_f32_16x16x32_bf16 v[0:3], v[210:213], v[242:245], v[0:3]
	s_setprio 0
	s_barrier
; #define PG8_STAGE(bufoff, gbase, voff) do { _Pragma("unroll") for (int _i = 0; _i < 2; ++_i) \
;         __builtin_amdgcn_global_load_lds((const unsigned*)((const char*)(gbase) + (voff)[_i]), (PG8_LAS unsigned*)(lds + (bufoff) + ldsw + _i * 8192), 16, 0, 0); } while (0)
; #define PG8_LDA(dst, b, h) do { _Pragma("unroll") for (int m = 0; m < 4; ++m) _Pragma("unroll") for (int k = 0; k < 2; ++k) dst[m][k] = *(const PG8_LAS bf16x8*)(lds + PG8_SA(b, h) + aoff + m * 2048 + k * 1024); } while (0)
; #define PG8_LDB(dst, b, h) do { _Pragma("unroll") for (int n = 0; n < 2; ++n) _Pragma("unroll") for (int k = 0; k < 2; ++k) dst[n][k] = *(const PG8_LAS bf16x8*)(lds + PG8_SB(b, h) + boff + n * 2048 + k * 1024); } while (0)
; #define PG8_MMA(ai, bj, At, Bt) do { __builtin_amdgcn_s_setprio(1); _Pragma("unroll") for (int m = 0; m < 4; ++m) _Pragma("unroll") for (int n = 0; n < 2; ++n) _Pragma("unroll") for (int k = 0; k < 2; ++k) \
;         acc[ai][bj][m][n] = __builtin_amdgcn_mfma_f32_16x16x32_bf16(Bt[n][k], At[m][k], acc[ai][bj][m][n], 0, 0, 0); __builtin_amdgcn_s_setprio(0); } while (0)
; #define PG8_WAIT_V(n) asm volatile("s_waitcnt vmcnt(" #n ")" ::: "memory")
; #define PG8_WAIT_L(n) asm volatile("s_waitcnt lgkmcnt(" #n ")" ::: "memory")
; #define PG8_BAR __builtin_amdgcn_s_barrier()
; #define PG8_SCHED __builtin_amdgcn_sched_barrier(0)
; template <class Epi, class Sched, bool ALIGN_EPI = false, bool SP2 = false>
; __device__ __forceinline__ void gemm_phase(PG8_LAS unsigned char* lds, const Gemm g, const Sched& S, const Epi& E) {
;     ...
;             PG8_LDB(B0, 1, 0); PG8_LDB(B1, 1, 1); PG8_SCHED; PG8_LDA(At, 1, 0); PG8_STAGE(PG8_SA(0, 1), a2 + hstep, voffA);
;             PG8_WAIT_V(8); PG8_WAIT_L(0); PG8_BAR; PG8_MMA(0, 0, At, B0); PG8_MMA(0, 1, At, B1); PG8_BAR; PG8_SCHED;
;             PG8_LDA(At, 1, 1); PG8_STAGE(PG8_SB(1, 0), b3, voffB); PG8_STAGE(PG8_SB(1, 1), b3 + hstep, voffB); PG8_STAGE(PG8_SA(1, 0), a3, voffA);
;             PG8_WAIT_V(8); PG8_WAIT_L(0); PG8_BAR; PG8_MMA(1, 0, At, B0); PG8_MMA(1, 1, At, B1); PG8_BAR; PG8_SCHED;
	ds_read_b128 v[128:131], v254 offset:32768
	ds_read_b128 v[132:135], v254 offset:33792
	ds_read_b128 v[136:139], v254 offset:34816
	ds_read_b128 v[140:143], v254 offset:35840
	ds_read_b128 v[174:177], v254 offset:49152
	ds_read_b128 v[184:187], v254 offset:50176
	ds_read_b128 v[188:191], v254 offset:51200
	ds_read_b128 v[210:213], v254 offset:52224
	s_add_u32 s0, s6, 0xb0000
	s_addc_u32 s1, s7, 0
	s_mov_b32 m0, s42
	ds_read_b128 v[214:217], v181 offset:32768
	ds_read_b128 v[218:221], v181 offset:33792
	ds_read_b128 v[222:225], v181 offset:34816
	ds_read_b128 v[226:229], v181 offset:35840
	ds_read_b128 v[230:233], v181 offset:36864
	ds_read_b128 v[234:237], v181 offset:37888
	ds_read_b128 v[238:241], v181 offset:38912
	ds_read_b128 v[242:245], v181 offset:39936
	global_load_lds_dwordx4 v168, s[0:1]
	s_mov_b32 m0, s43
	s_nop 0
	global_load_lds_dwordx4 v164, s[0:1]
	s_waitcnt vmcnt(8)
	s_waitcnt lgkmcnt(0)
	s_barrier
	s_setprio 1
	v_mfma_f32_16x16x32_bf16 v[124:127], v[128:131], v[214:217], v[124:127]
	v_mfma_f32_16x16x32_bf16 v[108:111], v[128:131], v[222:225], v[108:111]
	v_mfma_f32_16x16x32_bf16 v[92:95], v[128:131], v[230:233], v[92:95]
	v_mfma_f32_16x16x32_bf16 v[76:79], v[128:131], v[238:241], v[76:79]
	v_mfma_f32_16x16x32_bf16 v[120:123], v[136:139], v[214:217], v[120:123]
	v_mfma_f32_16x16x32_bf16 v[104:107], v[136:139], v[222:225], v[104:107]
	v_mfma_f32_16x16x32_bf16 v[88:91], v[136:139], v[230:233], v[88:91]
	v_mfma_f32_16x16x32_bf16 v[72:75], v[136:139], v[238:241], v[72:75]
	v_mfma_f32_16x16x32_bf16 v[124:127], v[132:135], v[218:221], v[124:127]
	v_mfma_f32_16x16x32_bf16 v[108:111], v[132:135], v[226:229], v[108:111]
	v_mfma_f32_16x16x32_bf16 v[92:95], v[132:135], v[234:237], v[92:95]
	v_mfma_f32_16x16x32_bf16 v[76:79], v[132:135], v[242:245], v[76:79]
	v_mfma_f32_16x16x32_bf16 v[120:123], v[140:143], v[218:221], v[120:123]
	v_mfma_f32_16x16x32_bf16 v[104:107], v[140:143], v[226:229], v[104:107]
	v_mfma_f32_16x16x32_bf16 v[88:91], v[140:143], v[234:237], v[88:91]
	v_mfma_f32_16x16x32_bf16 v[72:75], v[140:143], v[242:245], v[72:75]
	v_mfma_f32_16x16x32_bf16 v[116:119], v[174:177], v[214:217], v[116:119]
	v_mfma_f32_16x16x32_bf16 v[100:103], v[174:177], v[222:225], v[100:103]
	v_mfma_f32_16x16x32_bf16 v[84:87], v[174:177], v[230:233], v[84:87]
	v_mfma_f32_16x16x32_bf16 v[68:71], v[174:177], v[238:241], v[68:71]
	v_mfma_f32_16x16x32_bf16 v[112:115], v[188:191], v[214:217], v[112:115]
	v_mfma_f32_16x16x32_bf16 v[96:99], v[188:191], v[222:225], v[96:99]
	v_mfma_f32_16x16x32_bf16 v[80:83], v[188:191], v[230:233], v[80:83]
	v_mfma_f32_16x16x32_bf16 v[64:67], v[188:191], v[238:241], v[64:67]
	v_mfma_f32_16x16x32_bf16 v[116:119], v[184:187], v[218:221], v[116:119]
	v_mfma_f32_16x16x32_bf16 v[100:103], v[184:187], v[226:229], v[100:103]
	v_mfma_f32_16x16x32_bf16 v[84:87], v[184:187], v[234:237], v[84:87]
	v_mfma_f32_16x16x32_bf16 v[68:71], v[184:187], v[242:245], v[68:71]
	v_mfma_f32_16x16x32_bf16 v[112:115], v[210:213], v[218:221], v[112:115]
	v_mfma_f32_16x16x32_bf16 v[96:99], v[210:213], v[226:229], v[96:99]
	v_mfma_f32_16x16x32_bf16 v[80:83], v[210:213], v[234:237], v[80:83]
	v_mfma_f32_16x16x32_bf16 v[64:67], v[210:213], v[242:245], v[64:67]
	s_setprio 0
	s_barrier
	s_mov_b32 m0, s47
	s_add_u32 s0, s4, 0xb0080
	s_addc_u32 s1, s5, 0
	ds_read_b128 v[214:217], v181 offset:49152
	ds_read_b128 v[218:221], v181 offset:50176
	ds_read_b128 v[222:225], v181 offset:51200
	ds_read_b128 v[226:229], v181 offset:52224
	ds_read_b128 v[230:233], v181 offset:53248
	ds_read_b128 v[234:237], v181 offset:54272
	ds_read_b128 v[238:241], v181 offset:55296
	ds_read_b128 v[242:245], v181 offset:56320
	s_add_u32 s98, s4, 0x80
	s_addc_u32 s99, s5, 0
	global_load_lds_dwordx4 v166, s[98:99]
	s_mov_b32 m0, s48
	s_nop 0
	global_load_lds_dwordx4 v162, s[98:99]
	s_mov_b32 m0, s51
	s_nop 0
	global_load_lds_dwordx4 v166, s[0:1]
	s_mov_b32 m0, s52
	s_nop 0
	global_load_lds_dwordx4 v162, s[0:1]
	s_mov_b32 m0, s49
	s_nop 0
	s_add_u32 s100, s6, 0x80
	s_addc_u32 s101, s7, 0
	global_load_lds_dwordx4 v168, s[100:101]
	s_mov_b32 m0, s50
	s_nop 0
	global_load_lds_dwordx4 v164, s[100:101]
	s_waitcnt vmcnt(8)
	s_waitcnt lgkmcnt(0)
	s_barrier
	s_setprio 1
	v_mfma_f32_16x16x32_bf16 v[60:63], v[128:131], v[214:217], v[60:63]
	v_mfma_f32_16x16x32_bf16 v[44:47], v[128:131], v[222:225], v[44:47]
	v_mfma_f32_16x16x32_bf16 v[28:31], v[128:131], v[230:233], v[28:31]
	v_mfma_f32_16x16x32_bf16 v[12:15], v[128:131], v[238:241], v[12:15]
	v_mfma_f32_16x16x32_bf16 v[56:59], v[136:139], v[214:217], v[56:59]
	v_mfma_f32_16x16x32_bf16 v[40:43], v[136:139], v[222:225], v[40:43]
	v_mfma_f32_16x16x32_bf16 v[24:27], v[136:139], v[230:233], v[24:27]
	v_mfma_f32_16x16x32_bf16 v[8:11], v[136:139], v[238:241], v[8:11]
	v_mfma_f32_16x16x32_bf16 v[60:63], v[132:135], v[218:221], v[60:63]
	v_mfma_f32_16x16x32_bf16 v[44:47], v[132:135], v[226:229], v[44:47]
	v_mfma_f32_16x16x32_bf16 v[28:31], v[132:135], v[234:237], v[28:31]
	v_mfma_f32_16x16x32_bf16 v[12:15], v[132:135], v[242:245], v[12:15]
	v_mfma_f32_16x16x32_bf16 v[56:59], v[140:143], v[218:221], v[56:59]
	v_mfma_f32_16x16x32_bf16 v[40:43], v[140:143], v[226:229], v[40:43]
	v_mfma_f32_16x16x32_bf16 v[24:27], v[140:143], v[234:237], v[24:27]
	v_mfma_f32_16x16x32_bf16 v[8:11], v[140:143], v[242:245], v[8:11]
	v_mfma_f32_16x16x32_bf16 v[52:55], v[174:177], v[214:217], v[52:55]
	v_mfma_f32_16x16x32_bf16 v[36:39], v[174:177], v[222:225], v[36:39]
	v_mfma_f32_16x16x32_bf16 v[20:23], v[174:177], v[230:233], v[20:23]
	v_mfma_f32_16x16x32_bf16 v[4:7], v[174:177], v[238:241], v[4:7]
	v_mfma_f32_16x16x32_bf16 v[48:51], v[188:191], v[214:217], v[48:51]
	v_mfma_f32_16x16x32_bf16 v[32:35], v[188:191], v[222:225], v[32:35]
	v_mfma_f32_16x16x32_bf16 v[16:19], v[188:191], v[230:233], v[16:19]
	v_mfma_f32_16x16x32_bf16 v[0:3], v[188:191], v[238:241], v[0:3]
	v_mfma_f32_16x16x32_bf16 v[52:55], v[184:187], v[218:221], v[52:55]
	v_mfma_f32_16x16x32_bf16 v[36:39], v[184:187], v[226:229], v[36:39]
	v_mfma_f32_16x16x32_bf16 v[20:23], v[184:187], v[234:237], v[20:23]
	v_mfma_f32_16x16x32_bf16 v[4:7], v[184:187], v[242:245], v[4:7]
	v_mfma_f32_16x16x32_bf16 v[48:51], v[210:213], v[218:221], v[48:51]
	v_mfma_f32_16x16x32_bf16 v[32:35], v[210:213], v[226:229], v[32:35]
	v_mfma_f32_16x16x32_bf16 v[16:19], v[210:213], v[234:237], v[16:19]
	v_mfma_f32_16x16x32_bf16 v[0:3], v[210:213], v[242:245], v[0:3]
	s_setprio 0
	s_barrier
	s_add_i32 s13, s13, 2
	s_add_u32 s10, s10, 0x100
	s_addc_u32 s11, s11, 0
	s_cmp_gt_u32 s13, 41
	s_mov_b64 s[0:1], s[2:3]
; #define PG8_STAGE(bufoff, gbase, voff) do { _Pragma("unroll") for (int _i = 0; _i < 2; ++_i) \
;         __builtin_amdgcn_global_load_lds((const unsigned*)((const char*)(gbase) + (voff)[_i]), (PG8_LAS unsigned*)(lds + (bufoff) + ldsw + _i * 8192), 16, 0, 0); } while (0)
; #define PG8_LDA(dst, b, h) do { _Pragma("unroll") for (int m = 0; m < 4; ++m) _Pragma("unroll") for (int k = 0; k < 2; ++k) dst[m][k] = *(const PG8_LAS bf16x8*)(lds + PG8_SA(b, h) + aoff + m * 2048 + k * 1024); } while (0)
; #define PG8_LDB(dst, b, h) do { _Pragma("unroll") for (int n = 0; n < 2; ++n) _Pragma("unroll") for (int k = 0; k < 2; ++k) dst[n][k] = *(const PG8_LAS bf16x8*)(lds + PG8_SB(b, h) + boff + n * 2048 + k * 1024); } while (0)
; #define PG8_MMA(ai, bj, At, Bt) do { __builtin_amdgcn_s_setprio(1); _Pragma("unroll") for (int m = 0; m < 4; ++m) _Pragma("unroll") for (int n = 0; n < 2; ++n) _Pragma("unroll") for (int k = 0; k < 2; ++k) \
;         acc[ai][bj][m][n] = __builtin_amdgcn_mfma_f32_16x16x32_bf16(Bt[n][k], At[m][k], acc[ai][bj][m][n], 0, 0, 0); __builtin_amdgcn_s_setprio(0); } while (0)
; #define PG8_WAIT_V(n) asm volatile("s_waitcnt vmcnt(" #n ")" ::: "memory")
; #define PG8_WAIT_L(n) asm volatile("s_waitcnt lgkmcnt(" #n ")" ::: "memory")
; template <class Epi, class Sched, bool ALIGN_EPI = false, bool SP2 = false>
; __device__ __forceinline__ void gemm_phase(PG8_LAS unsigned char* lds, const Gemm g, const Sched& S, const Epi& E) {
;     ...
;             const bool last = (t == nt - 2);
;             const char* a1 = cA + (size_t)(t + 1) * kstep;
;             const char* a2 = last ? nA : cA + (size_t)(t + 2) * kstep; const char* b2 = last ? nB : cB + (size_t)(t + 2) * kstep;
;             const char* a3 = a2 + kstep; const char* b3 = b2 + kstep;
;             if (last && has_next) S.a_ready(nxt);
;             if constexpr (SP2) {
;             PG8_LDB(B0, 0, 0); PG8_LDB(B1, 0, 1); PG8_SCHED; PG8_LDA(At, 0, 0); PG8_STAGE(PG8_SA(1, 1), a1 + hstep, voffA);
;             PG8_WAIT_V(8); PG8_WAIT_L(0); PG8_BAR; PG8_MMA(0, 0, At, B0); PG8_MMA(0, 1, At, B1); PG8_BAR; PG8_SCHED;
;             PG8_LDA(At, 0, 1); PG8_STAGE(PG8_SB(0, 0), b2, voffB); PG8_STAGE(PG8_SB(0, 1), b2 + hstep, voffB); PG8_STAGE(PG8_SA(0, 0), a2, voffA);
;             PG8_WAIT_V(8); PG8_WAIT_L(0); PG8_BAR; PG8_MMA(1, 0, At, B0); PG8_MMA(1, 1, At, B1); PG8_BAR; PG8_SCHED;
.LBB0_545:
	ds_read_b128 v[128:131], v254
	ds_read_b128 v[132:135], v254 offset:1024
	ds_read_b128 v[136:139], v254 offset:2048
	ds_read_b128 v[140:143], v254 offset:3072
	ds_read_b128 v[174:177], v254 offset:16384
	ds_read_b128 v[184:187], v254 offset:17408
	ds_read_b128 v[188:191], v254 offset:18432
	ds_read_b128 v[210:213], v254 offset:19456
	s_add_u32 s2, s0, 0x100
	s_addc_u32 s3, s1, 0
	s_cmp_eq_u32 s13, 40
	s_cselect_b32 s7, s27, s3
	s_cselect_b32 s6, s26, s2
	s_cselect_b32 s5, s37, s11
	s_cselect_b32 s4, s36, s10
	s_add_i32 m0, s29, 0xc000
	ds_read_b128 v[214:217], v181
	ds_read_b128 v[218:221], v181 offset:1024
	ds_read_b128 v[222:225], v181 offset:2048
	ds_read_b128 v[226:229], v181 offset:3072
	ds_read_b128 v[230:233], v181 offset:4096
	ds_read_b128 v[234:237], v181 offset:5120
	ds_read_b128 v[238:241], v181 offset:6144
	ds_read_b128 v[242:245], v181 offset:7168
	global_load_lds_dwordx4 v170, s[0:1]
	s_add_i32 m0, s29, 0xe000
	s_nop 0
	global_load_lds_dwordx4 v172, s[0:1]
	s_waitcnt vmcnt(8)
	s_waitcnt lgkmcnt(0)
	s_barrier
	s_setprio 1
	v_mfma_f32_16x16x32_bf16 v[124:127], v[128:131], v[214:217], v[124:127]
	v_mfma_f32_16x16x32_bf16 v[108:111], v[128:131], v[222:225], v[108:111]
	v_mfma_f32_16x16x32_bf16 v[92:95], v[128:131], v[230:233], v[92:95]
	v_mfma_f32_16x16x32_bf16 v[76:79], v[128:131], v[238:241], v[76:79]
	v_mfma_f32_16x16x32_bf16 v[120:123], v[136:139], v[214:217], v[120:123]
	v_mfma_f32_16x16x32_bf16 v[104:107], v[136:139], v[222:225], v[104:107]
	v_mfma_f32_16x16x32_bf16 v[88:91], v[136:139], v[230:233], v[88:91]
	v_mfma_f32_16x16x32_bf16 v[72:75], v[136:139], v[238:241], v[72:75]
	v_mfma_f32_16x16x32_bf16 v[124:127], v[132:135], v[218:221], v[124:127]
	v_mfma_f32_16x16x32_bf16 v[108:111], v[132:135], v[226:229], v[108:111]
	v_mfma_f32_16x16x32_bf16 v[92:95], v[132:135], v[234:237], v[92:95]
	v_mfma_f32_16x16x32_bf16 v[76:79], v[132:135], v[242:245], v[76:79]
	v_mfma_f32_16x16x32_bf16 v[120:123], v[140:143], v[218:221], v[120:123]
	v_mfma_f32_16x16x32_bf16 v[104:107], v[140:143], v[226:229], v[104:107]
	v_mfma_f32_16x16x32_bf16 v[88:91], v[140:143], v[234:237], v[88:91]
	v_mfma_f32_16x16x32_bf16 v[72:75], v[140:143], v[242:245], v[72:75]
	v_mfma_f32_16x16x32_bf16 v[116:119], v[174:177], v[214:217], v[116:119]
	v_mfma_f32_16x16x32_bf16 v[100:103], v[174:177], v[222:225], v[100:103]
	v_mfma_f32_16x16x32_bf16 v[84:87], v[174:177], v[230:233], v[84:87]
	v_mfma_f32_16x16x32_bf16 v[68:71], v[174:177], v[238:241], v[68:71]
	v_mfma_f32_16x16x32_bf16 v[112:115], v[188:191], v[214:217], v[112:115]
	v_mfma_f32_16x16x32_bf16 v[96:99], v[188:191], v[222:225], v[96:99]
	v_mfma_f32_16x16x32_bf16 v[80:83], v[188:191], v[230:233], v[80:83]
	v_mfma_f32_16x16x32_bf16 v[64:67], v[188:191], v[238:241], v[64:67]
	v_mfma_f32_16x16x32_bf16 v[116:119], v[184:187], v[218:221], v[116:119]
	v_mfma_f32_16x16x32_bf16 v[100:103], v[184:187], v[226:229], v[100:103]
	v_mfma_f32_16x16x32_bf16 v[84:87], v[184:187], v[234:237], v[84:87]
	v_mfma_f32_16x16x32_bf16 v[68:71], v[184:187], v[242:245], v[68:71]
	v_mfma_f32_16x16x32_bf16 v[112:115], v[210:213], v[218:221], v[112:115]
	v_mfma_f32_16x16x32_bf16 v[96:99], v[210:213], v[226:229], v[96:99]
	v_mfma_f32_16x16x32_bf16 v[80:83], v[210:213], v[234:237], v[80:83]
	v_mfma_f32_16x16x32_bf16 v[64:67], v[210:213], v[242:245], v[64:67]
	s_setprio 0
	s_barrier
	s_mov_b32 m0, s35
	s_add_u32 s0, s4, 0xb0000
	s_addc_u32 s1, s5, 0
	ds_read_b128 v[214:217], v181 offset:16384
	ds_read_b128 v[218:221], v181 offset:17408
	ds_read_b128 v[222:225], v181 offset:18432
	ds_read_b128 v[226:229], v181 offset:19456
	ds_read_b128 v[230:233], v181 offset:20480
	ds_read_b128 v[234:237], v181 offset:21504
	ds_read_b128 v[238:241], v181 offset:22528
	ds_read_b128 v[242:245], v181 offset:23552
	global_load_lds_dwordx4 v166, s[4:5]
	s_mov_b32 m0, s38
	s_nop 0
	global_load_lds_dwordx4 v162, s[4:5]
	s_mov_b32 m0, s39
	s_nop 0
	global_load_lds_dwordx4 v166, s[0:1]
	s_mov_b32 m0, s40
	s_nop 0
	global_load_lds_dwordx4 v162, s[0:1]
	s_mov_b32 m0, s29
	s_nop 0
	global_load_lds_dwordx4 v168, s[6:7]
	s_mov_b32 m0, s41
	s_nop 0
	global_load_lds_dwordx4 v164, s[6:7]
	s_waitcnt vmcnt(8)
	s_waitcnt lgkmcnt(0)
	s_barrier
	s_setprio 1
	v_mfma_f32_16x16x32_bf16 v[60:63], v[128:131], v[214:217], v[60:63]
	v_mfma_f32_16x16x32_bf16 v[44:47], v[128:131], v[222:225], v[44:47]
	v_mfma_f32_16x16x32_bf16 v[28:31], v[128:131], v[230:233], v[28:31]
	v_mfma_f32_16x16x32_bf16 v[12:15], v[128:131], v[238:241], v[12:15]
	v_mfma_f32_16x16x32_bf16 v[56:59], v[136:139], v[214:217], v[56:59]
	v_mfma_f32_16x16x32_bf16 v[40:43], v[136:139], v[222:225], v[40:43]
	v_mfma_f32_16x16x32_bf16 v[24:27], v[136:139], v[230:233], v[24:27]
	v_mfma_f32_16x16x32_bf16 v[8:11], v[136:139], v[238:241], v[8:11]
	v_mfma_f32_16x16x32_bf16 v[60:63], v[132:135], v[218:221], v[60:63]
	v_mfma_f32_16x16x32_bf16 v[44:47], v[132:135], v[226:229], v[44:47]
	v_mfma_f32_16x16x32_bf16 v[28:31], v[132:135], v[234:237], v[28:31]
	v_mfma_f32_16x16x32_bf16 v[12:15], v[132:135], v[242:245], v[12:15]
	v_mfma_f32_16x16x32_bf16 v[56:59], v[140:143], v[218:221], v[56:59]
	v_mfma_f32_16x16x32_bf16 v[40:43], v[140:143], v[226:229], v[40:43]
	v_mfma_f32_16x16x32_bf16 v[24:27], v[140:143], v[234:237], v[24:27]
	v_mfma_f32_16x16x32_bf16 v[8:11], v[140:143], v[242:245], v[8:11]
	v_mfma_f32_16x16x32_bf16 v[52:55], v[174:177], v[214:217], v[52:55]
	v_mfma_f32_16x16x32_bf16 v[36:39], v[174:177], v[222:225], v[36:39]
	v_mfma_f32_16x16x32_bf16 v[20:23], v[174:177], v[230:233], v[20:23]
	v_mfma_f32_16x16x32_bf16 v[4:7], v[174:177], v[238:241], v[4:7]
	v_mfma_f32_16x16x32_bf16 v[48:51], v[188:191], v[214:217], v[48:51]
	v_mfma_f32_16x16x32_bf16 v[32:35], v[188:191], v[222:225], v[32:35]
	v_mfma_f32_16x16x32_bf16 v[16:19], v[188:191], v[230:233], v[16:19]
	v_mfma_f32_16x16x32_bf16 v[0:3], v[188:191], v[238:241], v[0:3]
	v_mfma_f32_16x16x32_bf16 v[52:55], v[184:187], v[218:221], v[52:55]
	v_mfma_f32_16x16x32_bf16 v[36:39], v[184:187], v[226:229], v[36:39]
	v_mfma_f32_16x16x32_bf16 v[20:23], v[184:187], v[234:237], v[20:23]
	v_mfma_f32_16x16x32_bf16 v[4:7], v[184:187], v[242:245], v[4:7]
	v_mfma_f32_16x16x32_bf16 v[48:51], v[210:213], v[218:221], v[48:51]
	v_mfma_f32_16x16x32_bf16 v[32:35], v[210:213], v[226:229], v[32:35]
	v_mfma_f32_16x16x32_bf16 v[16:19], v[210:213], v[234:237], v[16:19]
	v_mfma_f32_16x16x32_bf16 v[0:3], v[210:213], v[242:245], v[0:3]
	s_setprio 0
	s_barrier
; #define PG8_STAGE(bufoff, gbase, voff) do { _Pragma("unroll") for (int _i = 0; _i < 2; ++_i) \
;         __builtin_amdgcn_global_load_lds((const unsigned*)((const char*)(gbase) + (voff)[_i]), (PG8_LAS unsigned*)(lds + (bufoff) + ldsw + _i * 8192), 16, 0, 0); } while (0)
; #define PG8_LDA(dst, b, h) do { _Pragma("unroll") for (int m = 0; m < 4; ++m) _Pragma("unroll") for (int k = 0; k < 2; ++k) dst[m][k] = *(const PG8_LAS bf16x8*)(lds + PG8_SA(b, h) + aoff + m * 2048 + k * 1024); } while (0)
; #define PG8_LDB(dst, b, h) do { _Pragma("unroll") for (int n = 0; n < 2; ++n) _Pragma("unroll") for (int k = 0; k < 2; ++k) dst[n][k] = *(const PG8_LAS bf16x8*)(lds + PG8_SB(b, h) + boff + n * 2048 + k * 1024); } while (0)
; #define PG8_MMA(ai, bj, At, Bt) do { __builtin_amdgcn_s_setprio(1); _Pragma("unroll") for (int m = 0; m < 4; ++m) _Pragma("unroll") for (int n = 0; n < 2; ++n) _Pragma("unroll") for (int k = 0; k < 2; ++k) \
;         acc[ai][bj][m][n] = __builtin_amdgcn_mfma_f32_16x16x32_bf16(Bt[n][k], At[m][k], acc[ai][bj][m][n], 0, 0, 0); __builtin_amdgcn_s_setprio(0); } while (0)
; #define PG8_WAIT_V(n) asm volatile("s_waitcnt vmcnt(" #n ")" ::: "memory")
; #define PG8_WAIT_L(n) asm volatile("s_waitcnt lgkmcnt(" #n ")" ::: "memory")
; #define PG8_BAR __builtin_amdgcn_s_barrier()
; #define PG8_SCHED __builtin_amdgcn_sched_barrier(0)
; template <class Epi, class Sched, bool ALIGN_EPI = false, bool SP2 = false>
; __device__ __forceinline__ void gemm_phase(PG8_LAS unsigned char* lds, const Gemm g, const Sched& S, const Epi& E) {
;     ...
;             PG8_LDB(B0, 1, 0); PG8_LDB(B1, 1, 1); PG8_SCHED; PG8_LDA(At, 1, 0); PG8_STAGE(PG8_SA(0, 1), a2 + hstep, voffA);
;             PG8_WAIT_V(8); PG8_WAIT_L(0); PG8_BAR; PG8_MMA(0, 0, At, B0); PG8_MMA(0, 1, At, B1); PG8_BAR; PG8_SCHED;
;             PG8_LDA(At, 1, 1); PG8_STAGE(PG8_SB(1, 0), b3, voffB); PG8_STAGE(PG8_SB(1, 1), b3 + hstep, voffB); PG8_STAGE(PG8_SA(1, 0), a3, voffA);
;             PG8_WAIT_V(8); PG8_WAIT_L(0); PG8_BAR; PG8_MMA(1, 0, At, B0); PG8_MMA(1, 1, At, B1); PG8_BAR; PG8_SCHED;
;     ...
;         if constexpr (ALIGN_EPI) { if (wr == 0) PG8_BAR; }
	ds_read_b128 v[128:131], v254 offset:32768
	ds_read_b128 v[132:135], v254 offset:33792
	ds_read_b128 v[136:139], v254 offset:34816
	ds_read_b128 v[140:143], v254 offset:35840
	ds_read_b128 v[174:177], v254 offset:49152
	ds_read_b128 v[184:187], v254 offset:50176
	ds_read_b128 v[188:191], v254 offset:51200
	ds_read_b128 v[210:213], v254 offset:52224
	s_add_u32 s0, s6, 0xb0000
	s_addc_u32 s1, s7, 0
	s_mov_b32 m0, s42
	ds_read_b128 v[214:217], v181 offset:32768
	ds_read_b128 v[218:221], v181 offset:33792
	ds_read_b128 v[222:225], v181 offset:34816
	ds_read_b128 v[226:229], v181 offset:35840
	ds_read_b128 v[230:233], v181 offset:36864
	ds_read_b128 v[234:237], v181 offset:37888
	ds_read_b128 v[238:241], v181 offset:38912
	ds_read_b128 v[242:245], v181 offset:39936
	global_load_lds_dwordx4 v168, s[0:1]
	s_mov_b32 m0, s43
	s_nop 0
	global_load_lds_dwordx4 v164, s[0:1]
	s_waitcnt vmcnt(8)
	s_waitcnt lgkmcnt(0)
	s_barrier
	s_setprio 1
	v_mfma_f32_16x16x32_bf16 v[124:127], v[128:131], v[214:217], v[124:127]
	v_mfma_f32_16x16x32_bf16 v[108:111], v[128:131], v[222:225], v[108:111]
	v_mfma_f32_16x16x32_bf16 v[92:95], v[128:131], v[230:233], v[92:95]
	v_mfma_f32_16x16x32_bf16 v[76:79], v[128:131], v[238:241], v[76:79]
	v_mfma_f32_16x16x32_bf16 v[120:123], v[136:139], v[214:217], v[120:123]
	v_mfma_f32_16x16x32_bf16 v[104:107], v[136:139], v[222:225], v[104:107]
	v_mfma_f32_16x16x32_bf16 v[88:91], v[136:139], v[230:233], v[88:91]
	v_mfma_f32_16x16x32_bf16 v[72:75], v[136:139], v[238:241], v[72:75]
	v_mfma_f32_16x16x32_bf16 v[124:127], v[132:135], v[218:221], v[124:127]
	v_mfma_f32_16x16x32_bf16 v[108:111], v[132:135], v[226:229], v[108:111]
	v_mfma_f32_16x16x32_bf16 v[92:95], v[132:135], v[234:237], v[92:95]
	v_mfma_f32_16x16x32_bf16 v[76:79], v[132:135], v[242:245], v[76:79]
	v_mfma_f32_16x16x32_bf16 v[120:123], v[140:143], v[218:221], v[120:123]
	v_mfma_f32_16x16x32_bf16 v[104:107], v[140:143], v[226:229], v[104:107]
	v_mfma_f32_16x16x32_bf16 v[88:91], v[140:143], v[234:237], v[88:91]
	v_mfma_f32_16x16x32_bf16 v[72:75], v[140:143], v[242:245], v[72:75]
	v_mfma_f32_16x16x32_bf16 v[116:119], v[174:177], v[214:217], v[116:119]
	v_mfma_f32_16x16x32_bf16 v[100:103], v[174:177], v[222:225], v[100:103]
	v_mfma_f32_16x16x32_bf16 v[84:87], v[174:177], v[230:233], v[84:87]
	v_mfma_f32_16x16x32_bf16 v[68:71], v[174:177], v[238:241], v[68:71]
	v_mfma_f32_16x16x32_bf16 v[112:115], v[188:191], v[214:217], v[112:115]
	v_mfma_f32_16x16x32_bf16 v[96:99], v[188:191], v[222:225], v[96:99]
	v_mfma_f32_16x16x32_bf16 v[80:83], v[188:191], v[230:233], v[80:83]
	v_mfma_f32_16x16x32_bf16 v[64:67], v[188:191], v[238:241], v[64:67]
	v_mfma_f32_16x16x32_bf16 v[116:119], v[184:187], v[218:221], v[116:119]
	v_mfma_f32_16x16x32_bf16 v[100:103], v[184:187], v[226:229], v[100:103]
	v_mfma_f32_16x16x32_bf16 v[84:87], v[184:187], v[234:237], v[84:87]
	v_mfma_f32_16x16x32_bf16 v[68:71], v[184:187], v[242:245], v[68:71]
	v_mfma_f32_16x16x32_bf16 v[112:115], v[210:213], v[218:221], v[112:115]
	v_mfma_f32_16x16x32_bf16 v[96:99], v[210:213], v[226:229], v[96:99]
	v_mfma_f32_16x16x32_bf16 v[80:83], v[210:213], v[234:237], v[80:83]
	v_mfma_f32_16x16x32_bf16 v[64:67], v[210:213], v[242:245], v[64:67]
	s_setprio 0
	s_barrier
	s_mov_b32 m0, s47
	s_add_u32 s0, s4, 0xb0080
	s_addc_u32 s1, s5, 0
	ds_read_b128 v[214:217], v181 offset:49152
	ds_read_b128 v[218:221], v181 offset:50176
	ds_read_b128 v[222:225], v181 offset:51200
	ds_read_b128 v[226:229], v181 offset:52224
	ds_read_b128 v[230:233], v181 offset:53248
	ds_read_b128 v[234:237], v181 offset:54272
	ds_read_b128 v[238:241], v181 offset:55296
	ds_read_b128 v[242:245], v181 offset:56320
	s_add_u32 s98, s4, 0x80
	s_addc_u32 s99, s5, 0
	global_load_lds_dwordx4 v166, s[98:99]
	s_mov_b32 m0, s48
	s_nop 0
	global_load_lds_dwordx4 v162, s[98:99]
	s_mov_b32 m0, s51
	s_nop 0
	global_load_lds_dwordx4 v166, s[0:1]
	s_mov_b32 m0, s52
	s_nop 0
	global_load_lds_dwordx4 v162, s[0:1]
	s_mov_b32 m0, s49
	s_nop 0
	s_add_u32 s100, s6, 0x80
	s_addc_u32 s101, s7, 0
	global_load_lds_dwordx4 v168, s[100:101]
	s_mov_b32 m0, s50
	s_nop 0
	global_load_lds_dwordx4 v164, s[100:101]
	s_waitcnt vmcnt(8)
	s_waitcnt lgkmcnt(0)
	s_barrier
	s_setprio 1
	v_mfma_f32_16x16x32_bf16 v[60:63], v[128:131], v[214:217], v[60:63]
	v_mfma_f32_16x16x32_bf16 v[44:47], v[128:131], v[222:225], v[44:47]
	v_mfma_f32_16x16x32_bf16 v[28:31], v[128:131], v[230:233], v[28:31]
	v_mfma_f32_16x16x32_bf16 v[12:15], v[128:131], v[238:241], v[12:15]
	v_mfma_f32_16x16x32_bf16 v[56:59], v[136:139], v[214:217], v[56:59]
	v_mfma_f32_16x16x32_bf16 v[40:43], v[136:139], v[222:225], v[40:43]
	v_mfma_f32_16x16x32_bf16 v[24:27], v[136:139], v[230:233], v[24:27]
	v_mfma_f32_16x16x32_bf16 v[8:11], v[136:139], v[238:241], v[8:11]
	v_mfma_f32_16x16x32_bf16 v[60:63], v[132:135], v[218:221], v[60:63]
	v_mfma_f32_16x16x32_bf16 v[44:47], v[132:135], v[226:229], v[44:47]
	v_mfma_f32_16x16x32_bf16 v[28:31], v[132:135], v[234:237], v[28:31]
	v_mfma_f32_16x16x32_bf16 v[12:15], v[132:135], v[242:245], v[12:15]
	v_mfma_f32_16x16x32_bf16 v[56:59], v[140:143], v[218:221], v[56:59]
	v_mfma_f32_16x16x32_bf16 v[40:43], v[140:143], v[226:229], v[40:43]
	v_mfma_f32_16x16x32_bf16 v[24:27], v[140:143], v[234:237], v[24:27]
	v_mfma_f32_16x16x32_bf16 v[8:11], v[140:143], v[242:245], v[8:11]
	v_mfma_f32_16x16x32_bf16 v[52:55], v[174:177], v[214:217], v[52:55]
	v_mfma_f32_16x16x32_bf16 v[36:39], v[174:177], v[222:225], v[36:39]
	v_mfma_f32_16x16x32_bf16 v[20:23], v[174:177], v[230:233], v[20:23]
	v_mfma_f32_16x16x32_bf16 v[4:7], v[174:177], v[238:241], v[4:7]
	v_mfma_f32_16x16x32_bf16 v[48:51], v[188:191], v[214:217], v[48:51]
	v_mfma_f32_16x16x32_bf16 v[32:35], v[188:191], v[222:225], v[32:35]
	v_mfma_f32_16x16x32_bf16 v[16:19], v[188:191], v[230:233], v[16:19]
	v_mfma_f32_16x16x32_bf16 v[0:3], v[188:191], v[238:241], v[0:3]
	v_mfma_f32_16x16x32_bf16 v[52:55], v[184:187], v[218:221], v[52:55]
	v_mfma_f32_16x16x32_bf16 v[36:39], v[184:187], v[226:229], v[36:39]
	v_mfma_f32_16x16x32_bf16 v[20:23], v[184:187], v[234:237], v[20:23]
	v_mfma_f32_16x16x32_bf16 v[4:7], v[184:187], v[242:245], v[4:7]
	v_mfma_f32_16x16x32_bf16 v[48:51], v[210:213], v[218:221], v[48:51]
	v_mfma_f32_16x16x32_bf16 v[32:35], v[210:213], v[226:229], v[32:35]
	v_mfma_f32_16x16x32_bf16 v[16:19], v[210:213], v[234:237], v[16:19]
	v_mfma_f32_16x16x32_bf16 v[0:3], v[210:213], v[242:245], v[0:3]
	s_setprio 0
	s_barrier
	s_add_i32 s13, s13, 2
	s_add_u32 s10, s10, 0x100
	s_addc_u32 s11, s11, 0
	s_cmp_gt_u32 s13, 41
	s_mov_b64 s[0:1], s[2:3]
	s_cbranch_scc0 .LBB0_545
	s_and_b64 vcc, exec, s[22:23]
	s_cbranch_vccz .LBB0_548
	s_barrier

; #define PG8_STAGE(bufoff, gbase, voff) do { _Pragma("unroll") for (int _i = 0; _i < 2; ++_i) \
;         __builtin_amdgcn_global_load_lds((const unsigned*)((const char*)(gbase) + (voff)[_i]), (PG8_LAS unsigned*)(lds + (bufoff) + ldsw + _i * 8192), 16, 0, 0); } while (0)
; #define PG8_LDA(dst, b, h) do { _Pragma("unroll") for (int m = 0; m < 4; ++m) _Pragma("unroll") for (int k = 0; k < 2; ++k) dst[m][k] = *(const PG8_LAS bf16x8*)(lds + PG8_SA(b, h) + aoff + m * 2048 + k * 1024); } while (0)
; #define PG8_LDB(dst, b, h) do { _Pragma("unroll") for (int n = 0; n < 2; ++n) _Pragma("unroll") for (int k = 0; k < 2; ++k) dst[n][k] = *(const PG8_LAS bf16x8*)(lds + PG8_SB(b, h) + boff + n * 2048 + k * 1024); } while (0)
; #define PG8_MMA(ai, bj, At, Bt) do { __builtin_amdgcn_s_setprio(1); _Pragma("unroll") for (int m = 0; m < 4; ++m) _Pragma("unroll") for (int n = 0; n < 2; ++n) _Pragma("unroll") for (int k = 0; k < 2; ++k) \
;         acc[ai][bj][m][n] = __builtin_amdgcn_mfma_f32_16x16x32_bf16(Bt[n][k], At[m][k], acc[ai][bj][m][n], 0, 0, 0); __builtin_amdgcn_s_setprio(0); } while (0)
; #define PG8_WAIT_V(n) asm volatile("s_waitcnt vmcnt(" #n ")" ::: "memory")
; #define PG8_WAIT_L(n) asm volatile("s_waitcnt lgkmcnt(" #n ")" ::: "memory")
; template <class Epi, class Sched, bool ALIGN_EPI = false, bool SP2 = false>
; __device__ __forceinline__ void gemm_phase(PG8_LAS unsigned char* lds, const Gemm g, const Sched& S, const Epi& E) {
;     ...
;             const bool last = (t == nt - 2);
;             const char* a1 = cA + (size_t)(t + 1) * kstep;
;             const char* a2 = last ? nA : cA + (size_t)(t + 2) * kstep; const char* b2 = last ? nB : cB + (size_t)(t + 2) * kstep;
;             const char* a3 = a2 + kstep; const char* b3 = b2 + kstep;
;             if (last && has_next) S.a_ready(nxt);
;             if constexpr (SP2) {
;             PG8_LDB(B0, 0, 0); PG8_LDB(B1, 0, 1); PG8_SCHED; PG8_LDA(At, 0, 0); PG8_STAGE(PG8_SA(1, 1), a1 + hstep, voffA);
;             PG8_WAIT_V(8); PG8_WAIT_L(0); PG8_BAR; PG8_MMA(0, 0, At, B0); PG8_MMA(0, 1, At, B1); PG8_BAR; PG8_SCHED;
;             PG8_LDA(At, 0, 1); PG8_STAGE(PG8_SB(0, 0), b2, voffB); PG8_STAGE(PG8_SB(0, 1), b2 + hstep, voffB); PG8_STAGE(PG8_SA(0, 0), a2, voffA);
;             PG8_WAIT_V(8); PG8_WAIT_L(0); PG8_BAR; PG8_MMA(1, 0, At, B0); PG8_MMA(1, 1, At, B1); PG8_BAR; PG8_SCHED;
.Lsgi_peel:
	ds_read_b128 v[140:143], v254
	ds_read_b128 v[162:165], v254 offset:1024
	ds_read_b128 v[166:169], v254 offset:2048
	ds_read_b128 v[170:173], v254 offset:3072
	ds_read_b128 v[180:183], v254 offset:16384
	ds_read_b128 v[184:187], v254 offset:17408
	ds_read_b128 v[188:191], v254 offset:18432
	ds_read_b128 v[210:213], v254 offset:19456
	s_add_u32 s2, s0, 0xfffc0080
	s_addc_u32 s3, s1, -1
	s_cmp_eq_u32 s55, 12
	s_cselect_b32 s5, s13, s3
	s_cselect_b32 s4, s25, s2
	s_cselect_b32 s3, s23, s39
	s_cselect_b32 s2, s33, s38
	s_add_i32 m0, s6, 0xc000
	ds_read_b128 v[214:217], v178
	ds_read_b128 v[218:221], v178 offset:1024
	ds_read_b128 v[222:225], v178 offset:2048
	ds_read_b128 v[226:229], v178 offset:3072
	ds_read_b128 v[230:233], v178 offset:4096
	ds_read_b128 v[234:237], v178 offset:5120
	ds_read_b128 v[238:241], v178 offset:6144
	ds_read_b128 v[242:245], v178 offset:7168
	global_load_lds_dwordx4 v136, s[0:1]
	s_add_i32 m0, s6, 0xe000
	s_nop 0
	global_load_lds_dwordx4 v138, s[0:1]
	s_waitcnt vmcnt(8)
	s_waitcnt lgkmcnt(0)
	s_barrier
	s_setprio 1
	v_mfma_f32_16x16x32_bf16 v[124:127], v[140:143], v[214:217], 0
	v_mfma_f32_16x16x32_bf16 v[108:111], v[140:143], v[222:225], 0
	v_mfma_f32_16x16x32_bf16 v[92:95], v[140:143], v[230:233], 0
	v_mfma_f32_16x16x32_bf16 v[76:79], v[140:143], v[238:241], 0
	v_mfma_f32_16x16x32_bf16 v[120:123], v[166:169], v[214:217], 0
	v_mfma_f32_16x16x32_bf16 v[104:107], v[166:169], v[222:225], 0
	v_mfma_f32_16x16x32_bf16 v[88:91], v[166:169], v[230:233], 0
	v_mfma_f32_16x16x32_bf16 v[72:75], v[166:169], v[238:241], 0
	v_mfma_f32_16x16x32_bf16 v[124:127], v[162:165], v[218:221], v[124:127]
	v_mfma_f32_16x16x32_bf16 v[108:111], v[162:165], v[226:229], v[108:111]
	v_mfma_f32_16x16x32_bf16 v[92:95], v[162:165], v[234:237], v[92:95]
	v_mfma_f32_16x16x32_bf16 v[76:79], v[162:165], v[242:245], v[76:79]
	v_mfma_f32_16x16x32_bf16 v[120:123], v[170:173], v[218:221], v[120:123]
	v_mfma_f32_16x16x32_bf16 v[104:107], v[170:173], v[226:229], v[104:107]
	v_mfma_f32_16x16x32_bf16 v[88:91], v[170:173], v[234:237], v[88:91]
	v_mfma_f32_16x16x32_bf16 v[72:75], v[170:173], v[242:245], v[72:75]
	v_mfma_f32_16x16x32_bf16 v[116:119], v[180:183], v[214:217], 0
	v_mfma_f32_16x16x32_bf16 v[100:103], v[180:183], v[222:225], 0
	v_mfma_f32_16x16x32_bf16 v[84:87], v[180:183], v[230:233], 0
	v_mfma_f32_16x16x32_bf16 v[68:71], v[180:183], v[238:241], 0
	v_mfma_f32_16x16x32_bf16 v[112:115], v[188:191], v[214:217], 0
	v_mfma_f32_16x16x32_bf16 v[96:99], v[188:191], v[222:225], 0
	v_mfma_f32_16x16x32_bf16 v[80:83], v[188:191], v[230:233], 0
	v_mfma_f32_16x16x32_bf16 v[64:67], v[188:191], v[238:241], 0
	v_mfma_f32_16x16x32_bf16 v[116:119], v[184:187], v[218:221], v[116:119]
	v_mfma_f32_16x16x32_bf16 v[100:103], v[184:187], v[226:229], v[100:103]
	v_mfma_f32_16x16x32_bf16 v[84:87], v[184:187], v[234:237], v[84:87]
	v_mfma_f32_16x16x32_bf16 v[68:71], v[184:187], v[242:245], v[68:71]
	v_mfma_f32_16x16x32_bf16 v[112:115], v[210:213], v[218:221], v[112:115]
	v_mfma_f32_16x16x32_bf16 v[96:99], v[210:213], v[226:229], v[96:99]
	v_mfma_f32_16x16x32_bf16 v[80:83], v[210:213], v[234:237], v[80:83]
	v_mfma_f32_16x16x32_bf16 v[64:67], v[210:213], v[242:245], v[64:67]
	s_setprio 0
	s_barrier
	s_mov_b32 m0, s31
	s_add_u32 s56, s2, 0x40000
	s_addc_u32 s57, s3, 0
	ds_read_b128 v[214:217], v178 offset:16384
	ds_read_b128 v[218:221], v178 offset:17408
	ds_read_b128 v[222:225], v178 offset:18432
	ds_read_b128 v[226:229], v178 offset:19456
	ds_read_b128 v[230:233], v178 offset:20480
	ds_read_b128 v[234:237], v178 offset:21504
	ds_read_b128 v[238:241], v178 offset:22528
	ds_read_b128 v[242:245], v178 offset:23552
	global_load_lds_dwordx4 v132, s[2:3]
	s_mov_b32 m0, s34
	s_nop 0
	global_load_lds_dwordx4 v128, s[2:3]
	s_mov_b32 m0, s35
	s_nop 0
	global_load_lds_dwordx4 v132, s[56:57]
	s_mov_b32 m0, s40
	s_nop 0
	global_load_lds_dwordx4 v128, s[56:57]
	s_mov_b32 m0, s6
	s_nop 0
	global_load_lds_dwordx4 v134, s[4:5]
	s_mov_b32 m0, s41
	s_nop 0
	global_load_lds_dwordx4 v130, s[4:5]
	s_waitcnt vmcnt(8)
	s_waitcnt lgkmcnt(0)
	s_barrier
	s_setprio 1
	v_mfma_f32_16x16x32_bf16 v[60:63], v[140:143], v[214:217], 0
	v_mfma_f32_16x16x32_bf16 v[44:47], v[140:143], v[222:225], 0
	v_mfma_f32_16x16x32_bf16 v[28:31], v[140:143], v[230:233], 0
	v_mfma_f32_16x16x32_bf16 v[12:15], v[140:143], v[238:241], 0
	v_mfma_f32_16x16x32_bf16 v[56:59], v[166:169], v[214:217], 0
	v_mfma_f32_16x16x32_bf16 v[40:43], v[166:169], v[222:225], 0
	v_mfma_f32_16x16x32_bf16 v[24:27], v[166:169], v[230:233], 0
	v_mfma_f32_16x16x32_bf16 v[8:11], v[166:169], v[238:241], 0
	v_mfma_f32_16x16x32_bf16 v[60:63], v[162:165], v[218:221], v[60:63]
	v_mfma_f32_16x16x32_bf16 v[44:47], v[162:165], v[226:229], v[44:47]
	v_mfma_f32_16x16x32_bf16 v[28:31], v[162:165], v[234:237], v[28:31]
	v_mfma_f32_16x16x32_bf16 v[12:15], v[162:165], v[242:245], v[12:15]
	v_mfma_f32_16x16x32_bf16 v[56:59], v[170:173], v[218:221], v[56:59]
	v_mfma_f32_16x16x32_bf16 v[40:43], v[170:173], v[226:229], v[40:43]
	v_mfma_f32_16x16x32_bf16 v[24:27], v[170:173], v[234:237], v[24:27]
	v_mfma_f32_16x16x32_bf16 v[8:11], v[170:173], v[242:245], v[8:11]
	v_mfma_f32_16x16x32_bf16 v[52:55], v[180:183], v[214:217], 0
	v_mfma_f32_16x16x32_bf16 v[36:39], v[180:183], v[222:225], 0
	v_mfma_f32_16x16x32_bf16 v[20:23], v[180:183], v[230:233], 0
	v_mfma_f32_16x16x32_bf16 v[4:7], v[180:183], v[238:241], 0
	v_mfma_f32_16x16x32_bf16 v[48:51], v[188:191], v[214:217], 0
	v_mfma_f32_16x16x32_bf16 v[32:35], v[188:191], v[222:225], 0
	v_mfma_f32_16x16x32_bf16 v[16:19], v[188:191], v[230:233], 0
	v_mfma_f32_16x16x32_bf16 v[0:3], v[188:191], v[238:241], 0
	v_mfma_f32_16x16x32_bf16 v[52:55], v[184:187], v[218:221], v[52:55]
	v_mfma_f32_16x16x32_bf16 v[36:39], v[184:187], v[226:229], v[36:39]
	v_mfma_f32_16x16x32_bf16 v[20:23], v[184:187], v[234:237], v[20:23]
	v_mfma_f32_16x16x32_bf16 v[4:7], v[184:187], v[242:245], v[4:7]
	v_mfma_f32_16x16x32_bf16 v[48:51], v[210:213], v[218:221], v[48:51]
	v_mfma_f32_16x16x32_bf16 v[32:35], v[210:213], v[226:229], v[32:35]
	v_mfma_f32_16x16x32_bf16 v[16:19], v[210:213], v[234:237], v[16:19]
	v_mfma_f32_16x16x32_bf16 v[0:3], v[210:213], v[242:245], v[0:3]
	s_setprio 0
	s_barrier
; #define PG8_STAGE(bufoff, gbase, voff) do { _Pragma("unroll") for (int _i = 0; _i < 2; ++_i) \
;         __builtin_amdgcn_global_load_lds((const unsigned*)((const char*)(gbase) + (voff)[_i]), (PG8_LAS unsigned*)(lds + (bufoff) + ldsw + _i * 8192), 16, 0, 0); } while (0)
; #define PG8_LDA(dst, b, h) do { _Pragma("unroll") for (int m = 0; m < 4; ++m) _Pragma("unroll") for (int k = 0; k < 2; ++k) dst[m][k] = *(const PG8_LAS bf16x8*)(lds + PG8_SA(b, h) + aoff + m * 2048 + k * 1024); } while (0)
; #define PG8_LDB(dst, b, h) do { _Pragma("unroll") for (int n = 0; n < 2; ++n) _Pragma("unroll") for (int k = 0; k < 2; ++k) dst[n][k] = *(const PG8_LAS bf16x8*)(lds + PG8_SB(b, h) + boff + n * 2048 + k * 1024); } while (0)
; #define PG8_MMA(ai, bj, At, Bt) do { __builtin_amdgcn_s_setprio(1); _Pragma("unroll") for (int m = 0; m < 4; ++m) _Pragma("unroll") for (int n = 0; n < 2; ++n) _Pragma("unroll") for (int k = 0; k < 2; ++k) \
;         acc[ai][bj][m][n] = __builtin_amdgcn_mfma_f32_16x16x32_bf16(Bt[n][k], At[m][k], acc[ai][bj][m][n], 0, 0, 0); __builtin_amdgcn_s_setprio(0); } while (0)
; #define PG8_WAIT_V(n) asm volatile("s_waitcnt vmcnt(" #n ")" ::: "memory")
; #define PG8_WAIT_L(n) asm volatile("s_waitcnt lgkmcnt(" #n ")" ::: "memory")
; #define PG8_BAR __builtin_amdgcn_s_barrier()
; #define PG8_SCHED __builtin_amdgcn_sched_barrier(0)
; template <class Epi, class Sched, bool ALIGN_EPI = false, bool SP2 = false>
; __device__ __forceinline__ void gemm_phase(PG8_LAS unsigned char* lds, const Gemm g, const Sched& S, const Epi& E) {
;     ...
;             PG8_LDB(B0, 1, 0); PG8_LDB(B1, 1, 1); PG8_SCHED; PG8_LDA(At, 1, 0); PG8_STAGE(PG8_SA(0, 1), a2 + hstep, voffA);
;             PG8_WAIT_V(8); PG8_WAIT_L(0); PG8_BAR; PG8_MMA(0, 0, At, B0); PG8_MMA(0, 1, At, B1); PG8_BAR; PG8_SCHED;
;             PG8_LDA(At, 1, 1); PG8_STAGE(PG8_SB(1, 0), b3, voffB); PG8_STAGE(PG8_SB(1, 1), b3 + hstep, voffB); PG8_STAGE(PG8_SA(1, 0), a3, voffA);
;             PG8_WAIT_V(8); PG8_WAIT_L(0); PG8_BAR; PG8_MMA(1, 0, At, B0); PG8_MMA(1, 1, At, B1); PG8_BAR; PG8_SCHED;
	ds_read_b128 v[140:143], v254 offset:32768
	ds_read_b128 v[162:165], v254 offset:33792
	ds_read_b128 v[166:169], v254 offset:34816
	ds_read_b128 v[170:173], v254 offset:35840
	ds_read_b128 v[180:183], v254 offset:49152
	ds_read_b128 v[184:187], v254 offset:50176
	ds_read_b128 v[188:191], v254 offset:51200
	ds_read_b128 v[210:213], v254 offset:52224
	s_add_u32 s4, s4, 0x40000
	s_addc_u32 s5, s5, 0
	s_mov_b32 m0, s42
	ds_read_b128 v[214:217], v178 offset:32768
	ds_read_b128 v[218:221], v178 offset:33792
	ds_read_b128 v[222:225], v178 offset:34816
	ds_read_b128 v[226:229], v178 offset:35840
	ds_read_b128 v[230:233], v178 offset:36864
	ds_read_b128 v[234:237], v178 offset:37888
	ds_read_b128 v[238:241], v178 offset:38912
	ds_read_b128 v[242:245], v178 offset:39936
	global_load_lds_dwordx4 v134, s[4:5]
	s_mov_b32 m0, s43
	s_nop 0
	global_load_lds_dwordx4 v130, s[4:5]
	s_waitcnt vmcnt(8)
	s_waitcnt lgkmcnt(0)
	s_barrier
	s_setprio 1
	v_mfma_f32_16x16x32_bf16 v[124:127], v[140:143], v[214:217], v[124:127]
	v_mfma_f32_16x16x32_bf16 v[108:111], v[140:143], v[222:225], v[108:111]
	v_mfma_f32_16x16x32_bf16 v[92:95], v[140:143], v[230:233], v[92:95]
	v_mfma_f32_16x16x32_bf16 v[76:79], v[140:143], v[238:241], v[76:79]
	v_mfma_f32_16x16x32_bf16 v[120:123], v[166:169], v[214:217], v[120:123]
	v_mfma_f32_16x16x32_bf16 v[104:107], v[166:169], v[222:225], v[104:107]
	v_mfma_f32_16x16x32_bf16 v[88:91], v[166:169], v[230:233], v[88:91]
	v_mfma_f32_16x16x32_bf16 v[72:75], v[166:169], v[238:241], v[72:75]
	v_mfma_f32_16x16x32_bf16 v[124:127], v[162:165], v[218:221], v[124:127]
	v_mfma_f32_16x16x32_bf16 v[108:111], v[162:165], v[226:229], v[108:111]
	v_mfma_f32_16x16x32_bf16 v[92:95], v[162:165], v[234:237], v[92:95]
	v_mfma_f32_16x16x32_bf16 v[76:79], v[162:165], v[242:245], v[76:79]
	v_mfma_f32_16x16x32_bf16 v[120:123], v[170:173], v[218:221], v[120:123]
	v_mfma_f32_16x16x32_bf16 v[104:107], v[170:173], v[226:229], v[104:107]
	v_mfma_f32_16x16x32_bf16 v[88:91], v[170:173], v[234:237], v[88:91]
	v_mfma_f32_16x16x32_bf16 v[72:75], v[170:173], v[242:245], v[72:75]
	v_mfma_f32_16x16x32_bf16 v[116:119], v[180:183], v[214:217], v[116:119]
	v_mfma_f32_16x16x32_bf16 v[100:103], v[180:183], v[222:225], v[100:103]
	v_mfma_f32_16x16x32_bf16 v[84:87], v[180:183], v[230:233], v[84:87]
	v_mfma_f32_16x16x32_bf16 v[68:71], v[180:183], v[238:241], v[68:71]
	v_mfma_f32_16x16x32_bf16 v[112:115], v[188:191], v[214:217], v[112:115]
	v_mfma_f32_16x16x32_bf16 v[96:99], v[188:191], v[222:225], v[96:99]
	v_mfma_f32_16x16x32_bf16 v[80:83], v[188:191], v[230:233], v[80:83]
	v_mfma_f32_16x16x32_bf16 v[64:67], v[188:191], v[238:241], v[64:67]
	v_mfma_f32_16x16x32_bf16 v[116:119], v[184:187], v[218:221], v[116:119]
	v_mfma_f32_16x16x32_bf16 v[100:103], v[184:187], v[226:229], v[100:103]
	v_mfma_f32_16x16x32_bf16 v[84:87], v[184:187], v[234:237], v[84:87]
	v_mfma_f32_16x16x32_bf16 v[68:71], v[184:187], v[242:245], v[68:71]
	v_mfma_f32_16x16x32_bf16 v[112:115], v[210:213], v[218:221], v[112:115]
	v_mfma_f32_16x16x32_bf16 v[96:99], v[210:213], v[226:229], v[96:99]
	v_mfma_f32_16x16x32_bf16 v[80:83], v[210:213], v[234:237], v[80:83]
	v_mfma_f32_16x16x32_bf16 v[64:67], v[210:213], v[242:245], v[64:67]
	s_setprio 0
	s_barrier
	s_mov_b32 m0, s48
	s_add_u32 s2, s2, 0x40080
	s_addc_u32 s3, s3, 0
	ds_read_b128 v[214:217], v178 offset:49152
	ds_read_b128 v[218:221], v178 offset:50176
	ds_read_b128 v[222:225], v178 offset:51200
	ds_read_b128 v[226:229], v178 offset:52224
	ds_read_b128 v[230:233], v178 offset:53248
	ds_read_b128 v[234:237], v178 offset:54272
	ds_read_b128 v[238:241], v178 offset:55296
	ds_read_b128 v[242:245], v178 offset:56320
	s_add_u32 s98, s2, 0xfffc0000
	s_addc_u32 s99, s3, -1
	global_load_lds_dwordx4 v132, s[98:99]
	s_mov_b32 m0, s49
	s_nop 0
	global_load_lds_dwordx4 v128, s[98:99]
	s_mov_b32 m0, s52
	s_nop 0
	global_load_lds_dwordx4 v132, s[2:3]
	s_mov_b32 m0, s53
	s_nop 0
	global_load_lds_dwordx4 v128, s[2:3]
	s_mov_b32 m0, s50
	s_nop 0
	s_add_u32 s100, s4, 0xfffc0080
	s_addc_u32 s101, s5, -1
	global_load_lds_dwordx4 v134, s[100:101]
	s_mov_b32 m0, s51
	s_nop 0
	global_load_lds_dwordx4 v130, s[100:101]
	s_waitcnt vmcnt(8)
	s_waitcnt lgkmcnt(0)
	s_barrier
	s_setprio 1
	v_mfma_f32_16x16x32_bf16 v[60:63], v[140:143], v[214:217], v[60:63]
	v_mfma_f32_16x16x32_bf16 v[44:47], v[140:143], v[222:225], v[44:47]
	v_mfma_f32_16x16x32_bf16 v[28:31], v[140:143], v[230:233], v[28:31]
	v_mfma_f32_16x16x32_bf16 v[12:15], v[140:143], v[238:241], v[12:15]
	v_mfma_f32_16x16x32_bf16 v[56:59], v[166:169], v[214:217], v[56:59]
	v_mfma_f32_16x16x32_bf16 v[40:43], v[166:169], v[222:225], v[40:43]
	v_mfma_f32_16x16x32_bf16 v[24:27], v[166:169], v[230:233], v[24:27]
	v_mfma_f32_16x16x32_bf16 v[8:11], v[166:169], v[238:241], v[8:11]
	v_mfma_f32_16x16x32_bf16 v[60:63], v[162:165], v[218:221], v[60:63]
	v_mfma_f32_16x16x32_bf16 v[44:47], v[162:165], v[226:229], v[44:47]
	v_mfma_f32_16x16x32_bf16 v[28:31], v[162:165], v[234:237], v[28:31]
	v_mfma_f32_16x16x32_bf16 v[12:15], v[162:165], v[242:245], v[12:15]
	v_mfma_f32_16x16x32_bf16 v[56:59], v[170:173], v[218:221], v[56:59]
	v_mfma_f32_16x16x32_bf16 v[40:43], v[170:173], v[226:229], v[40:43]
	v_mfma_f32_16x16x32_bf16 v[24:27], v[170:173], v[234:237], v[24:27]
	v_mfma_f32_16x16x32_bf16 v[8:11], v[170:173], v[242:245], v[8:11]
	v_mfma_f32_16x16x32_bf16 v[52:55], v[180:183], v[214:217], v[52:55]
	v_mfma_f32_16x16x32_bf16 v[36:39], v[180:183], v[222:225], v[36:39]
	v_mfma_f32_16x16x32_bf16 v[20:23], v[180:183], v[230:233], v[20:23]
	v_mfma_f32_16x16x32_bf16 v[4:7], v[180:183], v[238:241], v[4:7]
	v_mfma_f32_16x16x32_bf16 v[48:51], v[188:191], v[214:217], v[48:51]
	v_mfma_f32_16x16x32_bf16 v[32:35], v[188:191], v[222:225], v[32:35]
	v_mfma_f32_16x16x32_bf16 v[16:19], v[188:191], v[230:233], v[16:19]
	v_mfma_f32_16x16x32_bf16 v[0:3], v[188:191], v[238:241], v[0:3]
	v_mfma_f32_16x16x32_bf16 v[52:55], v[184:187], v[218:221], v[52:55]
	v_mfma_f32_16x16x32_bf16 v[36:39], v[184:187], v[226:229], v[36:39]
	v_mfma_f32_16x16x32_bf16 v[20:23], v[184:187], v[234:237], v[20:23]
	v_mfma_f32_16x16x32_bf16 v[4:7], v[184:187], v[242:245], v[4:7]
	v_mfma_f32_16x16x32_bf16 v[48:51], v[210:213], v[218:221], v[48:51]
	v_mfma_f32_16x16x32_bf16 v[32:35], v[210:213], v[226:229], v[32:35]
	v_mfma_f32_16x16x32_bf16 v[16:19], v[210:213], v[234:237], v[16:19]
	v_mfma_f32_16x16x32_bf16 v[0:3], v[210:213], v[242:245], v[0:3]
	s_setprio 0
	s_barrier
	s_add_i32 s55, s55, 2
	s_add_u32 s0, s0, 0x100
	s_addc_u32 s1, s1, 0
	s_add_u32 s38, s38, 0x100
	s_addc_u32 s39, s39, 0
	s_cmp_gt_u32 s55, 13
; #define PG8_STAGE(bufoff, gbase, voff) do { _Pragma("unroll") for (int _i = 0; _i < 2; ++_i) \
;         __builtin_amdgcn_global_load_lds((const unsigned*)((const char*)(gbase) + (voff)[_i]), (PG8_LAS unsigned*)(lds + (bufoff) + ldsw + _i * 8192), 16, 0, 0); } while (0)
; #define PG8_LDA(dst, b, h) do { _Pragma("unroll") for (int m = 0; m < 4; ++m) _Pragma("unroll") for (int k = 0; k < 2; ++k) dst[m][k] = *(const PG8_LAS bf16x8*)(lds + PG8_SA(b, h) + aoff + m * 2048 + k * 1024); } while (0)
; #define PG8_LDB(dst, b, h) do { _Pragma("unroll") for (int n = 0; n < 2; ++n) _Pragma("unroll") for (int k = 0; k < 2; ++k) dst[n][k] = *(const PG8_LAS bf16x8*)(lds + PG8_SB(b, h) + boff + n * 2048 + k * 1024); } while (0)
; #define PG8_MMA(ai, bj, At, Bt) do { __builtin_amdgcn_s_setprio(1); _Pragma("unroll") for (int m = 0; m < 4; ++m) _Pragma("unroll") for (int n = 0; n < 2; ++n) _Pragma("unroll") for (int k = 0; k < 2; ++k) \
;         acc[ai][bj][m][n] = __builtin_amdgcn_mfma_f32_16x16x32_bf16(Bt[n][k], At[m][k], acc[ai][bj][m][n], 0, 0, 0); __builtin_amdgcn_s_setprio(0); } while (0)
; #define PG8_WAIT_V(n) asm volatile("s_waitcnt vmcnt(" #n ")" ::: "memory")
; #define PG8_WAIT_L(n) asm volatile("s_waitcnt lgkmcnt(" #n ")" ::: "memory")
; template <class Epi, class Sched, bool ALIGN_EPI = false, bool SP2 = false>
; __device__ __forceinline__ void gemm_phase(PG8_LAS unsigned char* lds, const Gemm g, const Sched& S, const Epi& E) {
;     ...
;             const bool last = (t == nt - 2);
;             const char* a1 = cA + (size_t)(t + 1) * kstep;
;             const char* a2 = last ? nA : cA + (size_t)(t + 2) * kstep; const char* b2 = last ? nB : cB + (size_t)(t + 2) * kstep;
;             const char* a3 = a2 + kstep; const char* b3 = b2 + kstep;
;             if (last && has_next) S.a_ready(nxt);
;             if constexpr (SP2) {
;             PG8_LDB(B0, 0, 0); PG8_LDB(B1, 0, 1); PG8_SCHED; PG8_LDA(At, 0, 0); PG8_STAGE(PG8_SA(1, 1), a1 + hstep, voffA);
;             PG8_WAIT_V(8); PG8_WAIT_L(0); PG8_BAR; PG8_MMA(0, 0, At, B0); PG8_MMA(0, 1, At, B1); PG8_BAR; PG8_SCHED;
;             PG8_LDA(At, 0, 1); PG8_STAGE(PG8_SB(0, 0), b2, voffB); PG8_STAGE(PG8_SB(0, 1), b2 + hstep, voffB); PG8_STAGE(PG8_SA(0, 0), a2, voffA);
;             PG8_WAIT_V(8); PG8_WAIT_L(0); PG8_BAR; PG8_MMA(1, 0, At, B0); PG8_MMA(1, 1, At, B1); PG8_BAR; PG8_SCHED;
.LBB0_749:
	ds_read_b128 v[140:143], v254
	ds_read_b128 v[162:165], v254 offset:1024
	ds_read_b128 v[166:169], v254 offset:2048
	ds_read_b128 v[170:173], v254 offset:3072
	ds_read_b128 v[180:183], v254 offset:16384
	ds_read_b128 v[184:187], v254 offset:17408
	ds_read_b128 v[188:191], v254 offset:18432
	ds_read_b128 v[210:213], v254 offset:19456
	s_add_u32 s2, s0, 0xfffc0080
	s_addc_u32 s3, s1, -1
	s_cmp_eq_u32 s55, 12
	s_cselect_b32 s5, s13, s3
	s_cselect_b32 s4, s25, s2
	s_cselect_b32 s3, s23, s39
	s_cselect_b32 s2, s33, s38
	s_add_i32 m0, s6, 0xc000
	ds_read_b128 v[214:217], v178
	ds_read_b128 v[218:221], v178 offset:1024
	ds_read_b128 v[222:225], v178 offset:2048
	ds_read_b128 v[226:229], v178 offset:3072
	ds_read_b128 v[230:233], v178 offset:4096
	ds_read_b128 v[234:237], v178 offset:5120
	ds_read_b128 v[238:241], v178 offset:6144
	ds_read_b128 v[242:245], v178 offset:7168
	global_load_lds_dwordx4 v136, s[0:1]
	s_add_i32 m0, s6, 0xe000
	s_nop 0
	global_load_lds_dwordx4 v138, s[0:1]
	s_waitcnt vmcnt(8)
	s_waitcnt lgkmcnt(0)
	s_barrier
	s_setprio 1
	v_mfma_f32_16x16x32_bf16 v[124:127], v[140:143], v[214:217], v[124:127]
	v_mfma_f32_16x16x32_bf16 v[108:111], v[140:143], v[222:225], v[108:111]
	v_mfma_f32_16x16x32_bf16 v[92:95], v[140:143], v[230:233], v[92:95]
	v_mfma_f32_16x16x32_bf16 v[76:79], v[140:143], v[238:241], v[76:79]
	v_mfma_f32_16x16x32_bf16 v[120:123], v[166:169], v[214:217], v[120:123]
	v_mfma_f32_16x16x32_bf16 v[104:107], v[166:169], v[222:225], v[104:107]
	v_mfma_f32_16x16x32_bf16 v[88:91], v[166:169], v[230:233], v[88:91]
	v_mfma_f32_16x16x32_bf16 v[72:75], v[166:169], v[238:241], v[72:75]
	v_mfma_f32_16x16x32_bf16 v[124:127], v[162:165], v[218:221], v[124:127]
	v_mfma_f32_16x16x32_bf16 v[108:111], v[162:165], v[226:229], v[108:111]
	v_mfma_f32_16x16x32_bf16 v[92:95], v[162:165], v[234:237], v[92:95]
	v_mfma_f32_16x16x32_bf16 v[76:79], v[162:165], v[242:245], v[76:79]
	v_mfma_f32_16x16x32_bf16 v[120:123], v[170:173], v[218:221], v[120:123]
	v_mfma_f32_16x16x32_bf16 v[104:107], v[170:173], v[226:229], v[104:107]
	v_mfma_f32_16x16x32_bf16 v[88:91], v[170:173], v[234:237], v[88:91]
	v_mfma_f32_16x16x32_bf16 v[72:75], v[170:173], v[242:245], v[72:75]
	v_mfma_f32_16x16x32_bf16 v[116:119], v[180:183], v[214:217], v[116:119]
	v_mfma_f32_16x16x32_bf16 v[100:103], v[180:183], v[222:225], v[100:103]
	v_mfma_f32_16x16x32_bf16 v[84:87], v[180:183], v[230:233], v[84:87]
	v_mfma_f32_16x16x32_bf16 v[68:71], v[180:183], v[238:241], v[68:71]
	v_mfma_f32_16x16x32_bf16 v[112:115], v[188:191], v[214:217], v[112:115]
	v_mfma_f32_16x16x32_bf16 v[96:99], v[188:191], v[222:225], v[96:99]
	v_mfma_f32_16x16x32_bf16 v[80:83], v[188:191], v[230:233], v[80:83]
	v_mfma_f32_16x16x32_bf16 v[64:67], v[188:191], v[238:241], v[64:67]
	v_mfma_f32_16x16x32_bf16 v[116:119], v[184:187], v[218:221], v[116:119]
	v_mfma_f32_16x16x32_bf16 v[100:103], v[184:187], v[226:229], v[100:103]
	v_mfma_f32_16x16x32_bf16 v[84:87], v[184:187], v[234:237], v[84:87]
	v_mfma_f32_16x16x32_bf16 v[68:71], v[184:187], v[242:245], v[68:71]
	v_mfma_f32_16x16x32_bf16 v[112:115], v[210:213], v[218:221], v[112:115]
	v_mfma_f32_16x16x32_bf16 v[96:99], v[210:213], v[226:229], v[96:99]
	v_mfma_f32_16x16x32_bf16 v[80:83], v[210:213], v[234:237], v[80:83]
	v_mfma_f32_16x16x32_bf16 v[64:67], v[210:213], v[242:245], v[64:67]
	s_setprio 0
	s_barrier
	s_mov_b32 m0, s31
	s_add_u32 s56, s2, 0x40000
	s_addc_u32 s57, s3, 0
	ds_read_b128 v[214:217], v178 offset:16384
	ds_read_b128 v[218:221], v178 offset:17408
	ds_read_b128 v[222:225], v178 offset:18432
	ds_read_b128 v[226:229], v178 offset:19456
	ds_read_b128 v[230:233], v178 offset:20480
	ds_read_b128 v[234:237], v178 offset:21504
	ds_read_b128 v[238:241], v178 offset:22528
	ds_read_b128 v[242:245], v178 offset:23552
	global_load_lds_dwordx4 v132, s[2:3]
	s_mov_b32 m0, s34
	s_nop 0
	global_load_lds_dwordx4 v128, s[2:3]
	s_mov_b32 m0, s35
	s_nop 0
	global_load_lds_dwordx4 v132, s[56:57]
	s_mov_b32 m0, s40
	s_nop 0
	global_load_lds_dwordx4 v128, s[56:57]
	s_mov_b32 m0, s6
	s_nop 0
	global_load_lds_dwordx4 v134, s[4:5]
	s_mov_b32 m0, s41
	s_nop 0
	global_load_lds_dwordx4 v130, s[4:5]
	s_waitcnt vmcnt(8)
	s_waitcnt lgkmcnt(0)
	s_barrier
	s_setprio 1
	v_mfma_f32_16x16x32_bf16 v[60:63], v[140:143], v[214:217], v[60:63]
	v_mfma_f32_16x16x32_bf16 v[44:47], v[140:143], v[222:225], v[44:47]
	v_mfma_f32_16x16x32_bf16 v[28:31], v[140:143], v[230:233], v[28:31]
	v_mfma_f32_16x16x32_bf16 v[12:15], v[140:143], v[238:241], v[12:15]
	v_mfma_f32_16x16x32_bf16 v[56:59], v[166:169], v[214:217], v[56:59]
	v_mfma_f32_16x16x32_bf16 v[40:43], v[166:169], v[222:225], v[40:43]
	v_mfma_f32_16x16x32_bf16 v[24:27], v[166:169], v[230:233], v[24:27]
	v_mfma_f32_16x16x32_bf16 v[8:11], v[166:169], v[238:241], v[8:11]
	v_mfma_f32_16x16x32_bf16 v[60:63], v[162:165], v[218:221], v[60:63]
	v_mfma_f32_16x16x32_bf16 v[44:47], v[162:165], v[226:229], v[44:47]
	v_mfma_f32_16x16x32_bf16 v[28:31], v[162:165], v[234:237], v[28:31]
	v_mfma_f32_16x16x32_bf16 v[12:15], v[162:165], v[242:245], v[12:15]
	v_mfma_f32_16x16x32_bf16 v[56:59], v[170:173], v[218:221], v[56:59]
	v_mfma_f32_16x16x32_bf16 v[40:43], v[170:173], v[226:229], v[40:43]
	v_mfma_f32_16x16x32_bf16 v[24:27], v[170:173], v[234:237], v[24:27]
	v_mfma_f32_16x16x32_bf16 v[8:11], v[170:173], v[242:245], v[8:11]
	v_mfma_f32_16x16x32_bf16 v[52:55], v[180:183], v[214:217], v[52:55]
	v_mfma_f32_16x16x32_bf16 v[36:39], v[180:183], v[222:225], v[36:39]
	v_mfma_f32_16x16x32_bf16 v[20:23], v[180:183], v[230:233], v[20:23]
	v_mfma_f32_16x16x32_bf16 v[4:7], v[180:183], v[238:241], v[4:7]
	v_mfma_f32_16x16x32_bf16 v[48:51], v[188:191], v[214:217], v[48:51]
	v_mfma_f32_16x16x32_bf16 v[32:35], v[188:191], v[222:225], v[32:35]
	v_mfma_f32_16x16x32_bf16 v[16:19], v[188:191], v[230:233], v[16:19]
	v_mfma_f32_16x16x32_bf16 v[0:3], v[188:191], v[238:241], v[0:3]
	v_mfma_f32_16x16x32_bf16 v[52:55], v[184:187], v[218:221], v[52:55]
	v_mfma_f32_16x16x32_bf16 v[36:39], v[184:187], v[226:229], v[36:39]
	v_mfma_f32_16x16x32_bf16 v[20:23], v[184:187], v[234:237], v[20:23]
	v_mfma_f32_16x16x32_bf16 v[4:7], v[184:187], v[242:245], v[4:7]
	v_mfma_f32_16x16x32_bf16 v[48:51], v[210:213], v[218:221], v[48:51]
	v_mfma_f32_16x16x32_bf16 v[32:35], v[210:213], v[226:229], v[32:35]
	v_mfma_f32_16x16x32_bf16 v[16:19], v[210:213], v[234:237], v[16:19]
	v_mfma_f32_16x16x32_bf16 v[0:3], v[210:213], v[242:245], v[0:3]
	s_setprio 0
	s_barrier
; #define PG8_STAGE(bufoff, gbase, voff) do { _Pragma("unroll") for (int _i = 0; _i < 2; ++_i) \
;         __builtin_amdgcn_global_load_lds((const unsigned*)((const char*)(gbase) + (voff)[_i]), (PG8_LAS unsigned*)(lds + (bufoff) + ldsw + _i * 8192), 16, 0, 0); } while (0)
; #define PG8_LDA(dst, b, h) do { _Pragma("unroll") for (int m = 0; m < 4; ++m) _Pragma("unroll") for (int k = 0; k < 2; ++k) dst[m][k] = *(const PG8_LAS bf16x8*)(lds + PG8_SA(b, h) + aoff + m * 2048 + k * 1024); } while (0)
; #define PG8_LDB(dst, b, h) do { _Pragma("unroll") for (int n = 0; n < 2; ++n) _Pragma("unroll") for (int k = 0; k < 2; ++k) dst[n][k] = *(const PG8_LAS bf16x8*)(lds + PG8_SB(b, h) + boff + n * 2048 + k * 1024); } while (0)
; #define PG8_MMA(ai, bj, At, Bt) do { __builtin_amdgcn_s_setprio(1); _Pragma("unroll") for (int m = 0; m < 4; ++m) _Pragma("unroll") for (int n = 0; n < 2; ++n) _Pragma("unroll") for (int k = 0; k < 2; ++k) \
;         acc[ai][bj][m][n] = __builtin_amdgcn_mfma_f32_16x16x32_bf16(Bt[n][k], At[m][k], acc[ai][bj][m][n], 0, 0, 0); __builtin_amdgcn_s_setprio(0); } while (0)
; #define PG8_WAIT_V(n) asm volatile("s_waitcnt vmcnt(" #n ")" ::: "memory")
; #define PG8_WAIT_L(n) asm volatile("s_waitcnt lgkmcnt(" #n ")" ::: "memory")
; #define PG8_BAR __builtin_amdgcn_s_barrier()
; #define PG8_SCHED __builtin_amdgcn_sched_barrier(0)
; template <class Epi, class Sched, bool ALIGN_EPI = false, bool SP2 = false>
; __device__ __forceinline__ void gemm_phase(PG8_LAS unsigned char* lds, const Gemm g, const Sched& S, const Epi& E) {
;     ...
;             PG8_LDB(B0, 1, 0); PG8_LDB(B1, 1, 1); PG8_SCHED; PG8_LDA(At, 1, 0); PG8_STAGE(PG8_SA(0, 1), a2 + hstep, voffA);
;             PG8_WAIT_V(8); PG8_WAIT_L(0); PG8_BAR; PG8_MMA(0, 0, At, B0); PG8_MMA(0, 1, At, B1); PG8_BAR; PG8_SCHED;
;             PG8_LDA(At, 1, 1); PG8_STAGE(PG8_SB(1, 0), b3, voffB); PG8_STAGE(PG8_SB(1, 1), b3 + hstep, voffB); PG8_STAGE(PG8_SA(1, 0), a3, voffA);
;             PG8_WAIT_V(8); PG8_WAIT_L(0); PG8_BAR; PG8_MMA(1, 0, At, B0); PG8_MMA(1, 1, At, B1); PG8_BAR; PG8_SCHED;
;     ...
;         }
;         if constexpr (ALIGN_EPI) { if (wr == 0) PG8_BAR; }
	ds_read_b128 v[140:143], v254 offset:32768
	ds_read_b128 v[162:165], v254 offset:33792
	ds_read_b128 v[166:169], v254 offset:34816
	ds_read_b128 v[170:173], v254 offset:35840
	ds_read_b128 v[180:183], v254 offset:49152
	ds_read_b128 v[184:187], v254 offset:50176
	ds_read_b128 v[188:191], v254 offset:51200
	ds_read_b128 v[210:213], v254 offset:52224
	s_add_u32 s4, s4, 0x40000
	s_addc_u32 s5, s5, 0
	s_mov_b32 m0, s42
	ds_read_b128 v[214:217], v178 offset:32768
	ds_read_b128 v[218:221], v178 offset:33792
	ds_read_b128 v[222:225], v178 offset:34816
	ds_read_b128 v[226:229], v178 offset:35840
	ds_read_b128 v[230:233], v178 offset:36864
	ds_read_b128 v[234:237], v178 offset:37888
	ds_read_b128 v[238:241], v178 offset:38912
	ds_read_b128 v[242:245], v178 offset:39936
	global_load_lds_dwordx4 v134, s[4:5]
	s_mov_b32 m0, s43
	s_nop 0
	global_load_lds_dwordx4 v130, s[4:5]
	s_waitcnt vmcnt(8)
	s_waitcnt lgkmcnt(0)
	s_barrier
	s_setprio 1
	v_mfma_f32_16x16x32_bf16 v[124:127], v[140:143], v[214:217], v[124:127]
	v_mfma_f32_16x16x32_bf16 v[108:111], v[140:143], v[222:225], v[108:111]
	v_mfma_f32_16x16x32_bf16 v[92:95], v[140:143], v[230:233], v[92:95]
	v_mfma_f32_16x16x32_bf16 v[76:79], v[140:143], v[238:241], v[76:79]
	v_mfma_f32_16x16x32_bf16 v[120:123], v[166:169], v[214:217], v[120:123]
	v_mfma_f32_16x16x32_bf16 v[104:107], v[166:169], v[222:225], v[104:107]
	v_mfma_f32_16x16x32_bf16 v[88:91], v[166:169], v[230:233], v[88:91]
	v_mfma_f32_16x16x32_bf16 v[72:75], v[166:169], v[238:241], v[72:75]
	v_mfma_f32_16x16x32_bf16 v[124:127], v[162:165], v[218:221], v[124:127]
	v_mfma_f32_16x16x32_bf16 v[108:111], v[162:165], v[226:229], v[108:111]
	v_mfma_f32_16x16x32_bf16 v[92:95], v[162:165], v[234:237], v[92:95]
	v_mfma_f32_16x16x32_bf16 v[76:79], v[162:165], v[242:245], v[76:79]
	v_mfma_f32_16x16x32_bf16 v[120:123], v[170:173], v[218:221], v[120:123]
	v_mfma_f32_16x16x32_bf16 v[104:107], v[170:173], v[226:229], v[104:107]
	v_mfma_f32_16x16x32_bf16 v[88:91], v[170:173], v[234:237], v[88:91]
	v_mfma_f32_16x16x32_bf16 v[72:75], v[170:173], v[242:245], v[72:75]
	v_mfma_f32_16x16x32_bf16 v[116:119], v[180:183], v[214:217], v[116:119]
	v_mfma_f32_16x16x32_bf16 v[100:103], v[180:183], v[222:225], v[100:103]
	v_mfma_f32_16x16x32_bf16 v[84:87], v[180:183], v[230:233], v[84:87]
	v_mfma_f32_16x16x32_bf16 v[68:71], v[180:183], v[238:241], v[68:71]
	v_mfma_f32_16x16x32_bf16 v[112:115], v[188:191], v[214:217], v[112:115]
	v_mfma_f32_16x16x32_bf16 v[96:99], v[188:191], v[222:225], v[96:99]
	v_mfma_f32_16x16x32_bf16 v[80:83], v[188:191], v[230:233], v[80:83]
	v_mfma_f32_16x16x32_bf16 v[64:67], v[188:191], v[238:241], v[64:67]
	v_mfma_f32_16x16x32_bf16 v[116:119], v[184:187], v[218:221], v[116:119]
	v_mfma_f32_16x16x32_bf16 v[100:103], v[184:187], v[226:229], v[100:103]
	v_mfma_f32_16x16x32_bf16 v[84:87], v[184:187], v[234:237], v[84:87]
	v_mfma_f32_16x16x32_bf16 v[68:71], v[184:187], v[242:245], v[68:71]
	v_mfma_f32_16x16x32_bf16 v[112:115], v[210:213], v[218:221], v[112:115]
	v_mfma_f32_16x16x32_bf16 v[96:99], v[210:213], v[226:229], v[96:99]
	v_mfma_f32_16x16x32_bf16 v[80:83], v[210:213], v[234:237], v[80:83]
	v_mfma_f32_16x16x32_bf16 v[64:67], v[210:213], v[242:245], v[64:67]
	s_setprio 0
	s_barrier
	s_mov_b32 m0, s48
	s_add_u32 s2, s2, 0x40080
	s_addc_u32 s3, s3, 0
	ds_read_b128 v[214:217], v178 offset:49152
	ds_read_b128 v[218:221], v178 offset:50176
	ds_read_b128 v[222:225], v178 offset:51200
	ds_read_b128 v[226:229], v178 offset:52224
	ds_read_b128 v[230:233], v178 offset:53248
	ds_read_b128 v[234:237], v178 offset:54272
	ds_read_b128 v[238:241], v178 offset:55296
	ds_read_b128 v[242:245], v178 offset:56320
	s_add_u32 s98, s2, 0xfffc0000
	s_addc_u32 s99, s3, -1
	global_load_lds_dwordx4 v132, s[98:99]
	s_mov_b32 m0, s49
	s_nop 0
	global_load_lds_dwordx4 v128, s[98:99]
	s_mov_b32 m0, s52
	s_nop 0
	global_load_lds_dwordx4 v132, s[2:3]
	s_mov_b32 m0, s53
	s_nop 0
	global_load_lds_dwordx4 v128, s[2:3]
	s_mov_b32 m0, s50
	s_nop 0
	s_add_u32 s100, s4, 0xfffc0080
	s_addc_u32 s101, s5, -1
	global_load_lds_dwordx4 v134, s[100:101]
	s_mov_b32 m0, s51
	s_nop 0
	global_load_lds_dwordx4 v130, s[100:101]
	s_waitcnt vmcnt(8)
	s_waitcnt lgkmcnt(0)
	s_barrier
	s_setprio 1
	v_mfma_f32_16x16x32_bf16 v[60:63], v[140:143], v[214:217], v[60:63]
	v_mfma_f32_16x16x32_bf16 v[44:47], v[140:143], v[222:225], v[44:47]
	v_mfma_f32_16x16x32_bf16 v[28:31], v[140:143], v[230:233], v[28:31]
	v_mfma_f32_16x16x32_bf16 v[12:15], v[140:143], v[238:241], v[12:15]
	v_mfma_f32_16x16x32_bf16 v[56:59], v[166:169], v[214:217], v[56:59]
	v_mfma_f32_16x16x32_bf16 v[40:43], v[166:169], v[222:225], v[40:43]
	v_mfma_f32_16x16x32_bf16 v[24:27], v[166:169], v[230:233], v[24:27]
	v_mfma_f32_16x16x32_bf16 v[8:11], v[166:169], v[238:241], v[8:11]
	v_mfma_f32_16x16x32_bf16 v[60:63], v[162:165], v[218:221], v[60:63]
	v_mfma_f32_16x16x32_bf16 v[44:47], v[162:165], v[226:229], v[44:47]
	v_mfma_f32_16x16x32_bf16 v[28:31], v[162:165], v[234:237], v[28:31]
	v_mfma_f32_16x16x32_bf16 v[12:15], v[162:165], v[242:245], v[12:15]
	v_mfma_f32_16x16x32_bf16 v[56:59], v[170:173], v[218:221], v[56:59]
	v_mfma_f32_16x16x32_bf16 v[40:43], v[170:173], v[226:229], v[40:43]
	v_mfma_f32_16x16x32_bf16 v[24:27], v[170:173], v[234:237], v[24:27]
	v_mfma_f32_16x16x32_bf16 v[8:11], v[170:173], v[242:245], v[8:11]
	v_mfma_f32_16x16x32_bf16 v[52:55], v[180:183], v[214:217], v[52:55]
	v_mfma_f32_16x16x32_bf16 v[36:39], v[180:183], v[222:225], v[36:39]
	v_mfma_f32_16x16x32_bf16 v[20:23], v[180:183], v[230:233], v[20:23]
	v_mfma_f32_16x16x32_bf16 v[4:7], v[180:183], v[238:241], v[4:7]
	v_mfma_f32_16x16x32_bf16 v[48:51], v[188:191], v[214:217], v[48:51]
	v_mfma_f32_16x16x32_bf16 v[32:35], v[188:191], v[222:225], v[32:35]
	v_mfma_f32_16x16x32_bf16 v[16:19], v[188:191], v[230:233], v[16:19]
	v_mfma_f32_16x16x32_bf16 v[0:3], v[188:191], v[238:241], v[0:3]
	v_mfma_f32_16x16x32_bf16 v[52:55], v[184:187], v[218:221], v[52:55]
	v_mfma_f32_16x16x32_bf16 v[36:39], v[184:187], v[226:229], v[36:39]
	v_mfma_f32_16x16x32_bf16 v[20:23], v[184:187], v[234:237], v[20:23]
	v_mfma_f32_16x16x32_bf16 v[4:7], v[184:187], v[242:245], v[4:7]
	v_mfma_f32_16x16x32_bf16 v[48:51], v[210:213], v[218:221], v[48:51]
	v_mfma_f32_16x16x32_bf16 v[32:35], v[210:213], v[226:229], v[32:35]
	v_mfma_f32_16x16x32_bf16 v[16:19], v[210:213], v[234:237], v[16:19]
	v_mfma_f32_16x16x32_bf16 v[0:3], v[210:213], v[242:245], v[0:3]
	s_setprio 0
	s_barrier
	s_add_i32 s55, s55, 2
	s_add_u32 s0, s0, 0x100
	s_addc_u32 s1, s1, 0
	s_add_u32 s38, s38, 0x100
	s_addc_u32 s39, s39, 0
	s_cmp_gt_u32 s55, 13
	s_cbranch_scc0 .LBB0_749
	s_and_b64 vcc, exec, s[18:19]
	s_cbranch_vccz .LBB0_752
	s_barrier

; #define PG8_STAGE(bufoff, gbase, voff) do { _Pragma("unroll") for (int _i = 0; _i < 2; ++_i) \
;         __builtin_amdgcn_global_load_lds((const unsigned*)((const char*)(gbase) + (voff)[_i]), (PG8_LAS unsigned*)(lds + (bufoff) + ldsw + _i * 8192), 16, 0, 0); } while (0)
; #define PG8_LDA(dst, b, h) do { _Pragma("unroll") for (int m = 0; m < 4; ++m) _Pragma("unroll") for (int k = 0; k < 2; ++k) dst[m][k] = *(const PG8_LAS bf16x8*)(lds + PG8_SA(b, h) + aoff + m * 2048 + k * 1024); } while (0)
; #define PG8_LDB(dst, b, h) do { _Pragma("unroll") for (int n = 0; n < 2; ++n) _Pragma("unroll") for (int k = 0; k < 2; ++k) dst[n][k] = *(const PG8_LAS bf16x8*)(lds + PG8_SB(b, h) + boff + n * 2048 + k * 1024); } while (0)
; #define PG8_MMA(ai, bj, At, Bt) do { __builtin_amdgcn_s_setprio(1); _Pragma("unroll") for (int m = 0; m < 4; ++m) _Pragma("unroll") for (int n = 0; n < 2; ++n) _Pragma("unroll") for (int k = 0; k < 2; ++k) \
;         acc[ai][bj][m][n] = __builtin_amdgcn_mfma_f32_16x16x32_bf16(Bt[n][k], At[m][k], acc[ai][bj][m][n], 0, 0, 0); __builtin_amdgcn_s_setprio(0); } while (0)
; #define PG8_WAIT_V(n) asm volatile("s_waitcnt vmcnt(" #n ")" ::: "memory")
; #define PG8_WAIT_L(n) asm volatile("s_waitcnt lgkmcnt(" #n ")" ::: "memory")
; template <class Epi, class Sched, bool ALIGN_EPI = false, bool SP2 = false>
; __device__ __forceinline__ void gemm_phase(PG8_LAS unsigned char* lds, const Gemm g, const Sched& S, const Epi& E) {
;     ...
;             const bool last = (t == nt - 2);
;             const char* a1 = cA + (size_t)(t + 1) * kstep;
;             const char* a2 = last ? nA : cA + (size_t)(t + 2) * kstep; const char* b2 = last ? nB : cB + (size_t)(t + 2) * kstep;
;             const char* a3 = a2 + kstep; const char* b3 = b2 + kstep;
;             if (last && has_next) S.a_ready(nxt);
;             if constexpr (SP2) {
;             PG8_LDB(B0, 0, 0); PG8_LDB(B1, 0, 1); PG8_SCHED; PG8_LDA(At, 0, 0); PG8_STAGE(PG8_SA(1, 1), a1 + hstep, voffA);
;             PG8_WAIT_V(8); PG8_WAIT_L(0); PG8_BAR; PG8_MMA(0, 0, At, B0); PG8_MMA(0, 1, At, B1); PG8_BAR; PG8_SCHED;
;             PG8_LDA(At, 0, 1); PG8_STAGE(PG8_SB(0, 0), b2, voffB); PG8_STAGE(PG8_SB(0, 1), b2 + hstep, voffB); PG8_STAGE(PG8_SA(0, 0), a2, voffA);
;             PG8_WAIT_V(8); PG8_WAIT_L(0); PG8_BAR; PG8_MMA(1, 0, At, B0); PG8_MMA(1, 1, At, B1); PG8_BAR; PG8_SCHED;
.Labi_peel:
	s_waitcnt lgkmcnt(0)
	ds_read_b128 v[140:143], v254
	ds_read_b128 v[162:165], v254 offset:1024
	ds_read_b128 v[166:169], v254 offset:2048
	ds_read_b128 v[176:179], v254 offset:3072
	ds_read_b128 v[180:183], v254 offset:16384
	ds_read_b128 v[184:187], v254 offset:17408
	ds_read_b128 v[188:191], v254 offset:18432
	ds_read_b128 v[210:213], v254 offset:19456
	s_add_u32 s2, s0, 0xfffc0080
	s_addc_u32 s3, s1, -1
	s_cmp_eq_u32 s52, 12
	s_cselect_b32 s5, s17, s3
	s_cselect_b32 s4, s48, s2
	s_cselect_b32 s3, s15, s51
	s_cselect_b32 s2, s49, s50
	s_add_i32 m0, s6, 0xc000
	ds_read_b128 v[214:217], v173
	ds_read_b128 v[218:221], v173 offset:1024
	ds_read_b128 v[222:225], v173 offset:2048
	ds_read_b128 v[226:229], v173 offset:3072
	ds_read_b128 v[230:233], v173 offset:4096
	ds_read_b128 v[234:237], v173 offset:5120
	ds_read_b128 v[238:241], v173 offset:6144
	ds_read_b128 v[242:245], v173 offset:7168
	global_load_lds_dwordx4 v136, s[0:1]
	s_add_i32 m0, s6, 0xe000
	s_nop 0
	global_load_lds_dwordx4 v138, s[0:1]
	s_waitcnt vmcnt(8)
	s_waitcnt lgkmcnt(0)
	s_barrier
	s_setprio 1
	v_mfma_f32_16x16x32_bf16 v[124:127], v[140:143], v[214:217], 0
	v_mfma_f32_16x16x32_bf16 v[112:115], v[140:143], v[222:225], 0
	v_mfma_f32_16x16x32_bf16 v[96:99], v[140:143], v[230:233], 0
	v_mfma_f32_16x16x32_bf16 v[80:83], v[140:143], v[238:241], 0
	v_mfma_f32_16x16x32_bf16 v[120:123], v[166:169], v[214:217], 0
	v_mfma_f32_16x16x32_bf16 v[104:107], v[166:169], v[222:225], 0
	v_mfma_f32_16x16x32_bf16 v[88:91], v[166:169], v[230:233], 0
	v_mfma_f32_16x16x32_bf16 v[72:75], v[166:169], v[238:241], 0
	v_mfma_f32_16x16x32_bf16 v[124:127], v[162:165], v[218:221], v[124:127]
	v_mfma_f32_16x16x32_bf16 v[112:115], v[162:165], v[226:229], v[112:115]
	v_mfma_f32_16x16x32_bf16 v[96:99], v[162:165], v[234:237], v[96:99]
	v_mfma_f32_16x16x32_bf16 v[80:83], v[162:165], v[242:245], v[80:83]
	v_mfma_f32_16x16x32_bf16 v[120:123], v[176:179], v[218:221], v[120:123]
	v_mfma_f32_16x16x32_bf16 v[104:107], v[176:179], v[226:229], v[104:107]
	v_mfma_f32_16x16x32_bf16 v[88:91], v[176:179], v[234:237], v[88:91]
	v_mfma_f32_16x16x32_bf16 v[72:75], v[176:179], v[242:245], v[72:75]
	v_mfma_f32_16x16x32_bf16 v[116:119], v[180:183], v[214:217], 0
	v_mfma_f32_16x16x32_bf16 v[100:103], v[180:183], v[222:225], 0
	v_mfma_f32_16x16x32_bf16 v[84:87], v[180:183], v[230:233], 0
	v_mfma_f32_16x16x32_bf16 v[68:71], v[180:183], v[238:241], 0
	v_mfma_f32_16x16x32_bf16 v[108:111], v[188:191], v[214:217], 0
	v_mfma_f32_16x16x32_bf16 v[92:95], v[188:191], v[222:225], 0
	v_mfma_f32_16x16x32_bf16 v[76:79], v[188:191], v[230:233], 0
	v_mfma_f32_16x16x32_bf16 v[64:67], v[188:191], v[238:241], 0
	v_mfma_f32_16x16x32_bf16 v[116:119], v[184:187], v[218:221], v[116:119]
	v_mfma_f32_16x16x32_bf16 v[100:103], v[184:187], v[226:229], v[100:103]
	v_mfma_f32_16x16x32_bf16 v[84:87], v[184:187], v[234:237], v[84:87]
	v_mfma_f32_16x16x32_bf16 v[68:71], v[184:187], v[242:245], v[68:71]
	v_mfma_f32_16x16x32_bf16 v[108:111], v[210:213], v[218:221], v[108:111]
	v_mfma_f32_16x16x32_bf16 v[92:95], v[210:213], v[226:229], v[92:95]
	v_mfma_f32_16x16x32_bf16 v[76:79], v[210:213], v[234:237], v[76:79]
	v_mfma_f32_16x16x32_bf16 v[64:67], v[210:213], v[242:245], v[64:67]
	s_setprio 0
	s_barrier
	s_mov_b32 m0, s27
	s_add_u32 s54, s2, 0x40000
	s_addc_u32 s55, s3, 0
	ds_read_b128 v[214:217], v173 offset:16384
	ds_read_b128 v[218:221], v173 offset:17408
	ds_read_b128 v[222:225], v173 offset:18432
	ds_read_b128 v[226:229], v173 offset:19456
	ds_read_b128 v[230:233], v173 offset:20480
	ds_read_b128 v[234:237], v173 offset:21504
	ds_read_b128 v[238:241], v173 offset:22528
	ds_read_b128 v[242:245], v173 offset:23552
	global_load_lds_dwordx4 v132, s[2:3]
	s_mov_b32 m0, s28
	s_nop 0
	global_load_lds_dwordx4 v128, s[2:3]
	s_mov_b32 m0, s29
	s_nop 0
	global_load_lds_dwordx4 v132, s[54:55]
	s_mov_b32 m0, s30
	s_nop 0
	global_load_lds_dwordx4 v128, s[54:55]
	s_mov_b32 m0, s6
	s_nop 0
	global_load_lds_dwordx4 v134, s[4:5]
	s_mov_b32 m0, s31
	s_nop 0
	global_load_lds_dwordx4 v130, s[4:5]
	s_waitcnt vmcnt(8)
	s_waitcnt lgkmcnt(0)
	s_barrier
	s_setprio 1
	v_mfma_f32_16x16x32_bf16 v[60:63], v[140:143], v[214:217], 0
	v_mfma_f32_16x16x32_bf16 v[48:51], v[140:143], v[222:225], 0
	v_mfma_f32_16x16x32_bf16 v[32:35], v[140:143], v[230:233], 0
	v_mfma_f32_16x16x32_bf16 v[16:19], v[140:143], v[238:241], 0
	v_mfma_f32_16x16x32_bf16 v[56:59], v[166:169], v[214:217], 0
	v_mfma_f32_16x16x32_bf16 v[40:43], v[166:169], v[222:225], 0
	v_mfma_f32_16x16x32_bf16 v[24:27], v[166:169], v[230:233], 0
	v_mfma_f32_16x16x32_bf16 v[8:11], v[166:169], v[238:241], 0
	v_mfma_f32_16x16x32_bf16 v[60:63], v[162:165], v[218:221], v[60:63]
	v_mfma_f32_16x16x32_bf16 v[48:51], v[162:165], v[226:229], v[48:51]
	v_mfma_f32_16x16x32_bf16 v[32:35], v[162:165], v[234:237], v[32:35]
	v_mfma_f32_16x16x32_bf16 v[16:19], v[162:165], v[242:245], v[16:19]
	v_mfma_f32_16x16x32_bf16 v[56:59], v[176:179], v[218:221], v[56:59]
	v_mfma_f32_16x16x32_bf16 v[40:43], v[176:179], v[226:229], v[40:43]
	v_mfma_f32_16x16x32_bf16 v[24:27], v[176:179], v[234:237], v[24:27]
	v_mfma_f32_16x16x32_bf16 v[8:11], v[176:179], v[242:245], v[8:11]
	v_mfma_f32_16x16x32_bf16 v[52:55], v[180:183], v[214:217], 0
	v_mfma_f32_16x16x32_bf16 v[36:39], v[180:183], v[222:225], 0
	v_mfma_f32_16x16x32_bf16 v[20:23], v[180:183], v[230:233], 0
	v_mfma_f32_16x16x32_bf16 v[4:7], v[180:183], v[238:241], 0
	v_mfma_f32_16x16x32_bf16 v[44:47], v[188:191], v[214:217], 0
	v_mfma_f32_16x16x32_bf16 v[28:31], v[188:191], v[222:225], 0
	v_mfma_f32_16x16x32_bf16 v[12:15], v[188:191], v[230:233], 0
	v_mfma_f32_16x16x32_bf16 v[0:3], v[188:191], v[238:241], 0
	v_mfma_f32_16x16x32_bf16 v[52:55], v[184:187], v[218:221], v[52:55]
	v_mfma_f32_16x16x32_bf16 v[36:39], v[184:187], v[226:229], v[36:39]
	v_mfma_f32_16x16x32_bf16 v[20:23], v[184:187], v[234:237], v[20:23]
	v_mfma_f32_16x16x32_bf16 v[4:7], v[184:187], v[242:245], v[4:7]
	v_mfma_f32_16x16x32_bf16 v[44:47], v[210:213], v[218:221], v[44:47]
	v_mfma_f32_16x16x32_bf16 v[28:31], v[210:213], v[226:229], v[28:31]
	v_mfma_f32_16x16x32_bf16 v[12:15], v[210:213], v[234:237], v[12:15]
	v_mfma_f32_16x16x32_bf16 v[0:3], v[210:213], v[242:245], v[0:3]
	s_setprio 0
	s_barrier
; #define PG8_STAGE(bufoff, gbase, voff) do { _Pragma("unroll") for (int _i = 0; _i < 2; ++_i) \
;         __builtin_amdgcn_global_load_lds((const unsigned*)((const char*)(gbase) + (voff)[_i]), (PG8_LAS unsigned*)(lds + (bufoff) + ldsw + _i * 8192), 16, 0, 0); } while (0)
; #define PG8_LDA(dst, b, h) do { _Pragma("unroll") for (int m = 0; m < 4; ++m) _Pragma("unroll") for (int k = 0; k < 2; ++k) dst[m][k] = *(const PG8_LAS bf16x8*)(lds + PG8_SA(b, h) + aoff + m * 2048 + k * 1024); } while (0)
; #define PG8_LDB(dst, b, h) do { _Pragma("unroll") for (int n = 0; n < 2; ++n) _Pragma("unroll") for (int k = 0; k < 2; ++k) dst[n][k] = *(const PG8_LAS bf16x8*)(lds + PG8_SB(b, h) + boff + n * 2048 + k * 1024); } while (0)
; #define PG8_MMA(ai, bj, At, Bt) do { __builtin_amdgcn_s_setprio(1); _Pragma("unroll") for (int m = 0; m < 4; ++m) _Pragma("unroll") for (int n = 0; n < 2; ++n) _Pragma("unroll") for (int k = 0; k < 2; ++k) \
;         acc[ai][bj][m][n] = __builtin_amdgcn_mfma_f32_16x16x32_bf16(Bt[n][k], At[m][k], acc[ai][bj][m][n], 0, 0, 0); __builtin_amdgcn_s_setprio(0); } while (0)
; #define PG8_WAIT_V(n) asm volatile("s_waitcnt vmcnt(" #n ")" ::: "memory")
; #define PG8_WAIT_L(n) asm volatile("s_waitcnt lgkmcnt(" #n ")" ::: "memory")
; #define PG8_BAR __builtin_amdgcn_s_barrier()
; #define PG8_SCHED __builtin_amdgcn_sched_barrier(0)
; template <class Epi, class Sched, bool ALIGN_EPI = false, bool SP2 = false>
; __device__ __forceinline__ void gemm_phase(PG8_LAS unsigned char* lds, const Gemm g, const Sched& S, const Epi& E) {
;     ...
;             PG8_LDB(B0, 1, 0); PG8_LDB(B1, 1, 1); PG8_SCHED; PG8_LDA(At, 1, 0); PG8_STAGE(PG8_SA(0, 1), a2 + hstep, voffA);
;             PG8_WAIT_V(8); PG8_WAIT_L(0); PG8_BAR; PG8_MMA(0, 0, At, B0); PG8_MMA(0, 1, At, B1); PG8_BAR; PG8_SCHED;
;             PG8_LDA(At, 1, 1); PG8_STAGE(PG8_SB(1, 0), b3, voffB); PG8_STAGE(PG8_SB(1, 1), b3 + hstep, voffB); PG8_STAGE(PG8_SA(1, 0), a3, voffA);
;             PG8_WAIT_V(8); PG8_WAIT_L(0); PG8_BAR; PG8_MMA(1, 0, At, B0); PG8_MMA(1, 1, At, B1); PG8_BAR; PG8_SCHED;
	ds_read_b128 v[140:143], v254 offset:32768
	ds_read_b128 v[162:165], v254 offset:33792
	ds_read_b128 v[166:169], v254 offset:34816
	ds_read_b128 v[176:179], v254 offset:35840
	ds_read_b128 v[180:183], v254 offset:49152
	ds_read_b128 v[184:187], v254 offset:50176
	ds_read_b128 v[188:191], v254 offset:51200
	ds_read_b128 v[210:213], v254 offset:52224
	s_add_u32 s4, s4, 0x40000
	s_addc_u32 s5, s5, 0
	s_mov_b32 m0, s33
	ds_read_b128 v[214:217], v173 offset:32768
	ds_read_b128 v[218:221], v173 offset:33792
	ds_read_b128 v[222:225], v173 offset:34816
	ds_read_b128 v[226:229], v173 offset:35840
	ds_read_b128 v[230:233], v173 offset:36864
	ds_read_b128 v[234:237], v173 offset:37888
	ds_read_b128 v[238:241], v173 offset:38912
	ds_read_b128 v[242:245], v173 offset:39936
	global_load_lds_dwordx4 v134, s[4:5]
	s_mov_b32 m0, s34
	s_nop 0
	global_load_lds_dwordx4 v130, s[4:5]
	s_waitcnt vmcnt(8)
	s_waitcnt lgkmcnt(0)
	s_barrier
	s_setprio 1
	v_mfma_f32_16x16x32_bf16 v[124:127], v[140:143], v[214:217], v[124:127]
	v_mfma_f32_16x16x32_bf16 v[112:115], v[140:143], v[222:225], v[112:115]
	v_mfma_f32_16x16x32_bf16 v[96:99], v[140:143], v[230:233], v[96:99]
	v_mfma_f32_16x16x32_bf16 v[80:83], v[140:143], v[238:241], v[80:83]
	v_mfma_f32_16x16x32_bf16 v[120:123], v[166:169], v[214:217], v[120:123]
	v_mfma_f32_16x16x32_bf16 v[104:107], v[166:169], v[222:225], v[104:107]
	v_mfma_f32_16x16x32_bf16 v[88:91], v[166:169], v[230:233], v[88:91]
	v_mfma_f32_16x16x32_bf16 v[72:75], v[166:169], v[238:241], v[72:75]
	v_mfma_f32_16x16x32_bf16 v[124:127], v[162:165], v[218:221], v[124:127]
	v_mfma_f32_16x16x32_bf16 v[112:115], v[162:165], v[226:229], v[112:115]
	v_mfma_f32_16x16x32_bf16 v[96:99], v[162:165], v[234:237], v[96:99]
	v_mfma_f32_16x16x32_bf16 v[80:83], v[162:165], v[242:245], v[80:83]
	v_mfma_f32_16x16x32_bf16 v[120:123], v[176:179], v[218:221], v[120:123]
	v_mfma_f32_16x16x32_bf16 v[104:107], v[176:179], v[226:229], v[104:107]
	v_mfma_f32_16x16x32_bf16 v[88:91], v[176:179], v[234:237], v[88:91]
	v_mfma_f32_16x16x32_bf16 v[72:75], v[176:179], v[242:245], v[72:75]
	v_mfma_f32_16x16x32_bf16 v[116:119], v[180:183], v[214:217], v[116:119]
	v_mfma_f32_16x16x32_bf16 v[100:103], v[180:183], v[222:225], v[100:103]
	v_mfma_f32_16x16x32_bf16 v[84:87], v[180:183], v[230:233], v[84:87]
	v_mfma_f32_16x16x32_bf16 v[68:71], v[180:183], v[238:241], v[68:71]
	v_mfma_f32_16x16x32_bf16 v[108:111], v[188:191], v[214:217], v[108:111]
	v_mfma_f32_16x16x32_bf16 v[92:95], v[188:191], v[222:225], v[92:95]
	v_mfma_f32_16x16x32_bf16 v[76:79], v[188:191], v[230:233], v[76:79]
	v_mfma_f32_16x16x32_bf16 v[64:67], v[188:191], v[238:241], v[64:67]
	v_mfma_f32_16x16x32_bf16 v[116:119], v[184:187], v[218:221], v[116:119]
	v_mfma_f32_16x16x32_bf16 v[100:103], v[184:187], v[226:229], v[100:103]
	v_mfma_f32_16x16x32_bf16 v[84:87], v[184:187], v[234:237], v[84:87]
	v_mfma_f32_16x16x32_bf16 v[68:71], v[184:187], v[242:245], v[68:71]
	v_mfma_f32_16x16x32_bf16 v[108:111], v[210:213], v[218:221], v[108:111]
	v_mfma_f32_16x16x32_bf16 v[92:95], v[210:213], v[226:229], v[92:95]
	v_mfma_f32_16x16x32_bf16 v[76:79], v[210:213], v[234:237], v[76:79]
	v_mfma_f32_16x16x32_bf16 v[64:67], v[210:213], v[242:245], v[64:67]
	s_setprio 0
	s_barrier
	s_mov_b32 m0, s37
	s_add_u32 s2, s2, 0x40080
	s_addc_u32 s3, s3, 0
	ds_read_b128 v[214:217], v173 offset:49152
	ds_read_b128 v[218:221], v173 offset:50176
	ds_read_b128 v[222:225], v173 offset:51200
	ds_read_b128 v[226:229], v173 offset:52224
	ds_read_b128 v[230:233], v173 offset:53248
	ds_read_b128 v[234:237], v173 offset:54272
	ds_read_b128 v[238:241], v173 offset:55296
	ds_read_b128 v[242:245], v173 offset:56320
	s_add_u32 s98, s2, 0xfffc0000
	s_addc_u32 s99, s3, -1
	global_load_lds_dwordx4 v132, s[98:99]
	s_mov_b32 m0, s38
	s_nop 0
	global_load_lds_dwordx4 v128, s[98:99]
	s_mov_b32 m0, s41
	s_nop 0
	global_load_lds_dwordx4 v132, s[2:3]
	s_mov_b32 m0, s42
	s_nop 0
	global_load_lds_dwordx4 v128, s[2:3]
	s_mov_b32 m0, s39
	s_nop 0
	s_add_u32 s100, s4, 0xfffc0080
	s_addc_u32 s101, s5, -1
	global_load_lds_dwordx4 v134, s[100:101]
	s_mov_b32 m0, s40
	s_nop 0
	global_load_lds_dwordx4 v130, s[100:101]
	s_waitcnt vmcnt(8)
	s_waitcnt lgkmcnt(0)
	s_barrier
	s_setprio 1
	v_mfma_f32_16x16x32_bf16 v[60:63], v[140:143], v[214:217], v[60:63]
	v_mfma_f32_16x16x32_bf16 v[48:51], v[140:143], v[222:225], v[48:51]
	v_mfma_f32_16x16x32_bf16 v[32:35], v[140:143], v[230:233], v[32:35]
	v_mfma_f32_16x16x32_bf16 v[16:19], v[140:143], v[238:241], v[16:19]
	v_mfma_f32_16x16x32_bf16 v[56:59], v[166:169], v[214:217], v[56:59]
	v_mfma_f32_16x16x32_bf16 v[40:43], v[166:169], v[222:225], v[40:43]
	v_mfma_f32_16x16x32_bf16 v[24:27], v[166:169], v[230:233], v[24:27]
	v_mfma_f32_16x16x32_bf16 v[8:11], v[166:169], v[238:241], v[8:11]
	v_mfma_f32_16x16x32_bf16 v[60:63], v[162:165], v[218:221], v[60:63]
	v_mfma_f32_16x16x32_bf16 v[48:51], v[162:165], v[226:229], v[48:51]
	v_mfma_f32_16x16x32_bf16 v[32:35], v[162:165], v[234:237], v[32:35]
	v_mfma_f32_16x16x32_bf16 v[16:19], v[162:165], v[242:245], v[16:19]
	v_mfma_f32_16x16x32_bf16 v[56:59], v[176:179], v[218:221], v[56:59]
	v_mfma_f32_16x16x32_bf16 v[40:43], v[176:179], v[226:229], v[40:43]
	v_mfma_f32_16x16x32_bf16 v[24:27], v[176:179], v[234:237], v[24:27]
	v_mfma_f32_16x16x32_bf16 v[8:11], v[176:179], v[242:245], v[8:11]
	v_mfma_f32_16x16x32_bf16 v[52:55], v[180:183], v[214:217], v[52:55]
	v_mfma_f32_16x16x32_bf16 v[36:39], v[180:183], v[222:225], v[36:39]
	v_mfma_f32_16x16x32_bf16 v[20:23], v[180:183], v[230:233], v[20:23]
	v_mfma_f32_16x16x32_bf16 v[4:7], v[180:183], v[238:241], v[4:7]
	v_mfma_f32_16x16x32_bf16 v[44:47], v[188:191], v[214:217], v[44:47]
	v_mfma_f32_16x16x32_bf16 v[28:31], v[188:191], v[222:225], v[28:31]
	v_mfma_f32_16x16x32_bf16 v[12:15], v[188:191], v[230:233], v[12:15]
	v_mfma_f32_16x16x32_bf16 v[0:3], v[188:191], v[238:241], v[0:3]
	v_mfma_f32_16x16x32_bf16 v[52:55], v[184:187], v[218:221], v[52:55]
	v_mfma_f32_16x16x32_bf16 v[36:39], v[184:187], v[226:229], v[36:39]
	v_mfma_f32_16x16x32_bf16 v[20:23], v[184:187], v[234:237], v[20:23]
	v_mfma_f32_16x16x32_bf16 v[4:7], v[184:187], v[242:245], v[4:7]
	v_mfma_f32_16x16x32_bf16 v[44:47], v[210:213], v[218:221], v[44:47]
	v_mfma_f32_16x16x32_bf16 v[28:31], v[210:213], v[226:229], v[28:31]
	v_mfma_f32_16x16x32_bf16 v[12:15], v[210:213], v[234:237], v[12:15]
	v_mfma_f32_16x16x32_bf16 v[0:3], v[210:213], v[242:245], v[0:3]
	s_setprio 0
	s_barrier
	s_add_i32 s52, s52, 2
	s_add_u32 s0, s0, 0x100
	s_addc_u32 s1, s1, 0
	s_add_u32 s50, s50, 0x100
	s_addc_u32 s51, s51, 0
	s_cmp_gt_u32 s52, 13
; #define PG8_STAGE(bufoff, gbase, voff) do { _Pragma("unroll") for (int _i = 0; _i < 2; ++_i) \
;         __builtin_amdgcn_global_load_lds((const unsigned*)((const char*)(gbase) + (voff)[_i]), (PG8_LAS unsigned*)(lds + (bufoff) + ldsw + _i * 8192), 16, 0, 0); } while (0)
; #define PG8_LDA(dst, b, h) do { _Pragma("unroll") for (int m = 0; m < 4; ++m) _Pragma("unroll") for (int k = 0; k < 2; ++k) dst[m][k] = *(const PG8_LAS bf16x8*)(lds + PG8_SA(b, h) + aoff + m * 2048 + k * 1024); } while (0)
; #define PG8_LDB(dst, b, h) do { _Pragma("unroll") for (int n = 0; n < 2; ++n) _Pragma("unroll") for (int k = 0; k < 2; ++k) dst[n][k] = *(const PG8_LAS bf16x8*)(lds + PG8_SB(b, h) + boff + n * 2048 + k * 1024); } while (0)
; #define PG8_MMA(ai, bj, At, Bt) do { __builtin_amdgcn_s_setprio(1); _Pragma("unroll") for (int m = 0; m < 4; ++m) _Pragma("unroll") for (int n = 0; n < 2; ++n) _Pragma("unroll") for (int k = 0; k < 2; ++k) \
;         acc[ai][bj][m][n] = __builtin_amdgcn_mfma_f32_16x16x32_bf16(Bt[n][k], At[m][k], acc[ai][bj][m][n], 0, 0, 0); __builtin_amdgcn_s_setprio(0); } while (0)
; #define PG8_WAIT_V(n) asm volatile("s_waitcnt vmcnt(" #n ")" ::: "memory")
; #define PG8_WAIT_L(n) asm volatile("s_waitcnt lgkmcnt(" #n ")" ::: "memory")
; template <class Epi, class Sched, bool ALIGN_EPI = false, bool SP2 = false>
; __device__ __forceinline__ void gemm_phase(PG8_LAS unsigned char* lds, const Gemm g, const Sched& S, const Epi& E) {
;     ...
;             const bool last = (t == nt - 2);
;             const char* a1 = cA + (size_t)(t + 1) * kstep;
;             const char* a2 = last ? nA : cA + (size_t)(t + 2) * kstep; const char* b2 = last ? nB : cB + (size_t)(t + 2) * kstep;
;             const char* a3 = a2 + kstep; const char* b3 = b2 + kstep;
;             if (last && has_next) S.a_ready(nxt);
;             if constexpr (SP2) {
;             PG8_LDB(B0, 0, 0); PG8_LDB(B1, 0, 1); PG8_SCHED; PG8_LDA(At, 0, 0); PG8_STAGE(PG8_SA(1, 1), a1 + hstep, voffA);
;             PG8_WAIT_V(8); PG8_WAIT_L(0); PG8_BAR; PG8_MMA(0, 0, At, B0); PG8_MMA(0, 1, At, B1); PG8_BAR; PG8_SCHED;
;             PG8_LDA(At, 0, 1); PG8_STAGE(PG8_SB(0, 0), b2, voffB); PG8_STAGE(PG8_SB(0, 1), b2 + hstep, voffB); PG8_STAGE(PG8_SA(0, 0), a2, voffA);
;             PG8_WAIT_V(8); PG8_WAIT_L(0); PG8_BAR; PG8_MMA(1, 0, At, B0); PG8_MMA(1, 1, At, B1); PG8_BAR; PG8_SCHED;
.LBB0_792:
	s_waitcnt lgkmcnt(0)
	ds_read_b128 v[140:143], v254
	ds_read_b128 v[162:165], v254 offset:1024
	ds_read_b128 v[166:169], v254 offset:2048
	ds_read_b128 v[176:179], v254 offset:3072
	ds_read_b128 v[180:183], v254 offset:16384
	ds_read_b128 v[184:187], v254 offset:17408
	ds_read_b128 v[188:191], v254 offset:18432
	ds_read_b128 v[210:213], v254 offset:19456
	s_add_u32 s2, s0, 0xfffc0080
	s_addc_u32 s3, s1, -1
	s_cmp_eq_u32 s52, 12
	s_cselect_b32 s5, s17, s3
	s_cselect_b32 s4, s48, s2
	s_cselect_b32 s3, s15, s51
	s_cselect_b32 s2, s49, s50
	s_add_i32 m0, s6, 0xc000
	ds_read_b128 v[214:217], v173
	ds_read_b128 v[218:221], v173 offset:1024
	ds_read_b128 v[222:225], v173 offset:2048
	ds_read_b128 v[226:229], v173 offset:3072
	ds_read_b128 v[230:233], v173 offset:4096
	ds_read_b128 v[234:237], v173 offset:5120
	ds_read_b128 v[238:241], v173 offset:6144
	ds_read_b128 v[242:245], v173 offset:7168
	global_load_lds_dwordx4 v136, s[0:1]
	s_add_i32 m0, s6, 0xe000
	s_nop 0
	global_load_lds_dwordx4 v138, s[0:1]
	s_waitcnt vmcnt(8)
	s_waitcnt lgkmcnt(0)
	s_barrier
	s_setprio 1
	v_mfma_f32_16x16x32_bf16 v[124:127], v[140:143], v[214:217], v[124:127]
	v_mfma_f32_16x16x32_bf16 v[112:115], v[140:143], v[222:225], v[112:115]
	v_mfma_f32_16x16x32_bf16 v[96:99], v[140:143], v[230:233], v[96:99]
	v_mfma_f32_16x16x32_bf16 v[80:83], v[140:143], v[238:241], v[80:83]
	v_mfma_f32_16x16x32_bf16 v[120:123], v[166:169], v[214:217], v[120:123]
	v_mfma_f32_16x16x32_bf16 v[104:107], v[166:169], v[222:225], v[104:107]
	v_mfma_f32_16x16x32_bf16 v[88:91], v[166:169], v[230:233], v[88:91]
	v_mfma_f32_16x16x32_bf16 v[72:75], v[166:169], v[238:241], v[72:75]
	v_mfma_f32_16x16x32_bf16 v[124:127], v[162:165], v[218:221], v[124:127]
	v_mfma_f32_16x16x32_bf16 v[112:115], v[162:165], v[226:229], v[112:115]
	v_mfma_f32_16x16x32_bf16 v[96:99], v[162:165], v[234:237], v[96:99]
	v_mfma_f32_16x16x32_bf16 v[80:83], v[162:165], v[242:245], v[80:83]
	v_mfma_f32_16x16x32_bf16 v[120:123], v[176:179], v[218:221], v[120:123]
	v_mfma_f32_16x16x32_bf16 v[104:107], v[176:179], v[226:229], v[104:107]
	v_mfma_f32_16x16x32_bf16 v[88:91], v[176:179], v[234:237], v[88:91]
	v_mfma_f32_16x16x32_bf16 v[72:75], v[176:179], v[242:245], v[72:75]
	v_mfma_f32_16x16x32_bf16 v[116:119], v[180:183], v[214:217], v[116:119]
	v_mfma_f32_16x16x32_bf16 v[100:103], v[180:183], v[222:225], v[100:103]
	v_mfma_f32_16x16x32_bf16 v[84:87], v[180:183], v[230:233], v[84:87]
	v_mfma_f32_16x16x32_bf16 v[68:71], v[180:183], v[238:241], v[68:71]
	v_mfma_f32_16x16x32_bf16 v[108:111], v[188:191], v[214:217], v[108:111]
	v_mfma_f32_16x16x32_bf16 v[92:95], v[188:191], v[222:225], v[92:95]
	v_mfma_f32_16x16x32_bf16 v[76:79], v[188:191], v[230:233], v[76:79]
	v_mfma_f32_16x16x32_bf16 v[64:67], v[188:191], v[238:241], v[64:67]
	v_mfma_f32_16x16x32_bf16 v[116:119], v[184:187], v[218:221], v[116:119]
	v_mfma_f32_16x16x32_bf16 v[100:103], v[184:187], v[226:229], v[100:103]
	v_mfma_f32_16x16x32_bf16 v[84:87], v[184:187], v[234:237], v[84:87]
	v_mfma_f32_16x16x32_bf16 v[68:71], v[184:187], v[242:245], v[68:71]
	v_mfma_f32_16x16x32_bf16 v[108:111], v[210:213], v[218:221], v[108:111]
	v_mfma_f32_16x16x32_bf16 v[92:95], v[210:213], v[226:229], v[92:95]
	v_mfma_f32_16x16x32_bf16 v[76:79], v[210:213], v[234:237], v[76:79]
	v_mfma_f32_16x16x32_bf16 v[64:67], v[210:213], v[242:245], v[64:67]
	s_setprio 0
	s_barrier
	s_mov_b32 m0, s27
	s_add_u32 s54, s2, 0x40000
	s_addc_u32 s55, s3, 0
	ds_read_b128 v[214:217], v173 offset:16384
	ds_read_b128 v[218:221], v173 offset:17408
	ds_read_b128 v[222:225], v173 offset:18432
	ds_read_b128 v[226:229], v173 offset:19456
	ds_read_b128 v[230:233], v173 offset:20480
	ds_read_b128 v[234:237], v173 offset:21504
	ds_read_b128 v[238:241], v173 offset:22528
	ds_read_b128 v[242:245], v173 offset:23552
	global_load_lds_dwordx4 v132, s[2:3]
	s_mov_b32 m0, s28
	s_nop 0
	global_load_lds_dwordx4 v128, s[2:3]
	s_mov_b32 m0, s29
	s_nop 0
	global_load_lds_dwordx4 v132, s[54:55]
	s_mov_b32 m0, s30
	s_nop 0
	global_load_lds_dwordx4 v128, s[54:55]
	s_mov_b32 m0, s6
	s_nop 0
	global_load_lds_dwordx4 v134, s[4:5]
	s_mov_b32 m0, s31
	s_nop 0
	global_load_lds_dwordx4 v130, s[4:5]
	s_waitcnt vmcnt(8)
	s_waitcnt lgkmcnt(0)
	s_barrier
	s_setprio 1
	v_mfma_f32_16x16x32_bf16 v[60:63], v[140:143], v[214:217], v[60:63]
	v_mfma_f32_16x16x32_bf16 v[48:51], v[140:143], v[222:225], v[48:51]
	v_mfma_f32_16x16x32_bf16 v[32:35], v[140:143], v[230:233], v[32:35]
	v_mfma_f32_16x16x32_bf16 v[16:19], v[140:143], v[238:241], v[16:19]
	v_mfma_f32_16x16x32_bf16 v[56:59], v[166:169], v[214:217], v[56:59]
	v_mfma_f32_16x16x32_bf16 v[40:43], v[166:169], v[222:225], v[40:43]
	v_mfma_f32_16x16x32_bf16 v[24:27], v[166:169], v[230:233], v[24:27]
	v_mfma_f32_16x16x32_bf16 v[8:11], v[166:169], v[238:241], v[8:11]
	v_mfma_f32_16x16x32_bf16 v[60:63], v[162:165], v[218:221], v[60:63]
	v_mfma_f32_16x16x32_bf16 v[48:51], v[162:165], v[226:229], v[48:51]
	v_mfma_f32_16x16x32_bf16 v[32:35], v[162:165], v[234:237], v[32:35]
	v_mfma_f32_16x16x32_bf16 v[16:19], v[162:165], v[242:245], v[16:19]
	v_mfma_f32_16x16x32_bf16 v[56:59], v[176:179], v[218:221], v[56:59]
	v_mfma_f32_16x16x32_bf16 v[40:43], v[176:179], v[226:229], v[40:43]
	v_mfma_f32_16x16x32_bf16 v[24:27], v[176:179], v[234:237], v[24:27]
	v_mfma_f32_16x16x32_bf16 v[8:11], v[176:179], v[242:245], v[8:11]
	v_mfma_f32_16x16x32_bf16 v[52:55], v[180:183], v[214:217], v[52:55]
	v_mfma_f32_16x16x32_bf16 v[36:39], v[180:183], v[222:225], v[36:39]
	v_mfma_f32_16x16x32_bf16 v[20:23], v[180:183], v[230:233], v[20:23]
	v_mfma_f32_16x16x32_bf16 v[4:7], v[180:183], v[238:241], v[4:7]
	v_mfma_f32_16x16x32_bf16 v[44:47], v[188:191], v[214:217], v[44:47]
	v_mfma_f32_16x16x32_bf16 v[28:31], v[188:191], v[222:225], v[28:31]
	v_mfma_f32_16x16x32_bf16 v[12:15], v[188:191], v[230:233], v[12:15]
	v_mfma_f32_16x16x32_bf16 v[0:3], v[188:191], v[238:241], v[0:3]
	v_mfma_f32_16x16x32_bf16 v[52:55], v[184:187], v[218:221], v[52:55]
	v_mfma_f32_16x16x32_bf16 v[36:39], v[184:187], v[226:229], v[36:39]
	v_mfma_f32_16x16x32_bf16 v[20:23], v[184:187], v[234:237], v[20:23]
	v_mfma_f32_16x16x32_bf16 v[4:7], v[184:187], v[242:245], v[4:7]
	v_mfma_f32_16x16x32_bf16 v[44:47], v[210:213], v[218:221], v[44:47]
	v_mfma_f32_16x16x32_bf16 v[28:31], v[210:213], v[226:229], v[28:31]
	v_mfma_f32_16x16x32_bf16 v[12:15], v[210:213], v[234:237], v[12:15]
	v_mfma_f32_16x16x32_bf16 v[0:3], v[210:213], v[242:245], v[0:3]
	s_setprio 0
	s_barrier
; #define PG8_STAGE(bufoff, gbase, voff) do { _Pragma("unroll") for (int _i = 0; _i < 2; ++_i) \
;         __builtin_amdgcn_global_load_lds((const unsigned*)((const char*)(gbase) + (voff)[_i]), (PG8_LAS unsigned*)(lds + (bufoff) + ldsw + _i * 8192), 16, 0, 0); } while (0)
; #define PG8_LDA(dst, b, h) do { _Pragma("unroll") for (int m = 0; m < 4; ++m) _Pragma("unroll") for (int k = 0; k < 2; ++k) dst[m][k] = *(const PG8_LAS bf16x8*)(lds + PG8_SA(b, h) + aoff + m * 2048 + k * 1024); } while (0)
; #define PG8_LDB(dst, b, h) do { _Pragma("unroll") for (int n = 0; n < 2; ++n) _Pragma("unroll") for (int k = 0; k < 2; ++k) dst[n][k] = *(const PG8_LAS bf16x8*)(lds + PG8_SB(b, h) + boff + n * 2048 + k * 1024); } while (0)
; #define PG8_MMA(ai, bj, At, Bt) do { __builtin_amdgcn_s_setprio(1); _Pragma("unroll") for (int m = 0; m < 4; ++m) _Pragma("unroll") for (int n = 0; n < 2; ++n) _Pragma("unroll") for (int k = 0; k < 2; ++k) \
;         acc[ai][bj][m][n] = __builtin_amdgcn_mfma_f32_16x16x32_bf16(Bt[n][k], At[m][k], acc[ai][bj][m][n], 0, 0, 0); __builtin_amdgcn_s_setprio(0); } while (0)
; #define PG8_WAIT_V(n) asm volatile("s_waitcnt vmcnt(" #n ")" ::: "memory")
; #define PG8_WAIT_L(n) asm volatile("s_waitcnt lgkmcnt(" #n ")" ::: "memory")
; #define PG8_BAR __builtin_amdgcn_s_barrier()
; #define PG8_SCHED __builtin_amdgcn_sched_barrier(0)
; template <class Epi, class Sched, bool ALIGN_EPI = false, bool SP2 = false>
; __device__ __forceinline__ void gemm_phase(PG8_LAS unsigned char* lds, const Gemm g, const Sched& S, const Epi& E) {
;     ...
;             PG8_LDB(B0, 1, 0); PG8_LDB(B1, 1, 1); PG8_SCHED; PG8_LDA(At, 1, 0); PG8_STAGE(PG8_SA(0, 1), a2 + hstep, voffA);
;             PG8_WAIT_V(8); PG8_WAIT_L(0); PG8_BAR; PG8_MMA(0, 0, At, B0); PG8_MMA(0, 1, At, B1); PG8_BAR; PG8_SCHED;
;             PG8_LDA(At, 1, 1); PG8_STAGE(PG8_SB(1, 0), b3, voffB); PG8_STAGE(PG8_SB(1, 1), b3 + hstep, voffB); PG8_STAGE(PG8_SA(1, 0), a3, voffA);
;             PG8_WAIT_V(8); PG8_WAIT_L(0); PG8_BAR; PG8_MMA(1, 0, At, B0); PG8_MMA(1, 1, At, B1); PG8_BAR; PG8_SCHED;
;     ...
;         }
;         if constexpr (ALIGN_EPI) { if (wr == 0) PG8_BAR; }
	ds_read_b128 v[140:143], v254 offset:32768
	ds_read_b128 v[162:165], v254 offset:33792
	ds_read_b128 v[166:169], v254 offset:34816
	ds_read_b128 v[176:179], v254 offset:35840
	ds_read_b128 v[180:183], v254 offset:49152
	ds_read_b128 v[184:187], v254 offset:50176
	ds_read_b128 v[188:191], v254 offset:51200
	ds_read_b128 v[210:213], v254 offset:52224
	s_add_u32 s4, s4, 0x40000
	s_addc_u32 s5, s5, 0
	s_mov_b32 m0, s33
	ds_read_b128 v[214:217], v173 offset:32768
	ds_read_b128 v[218:221], v173 offset:33792
	ds_read_b128 v[222:225], v173 offset:34816
	ds_read_b128 v[226:229], v173 offset:35840
	ds_read_b128 v[230:233], v173 offset:36864
	ds_read_b128 v[234:237], v173 offset:37888
	ds_read_b128 v[238:241], v173 offset:38912
	ds_read_b128 v[242:245], v173 offset:39936
	global_load_lds_dwordx4 v134, s[4:5]
	s_mov_b32 m0, s34
	s_nop 0
	global_load_lds_dwordx4 v130, s[4:5]
	s_waitcnt vmcnt(8)
	s_waitcnt lgkmcnt(0)
	s_barrier
	s_setprio 1
	v_mfma_f32_16x16x32_bf16 v[124:127], v[140:143], v[214:217], v[124:127]
	v_mfma_f32_16x16x32_bf16 v[112:115], v[140:143], v[222:225], v[112:115]
	v_mfma_f32_16x16x32_bf16 v[96:99], v[140:143], v[230:233], v[96:99]
	v_mfma_f32_16x16x32_bf16 v[80:83], v[140:143], v[238:241], v[80:83]
	v_mfma_f32_16x16x32_bf16 v[120:123], v[166:169], v[214:217], v[120:123]
	v_mfma_f32_16x16x32_bf16 v[104:107], v[166:169], v[222:225], v[104:107]
	v_mfma_f32_16x16x32_bf16 v[88:91], v[166:169], v[230:233], v[88:91]
	v_mfma_f32_16x16x32_bf16 v[72:75], v[166:169], v[238:241], v[72:75]
	v_mfma_f32_16x16x32_bf16 v[124:127], v[162:165], v[218:221], v[124:127]
	v_mfma_f32_16x16x32_bf16 v[112:115], v[162:165], v[226:229], v[112:115]
	v_mfma_f32_16x16x32_bf16 v[96:99], v[162:165], v[234:237], v[96:99]
	v_mfma_f32_16x16x32_bf16 v[80:83], v[162:165], v[242:245], v[80:83]
	v_mfma_f32_16x16x32_bf16 v[120:123], v[176:179], v[218:221], v[120:123]
	v_mfma_f32_16x16x32_bf16 v[104:107], v[176:179], v[226:229], v[104:107]
	v_mfma_f32_16x16x32_bf16 v[88:91], v[176:179], v[234:237], v[88:91]
	v_mfma_f32_16x16x32_bf16 v[72:75], v[176:179], v[242:245], v[72:75]
	v_mfma_f32_16x16x32_bf16 v[116:119], v[180:183], v[214:217], v[116:119]
	v_mfma_f32_16x16x32_bf16 v[100:103], v[180:183], v[222:225], v[100:103]
	v_mfma_f32_16x16x32_bf16 v[84:87], v[180:183], v[230:233], v[84:87]
	v_mfma_f32_16x16x32_bf16 v[68:71], v[180:183], v[238:241], v[68:71]
	v_mfma_f32_16x16x32_bf16 v[108:111], v[188:191], v[214:217], v[108:111]
	v_mfma_f32_16x16x32_bf16 v[92:95], v[188:191], v[222:225], v[92:95]
	v_mfma_f32_16x16x32_bf16 v[76:79], v[188:191], v[230:233], v[76:79]
	v_mfma_f32_16x16x32_bf16 v[64:67], v[188:191], v[238:241], v[64:67]
	v_mfma_f32_16x16x32_bf16 v[116:119], v[184:187], v[218:221], v[116:119]
	v_mfma_f32_16x16x32_bf16 v[100:103], v[184:187], v[226:229], v[100:103]
	v_mfma_f32_16x16x32_bf16 v[84:87], v[184:187], v[234:237], v[84:87]
	v_mfma_f32_16x16x32_bf16 v[68:71], v[184:187], v[242:245], v[68:71]
	v_mfma_f32_16x16x32_bf16 v[108:111], v[210:213], v[218:221], v[108:111]
	v_mfma_f32_16x16x32_bf16 v[92:95], v[210:213], v[226:229], v[92:95]
	v_mfma_f32_16x16x32_bf16 v[76:79], v[210:213], v[234:237], v[76:79]
	v_mfma_f32_16x16x32_bf16 v[64:67], v[210:213], v[242:245], v[64:67]
	s_setprio 0
	s_barrier
	s_mov_b32 m0, s37
	s_add_u32 s2, s2, 0x40080
	s_addc_u32 s3, s3, 0
	ds_read_b128 v[214:217], v173 offset:49152
	ds_read_b128 v[218:221], v173 offset:50176
	ds_read_b128 v[222:225], v173 offset:51200
	ds_read_b128 v[226:229], v173 offset:52224
	ds_read_b128 v[230:233], v173 offset:53248
	ds_read_b128 v[234:237], v173 offset:54272
	ds_read_b128 v[238:241], v173 offset:55296
	ds_read_b128 v[242:245], v173 offset:56320
	s_add_u32 s98, s2, 0xfffc0000
	s_addc_u32 s99, s3, -1
	global_load_lds_dwordx4 v132, s[98:99]
	s_mov_b32 m0, s38
	s_nop 0
	global_load_lds_dwordx4 v128, s[98:99]
	s_mov_b32 m0, s41
	s_nop 0
	global_load_lds_dwordx4 v132, s[2:3]
	s_mov_b32 m0, s42
	s_nop 0
	global_load_lds_dwordx4 v128, s[2:3]
	s_mov_b32 m0, s39
	s_nop 0
	s_add_u32 s100, s4, 0xfffc0080
	s_addc_u32 s101, s5, -1
	global_load_lds_dwordx4 v134, s[100:101]
	s_mov_b32 m0, s40
	s_nop 0
	global_load_lds_dwordx4 v130, s[100:101]
	s_waitcnt vmcnt(8)
	s_waitcnt lgkmcnt(0)
	s_barrier
	s_setprio 1
	v_mfma_f32_16x16x32_bf16 v[60:63], v[140:143], v[214:217], v[60:63]
	v_mfma_f32_16x16x32_bf16 v[48:51], v[140:143], v[222:225], v[48:51]
	v_mfma_f32_16x16x32_bf16 v[32:35], v[140:143], v[230:233], v[32:35]
	v_mfma_f32_16x16x32_bf16 v[16:19], v[140:143], v[238:241], v[16:19]
	v_mfma_f32_16x16x32_bf16 v[56:59], v[166:169], v[214:217], v[56:59]
	v_mfma_f32_16x16x32_bf16 v[40:43], v[166:169], v[222:225], v[40:43]
	v_mfma_f32_16x16x32_bf16 v[24:27], v[166:169], v[230:233], v[24:27]
	v_mfma_f32_16x16x32_bf16 v[8:11], v[166:169], v[238:241], v[8:11]
	v_mfma_f32_16x16x32_bf16 v[60:63], v[162:165], v[218:221], v[60:63]
	v_mfma_f32_16x16x32_bf16 v[48:51], v[162:165], v[226:229], v[48:51]
	v_mfma_f32_16x16x32_bf16 v[32:35], v[162:165], v[234:237], v[32:35]
	v_mfma_f32_16x16x32_bf16 v[16:19], v[162:165], v[242:245], v[16:19]
	v_mfma_f32_16x16x32_bf16 v[56:59], v[176:179], v[218:221], v[56:59]
	v_mfma_f32_16x16x32_bf16 v[40:43], v[176:179], v[226:229], v[40:43]
	v_mfma_f32_16x16x32_bf16 v[24:27], v[176:179], v[234:237], v[24:27]
	v_mfma_f32_16x16x32_bf16 v[8:11], v[176:179], v[242:245], v[8:11]
	v_mfma_f32_16x16x32_bf16 v[52:55], v[180:183], v[214:217], v[52:55]
	v_mfma_f32_16x16x32_bf16 v[36:39], v[180:183], v[222:225], v[36:39]
	v_mfma_f32_16x16x32_bf16 v[20:23], v[180:183], v[230:233], v[20:23]
	v_mfma_f32_16x16x32_bf16 v[4:7], v[180:183], v[238:241], v[4:7]
	v_mfma_f32_16x16x32_bf16 v[44:47], v[188:191], v[214:217], v[44:47]
	v_mfma_f32_16x16x32_bf16 v[28:31], v[188:191], v[222:225], v[28:31]
	v_mfma_f32_16x16x32_bf16 v[12:15], v[188:191], v[230:233], v[12:15]
	v_mfma_f32_16x16x32_bf16 v[0:3], v[188:191], v[238:241], v[0:3]
	v_mfma_f32_16x16x32_bf16 v[52:55], v[184:187], v[218:221], v[52:55]
	v_mfma_f32_16x16x32_bf16 v[36:39], v[184:187], v[226:229], v[36:39]
	v_mfma_f32_16x16x32_bf16 v[20:23], v[184:187], v[234:237], v[20:23]
	v_mfma_f32_16x16x32_bf16 v[4:7], v[184:187], v[242:245], v[4:7]
	v_mfma_f32_16x16x32_bf16 v[44:47], v[210:213], v[218:221], v[44:47]
	v_mfma_f32_16x16x32_bf16 v[28:31], v[210:213], v[226:229], v[28:31]
	v_mfma_f32_16x16x32_bf16 v[12:15], v[210:213], v[234:237], v[12:15]
	v_mfma_f32_16x16x32_bf16 v[0:3], v[210:213], v[242:245], v[0:3]
	s_setprio 0
	s_barrier
	s_add_i32 s52, s52, 2
	s_add_u32 s0, s0, 0x100
	s_addc_u32 s1, s1, 0
	s_add_u32 s50, s50, 0x100
	s_addc_u32 s51, s51, 0
	s_cmp_gt_u32 s52, 13
	s_cbranch_scc0 .LBB0_792
	s_and_b64 vcc, exec, s[12:13]
	s_cbranch_vccz .LBB0_795
	s_barrier

; #define PG8_STAGE(bufoff, gbase, voff) do { _Pragma("unroll") for (int _i = 0; _i < 2; ++_i) \
;         __builtin_amdgcn_global_load_lds((const unsigned*)((const char*)(gbase) + (voff)[_i]), (PG8_LAS unsigned*)(lds + (bufoff) + ldsw + _i * 8192), 16, 0, 0); } while (0)
; #define PG8_LDA(dst, b, h) do { _Pragma("unroll") for (int m = 0; m < 4; ++m) _Pragma("unroll") for (int k = 0; k < 2; ++k) dst[m][k] = *(const PG8_LAS bf16x8*)(lds + PG8_SA(b, h) + aoff + m * 2048 + k * 1024); } while (0)
; #define PG8_LDB(dst, b, h) do { _Pragma("unroll") for (int n = 0; n < 2; ++n) _Pragma("unroll") for (int k = 0; k < 2; ++k) dst[n][k] = *(const PG8_LAS bf16x8*)(lds + PG8_SB(b, h) + boff + n * 2048 + k * 1024); } while (0)
; #define PG8_MMA(ai, bj, At, Bt) do { __builtin_amdgcn_s_setprio(1); _Pragma("unroll") for (int m = 0; m < 4; ++m) _Pragma("unroll") for (int n = 0; n < 2; ++n) _Pragma("unroll") for (int k = 0; k < 2; ++k) \
;         acc[ai][bj][m][n] = __builtin_amdgcn_mfma_f32_16x16x32_bf16(Bt[n][k], At[m][k], acc[ai][bj][m][n], 0, 0, 0); __builtin_amdgcn_s_setprio(0); } while (0)
; #define PG8_WAIT_V(n) asm volatile("s_waitcnt vmcnt(" #n ")" ::: "memory")
; #define PG8_WAIT_L(n) asm volatile("s_waitcnt lgkmcnt(" #n ")" ::: "memory")
; template <class Epi, class Sched, bool ALIGN_EPI = false, bool SP2 = false>
; __device__ __forceinline__ void gemm_phase(PG8_LAS unsigned char* lds, const Gemm g, const Sched& S, const Epi& E) {
;     ...
;             const bool last = (t == nt - 2);
;             const char* a1 = cA + (size_t)(t + 1) * kstep;
;             const char* a2 = last ? nA : cA + (size_t)(t + 2) * kstep; const char* b2 = last ? nB : cB + (size_t)(t + 2) * kstep;
;             const char* a3 = a2 + kstep; const char* b3 = b2 + kstep;
;             if (last && has_next) S.a_ready(nxt);
;             if constexpr (SP2) {
;             PG8_LDB(B0, 0, 0); PG8_LDB(B1, 0, 1); PG8_SCHED; PG8_LDA(At, 0, 0); PG8_STAGE(PG8_SA(1, 1), a1 + hstep, voffA);
;             PG8_WAIT_V(8); PG8_WAIT_L(0); PG8_BAR; PG8_MMA(0, 0, At, B0); PG8_MMA(0, 1, At, B1); PG8_BAR; PG8_SCHED;
;             PG8_LDA(At, 0, 1); PG8_STAGE(PG8_SB(0, 0), b2, voffB); PG8_STAGE(PG8_SB(0, 1), b2 + hstep, voffB); PG8_STAGE(PG8_SA(0, 0), a2, voffA);
;             PG8_WAIT_V(8); PG8_WAIT_L(0); PG8_BAR; PG8_MMA(1, 0, At, B0); PG8_MMA(1, 1, At, B1); PG8_BAR; PG8_SCHED;
.Lsgo_peel:
	ds_read_b128 v[140:143], v254
	ds_read_b128 v[166:169], v254 offset:1024
	ds_read_b128 v[170:173], v254 offset:2048
	ds_read_b128 v[174:177], v254 offset:3072
	ds_read_b128 v[178:181], v254 offset:16384
	ds_read_b128 v[182:185], v254 offset:17408
	ds_read_b128 v[186:189], v254 offset:18432
	ds_read_b128 v[210:213], v254 offset:19456
	s_add_u32 s2, s0, 0xfffc0080
	s_addc_u32 s3, s1, -1
	s_cmp_eq_u32 s55, 12
	s_cselect_b32 s5, s23, s3
	s_cselect_b32 s4, s51, s2
	s_cselect_b32 s3, s21, s54
	s_cselect_b32 s2, s52, s53
	s_add_i32 m0, s31, 0xc000
	ds_read_b128 v[214:217], v163
	ds_read_b128 v[218:221], v163 offset:1024
	ds_read_b128 v[222:225], v163 offset:2048
	ds_read_b128 v[226:229], v163 offset:3072
	ds_read_b128 v[230:233], v163 offset:4096
	ds_read_b128 v[234:237], v163 offset:5120
	ds_read_b128 v[238:241], v163 offset:6144
	ds_read_b128 v[242:245], v163 offset:7168
	global_load_lds_dwordx4 v136, s[0:1]
	s_add_i32 m0, s31, 0xe000
	s_nop 0
	global_load_lds_dwordx4 v138, s[0:1]
	s_waitcnt vmcnt(8)
	s_waitcnt lgkmcnt(0)
	s_barrier
	s_setprio 1
	v_mfma_f32_16x16x32_bf16 v[124:127], v[140:143], v[214:217], 0
	v_mfma_f32_16x16x32_bf16 v[108:111], v[140:143], v[222:225], 0
	v_mfma_f32_16x16x32_bf16 v[92:95], v[140:143], v[230:233], 0
	v_mfma_f32_16x16x32_bf16 v[76:79], v[140:143], v[238:241], 0
	v_mfma_f32_16x16x32_bf16 v[120:123], v[170:173], v[214:217], 0
	v_mfma_f32_16x16x32_bf16 v[104:107], v[170:173], v[222:225], 0
	v_mfma_f32_16x16x32_bf16 v[88:91], v[170:173], v[230:233], 0
	v_mfma_f32_16x16x32_bf16 v[72:75], v[170:173], v[238:241], 0
	v_mfma_f32_16x16x32_bf16 v[124:127], v[166:169], v[218:221], v[124:127]
	v_mfma_f32_16x16x32_bf16 v[108:111], v[166:169], v[226:229], v[108:111]
	v_mfma_f32_16x16x32_bf16 v[92:95], v[166:169], v[234:237], v[92:95]
	v_mfma_f32_16x16x32_bf16 v[76:79], v[166:169], v[242:245], v[76:79]
	v_mfma_f32_16x16x32_bf16 v[120:123], v[174:177], v[218:221], v[120:123]
	v_mfma_f32_16x16x32_bf16 v[104:107], v[174:177], v[226:229], v[104:107]
	v_mfma_f32_16x16x32_bf16 v[88:91], v[174:177], v[234:237], v[88:91]
	v_mfma_f32_16x16x32_bf16 v[72:75], v[174:177], v[242:245], v[72:75]
	v_mfma_f32_16x16x32_bf16 v[116:119], v[178:181], v[214:217], 0
	v_mfma_f32_16x16x32_bf16 v[100:103], v[178:181], v[222:225], 0
	v_mfma_f32_16x16x32_bf16 v[84:87], v[178:181], v[230:233], 0
	v_mfma_f32_16x16x32_bf16 v[68:71], v[178:181], v[238:241], 0
	v_mfma_f32_16x16x32_bf16 v[112:115], v[186:189], v[214:217], 0
	v_mfma_f32_16x16x32_bf16 v[96:99], v[186:189], v[222:225], 0
	v_mfma_f32_16x16x32_bf16 v[80:83], v[186:189], v[230:233], 0
	v_mfma_f32_16x16x32_bf16 v[64:67], v[186:189], v[238:241], 0
	v_mfma_f32_16x16x32_bf16 v[116:119], v[182:185], v[218:221], v[116:119]
	v_mfma_f32_16x16x32_bf16 v[100:103], v[182:185], v[226:229], v[100:103]
	v_mfma_f32_16x16x32_bf16 v[84:87], v[182:185], v[234:237], v[84:87]
	v_mfma_f32_16x16x32_bf16 v[68:71], v[182:185], v[242:245], v[68:71]
	v_mfma_f32_16x16x32_bf16 v[112:115], v[210:213], v[218:221], v[112:115]
	v_mfma_f32_16x16x32_bf16 v[96:99], v[210:213], v[226:229], v[96:99]
	v_mfma_f32_16x16x32_bf16 v[80:83], v[210:213], v[234:237], v[80:83]
	v_mfma_f32_16x16x32_bf16 v[64:67], v[210:213], v[242:245], v[64:67]
	s_setprio 0
	s_barrier
	s_mov_b32 m0, s33
	s_add_u32 s56, s2, 0x40000
	s_addc_u32 s57, s3, 0
	ds_read_b128 v[214:217], v163 offset:16384
	ds_read_b128 v[218:221], v163 offset:17408
	ds_read_b128 v[222:225], v163 offset:18432
	ds_read_b128 v[226:229], v163 offset:19456
	ds_read_b128 v[230:233], v163 offset:20480
	ds_read_b128 v[234:237], v163 offset:21504
	ds_read_b128 v[238:241], v163 offset:22528
	ds_read_b128 v[242:245], v163 offset:23552
	global_load_lds_dwordx4 v132, s[2:3]
	s_mov_b32 m0, s34
	s_nop 0
	global_load_lds_dwordx4 v128, s[2:3]
	s_mov_b32 m0, s35
	s_nop 0
	global_load_lds_dwordx4 v132, s[56:57]
	s_mov_b32 m0, s36
	s_nop 0
	global_load_lds_dwordx4 v128, s[56:57]
	s_mov_b32 m0, s31
	s_nop 0
	global_load_lds_dwordx4 v134, s[4:5]
	s_mov_b32 m0, s37
	s_nop 0
	global_load_lds_dwordx4 v130, s[4:5]
	s_waitcnt vmcnt(8)
	s_waitcnt lgkmcnt(0)
	s_barrier
	s_setprio 1
	v_mfma_f32_16x16x32_bf16 v[60:63], v[140:143], v[214:217], 0
	v_mfma_f32_16x16x32_bf16 v[44:47], v[140:143], v[222:225], 0
	v_mfma_f32_16x16x32_bf16 v[28:31], v[140:143], v[230:233], 0
	v_mfma_f32_16x16x32_bf16 v[12:15], v[140:143], v[238:241], 0
	v_mfma_f32_16x16x32_bf16 v[56:59], v[170:173], v[214:217], 0
	v_mfma_f32_16x16x32_bf16 v[40:43], v[170:173], v[222:225], 0
	v_mfma_f32_16x16x32_bf16 v[24:27], v[170:173], v[230:233], 0
	v_mfma_f32_16x16x32_bf16 v[8:11], v[170:173], v[238:241], 0
	v_mfma_f32_16x16x32_bf16 v[60:63], v[166:169], v[218:221], v[60:63]
	v_mfma_f32_16x16x32_bf16 v[44:47], v[166:169], v[226:229], v[44:47]
	v_mfma_f32_16x16x32_bf16 v[28:31], v[166:169], v[234:237], v[28:31]
	v_mfma_f32_16x16x32_bf16 v[12:15], v[166:169], v[242:245], v[12:15]
	v_mfma_f32_16x16x32_bf16 v[56:59], v[174:177], v[218:221], v[56:59]
	v_mfma_f32_16x16x32_bf16 v[40:43], v[174:177], v[226:229], v[40:43]
	v_mfma_f32_16x16x32_bf16 v[24:27], v[174:177], v[234:237], v[24:27]
	v_mfma_f32_16x16x32_bf16 v[8:11], v[174:177], v[242:245], v[8:11]
	v_mfma_f32_16x16x32_bf16 v[52:55], v[178:181], v[214:217], 0
	v_mfma_f32_16x16x32_bf16 v[36:39], v[178:181], v[222:225], 0
	v_mfma_f32_16x16x32_bf16 v[20:23], v[178:181], v[230:233], 0
	v_mfma_f32_16x16x32_bf16 v[4:7], v[178:181], v[238:241], 0
	v_mfma_f32_16x16x32_bf16 v[48:51], v[186:189], v[214:217], 0
	v_mfma_f32_16x16x32_bf16 v[32:35], v[186:189], v[222:225], 0
	v_mfma_f32_16x16x32_bf16 v[16:19], v[186:189], v[230:233], 0
	v_mfma_f32_16x16x32_bf16 v[0:3], v[186:189], v[238:241], 0
	v_mfma_f32_16x16x32_bf16 v[52:55], v[182:185], v[218:221], v[52:55]
	v_mfma_f32_16x16x32_bf16 v[36:39], v[182:185], v[226:229], v[36:39]
	v_mfma_f32_16x16x32_bf16 v[20:23], v[182:185], v[234:237], v[20:23]
	v_mfma_f32_16x16x32_bf16 v[4:7], v[182:185], v[242:245], v[4:7]
	v_mfma_f32_16x16x32_bf16 v[48:51], v[210:213], v[218:221], v[48:51]
	v_mfma_f32_16x16x32_bf16 v[32:35], v[210:213], v[226:229], v[32:35]
	v_mfma_f32_16x16x32_bf16 v[16:19], v[210:213], v[234:237], v[16:19]
	v_mfma_f32_16x16x32_bf16 v[0:3], v[210:213], v[242:245], v[0:3]
	s_setprio 0
	s_barrier
; #define PG8_STAGE(bufoff, gbase, voff) do { _Pragma("unroll") for (int _i = 0; _i < 2; ++_i) \
;         __builtin_amdgcn_global_load_lds((const unsigned*)((const char*)(gbase) + (voff)[_i]), (PG8_LAS unsigned*)(lds + (bufoff) + ldsw + _i * 8192), 16, 0, 0); } while (0)
; #define PG8_LDA(dst, b, h) do { _Pragma("unroll") for (int m = 0; m < 4; ++m) _Pragma("unroll") for (int k = 0; k < 2; ++k) dst[m][k] = *(const PG8_LAS bf16x8*)(lds + PG8_SA(b, h) + aoff + m * 2048 + k * 1024); } while (0)
; #define PG8_LDB(dst, b, h) do { _Pragma("unroll") for (int n = 0; n < 2; ++n) _Pragma("unroll") for (int k = 0; k < 2; ++k) dst[n][k] = *(const PG8_LAS bf16x8*)(lds + PG8_SB(b, h) + boff + n * 2048 + k * 1024); } while (0)
; #define PG8_MMA(ai, bj, At, Bt) do { __builtin_amdgcn_s_setprio(1); _Pragma("unroll") for (int m = 0; m < 4; ++m) _Pragma("unroll") for (int n = 0; n < 2; ++n) _Pragma("unroll") for (int k = 0; k < 2; ++k) \
;         acc[ai][bj][m][n] = __builtin_amdgcn_mfma_f32_16x16x32_bf16(Bt[n][k], At[m][k], acc[ai][bj][m][n], 0, 0, 0); __builtin_amdgcn_s_setprio(0); } while (0)
; #define PG8_WAIT_V(n) asm volatile("s_waitcnt vmcnt(" #n ")" ::: "memory")
; #define PG8_WAIT_L(n) asm volatile("s_waitcnt lgkmcnt(" #n ")" ::: "memory")
; #define PG8_BAR __builtin_amdgcn_s_barrier()
; #define PG8_SCHED __builtin_amdgcn_sched_barrier(0)
; template <class Epi, class Sched, bool ALIGN_EPI = false, bool SP2 = false>
; __device__ __forceinline__ void gemm_phase(PG8_LAS unsigned char* lds, const Gemm g, const Sched& S, const Epi& E) {
;     ...
;             PG8_LDB(B0, 1, 0); PG8_LDB(B1, 1, 1); PG8_SCHED; PG8_LDA(At, 1, 0); PG8_STAGE(PG8_SA(0, 1), a2 + hstep, voffA);
;             PG8_WAIT_V(8); PG8_WAIT_L(0); PG8_BAR; PG8_MMA(0, 0, At, B0); PG8_MMA(0, 1, At, B1); PG8_BAR; PG8_SCHED;
;             PG8_LDA(At, 1, 1); PG8_STAGE(PG8_SB(1, 0), b3, voffB); PG8_STAGE(PG8_SB(1, 1), b3 + hstep, voffB); PG8_STAGE(PG8_SA(1, 0), a3, voffA);
;             PG8_WAIT_V(8); PG8_WAIT_L(0); PG8_BAR; PG8_MMA(1, 0, At, B0); PG8_MMA(1, 1, At, B1); PG8_BAR; PG8_SCHED;
	ds_read_b128 v[140:143], v254 offset:32768
	ds_read_b128 v[166:169], v254 offset:33792
	ds_read_b128 v[170:173], v254 offset:34816
	ds_read_b128 v[174:177], v254 offset:35840
	ds_read_b128 v[178:181], v254 offset:49152
	ds_read_b128 v[182:185], v254 offset:50176
	ds_read_b128 v[186:189], v254 offset:51200
	ds_read_b128 v[210:213], v254 offset:52224
	s_add_u32 s4, s4, 0x40000
	s_addc_u32 s5, s5, 0
	s_mov_b32 m0, s38
	ds_read_b128 v[214:217], v163 offset:32768
	ds_read_b128 v[218:221], v163 offset:33792
	ds_read_b128 v[222:225], v163 offset:34816
	ds_read_b128 v[226:229], v163 offset:35840
	ds_read_b128 v[230:233], v163 offset:36864
	ds_read_b128 v[234:237], v163 offset:37888
	ds_read_b128 v[238:241], v163 offset:38912
	ds_read_b128 v[242:245], v163 offset:39936
	global_load_lds_dwordx4 v134, s[4:5]
	s_mov_b32 m0, s39
	s_nop 0
	global_load_lds_dwordx4 v130, s[4:5]
	s_waitcnt vmcnt(8)
	s_waitcnt lgkmcnt(0)
	s_barrier
	s_setprio 1
	v_mfma_f32_16x16x32_bf16 v[124:127], v[140:143], v[214:217], v[124:127]
	v_mfma_f32_16x16x32_bf16 v[108:111], v[140:143], v[222:225], v[108:111]
	v_mfma_f32_16x16x32_bf16 v[92:95], v[140:143], v[230:233], v[92:95]
	v_mfma_f32_16x16x32_bf16 v[76:79], v[140:143], v[238:241], v[76:79]
	v_mfma_f32_16x16x32_bf16 v[120:123], v[170:173], v[214:217], v[120:123]
	v_mfma_f32_16x16x32_bf16 v[104:107], v[170:173], v[222:225], v[104:107]
	v_mfma_f32_16x16x32_bf16 v[88:91], v[170:173], v[230:233], v[88:91]
	v_mfma_f32_16x16x32_bf16 v[72:75], v[170:173], v[238:241], v[72:75]
	v_mfma_f32_16x16x32_bf16 v[124:127], v[166:169], v[218:221], v[124:127]
	v_mfma_f32_16x16x32_bf16 v[108:111], v[166:169], v[226:229], v[108:111]
	v_mfma_f32_16x16x32_bf16 v[92:95], v[166:169], v[234:237], v[92:95]
	v_mfma_f32_16x16x32_bf16 v[76:79], v[166:169], v[242:245], v[76:79]
	v_mfma_f32_16x16x32_bf16 v[120:123], v[174:177], v[218:221], v[120:123]
	v_mfma_f32_16x16x32_bf16 v[104:107], v[174:177], v[226:229], v[104:107]
	v_mfma_f32_16x16x32_bf16 v[88:91], v[174:177], v[234:237], v[88:91]
	v_mfma_f32_16x16x32_bf16 v[72:75], v[174:177], v[242:245], v[72:75]
	v_mfma_f32_16x16x32_bf16 v[116:119], v[178:181], v[214:217], v[116:119]
	v_mfma_f32_16x16x32_bf16 v[100:103], v[178:181], v[222:225], v[100:103]
	v_mfma_f32_16x16x32_bf16 v[84:87], v[178:181], v[230:233], v[84:87]
	v_mfma_f32_16x16x32_bf16 v[68:71], v[178:181], v[238:241], v[68:71]
	v_mfma_f32_16x16x32_bf16 v[112:115], v[186:189], v[214:217], v[112:115]
	v_mfma_f32_16x16x32_bf16 v[96:99], v[186:189], v[222:225], v[96:99]
	v_mfma_f32_16x16x32_bf16 v[80:83], v[186:189], v[230:233], v[80:83]
	v_mfma_f32_16x16x32_bf16 v[64:67], v[186:189], v[238:241], v[64:67]
	v_mfma_f32_16x16x32_bf16 v[116:119], v[182:185], v[218:221], v[116:119]
	v_mfma_f32_16x16x32_bf16 v[100:103], v[182:185], v[226:229], v[100:103]
	v_mfma_f32_16x16x32_bf16 v[84:87], v[182:185], v[234:237], v[84:87]
	v_mfma_f32_16x16x32_bf16 v[68:71], v[182:185], v[242:245], v[68:71]
	v_mfma_f32_16x16x32_bf16 v[112:115], v[210:213], v[218:221], v[112:115]
	v_mfma_f32_16x16x32_bf16 v[96:99], v[210:213], v[226:229], v[96:99]
	v_mfma_f32_16x16x32_bf16 v[80:83], v[210:213], v[234:237], v[80:83]
	v_mfma_f32_16x16x32_bf16 v[64:67], v[210:213], v[242:245], v[64:67]
	s_setprio 0
	s_barrier
	s_mov_b32 m0, s43
	s_add_u32 s2, s2, 0x40080
	s_addc_u32 s3, s3, 0
	ds_read_b128 v[214:217], v163 offset:49152
	ds_read_b128 v[218:221], v163 offset:50176
	ds_read_b128 v[222:225], v163 offset:51200
	ds_read_b128 v[226:229], v163 offset:52224
	ds_read_b128 v[230:233], v163 offset:53248
	ds_read_b128 v[234:237], v163 offset:54272
	ds_read_b128 v[238:241], v163 offset:55296
	ds_read_b128 v[242:245], v163 offset:56320
	s_add_u32 s98, s2, 0xfffc0000
	s_addc_u32 s99, s3, -1
	global_load_lds_dwordx4 v132, s[98:99]
	s_mov_b32 m0, s44
	s_nop 0
	global_load_lds_dwordx4 v128, s[98:99]
	s_mov_b32 m0, s48
	s_nop 0
	global_load_lds_dwordx4 v132, s[2:3]
	s_mov_b32 m0, s49
	s_nop 0
	global_load_lds_dwordx4 v128, s[2:3]
	s_mov_b32 m0, s45
	s_nop 0
	s_add_u32 s100, s4, 0xfffc0080
	s_addc_u32 s101, s5, -1
	global_load_lds_dwordx4 v134, s[100:101]
	s_mov_b32 m0, s47
	s_nop 0
	global_load_lds_dwordx4 v130, s[100:101]
	s_waitcnt vmcnt(8)
	s_waitcnt lgkmcnt(0)
	s_barrier
	s_setprio 1
	v_mfma_f32_16x16x32_bf16 v[60:63], v[140:143], v[214:217], v[60:63]
	v_mfma_f32_16x16x32_bf16 v[44:47], v[140:143], v[222:225], v[44:47]
	v_mfma_f32_16x16x32_bf16 v[28:31], v[140:143], v[230:233], v[28:31]
	v_mfma_f32_16x16x32_bf16 v[12:15], v[140:143], v[238:241], v[12:15]
	v_mfma_f32_16x16x32_bf16 v[56:59], v[170:173], v[214:217], v[56:59]
	v_mfma_f32_16x16x32_bf16 v[40:43], v[170:173], v[222:225], v[40:43]
	v_mfma_f32_16x16x32_bf16 v[24:27], v[170:173], v[230:233], v[24:27]
	v_mfma_f32_16x16x32_bf16 v[8:11], v[170:173], v[238:241], v[8:11]
	v_mfma_f32_16x16x32_bf16 v[60:63], v[166:169], v[218:221], v[60:63]
	v_mfma_f32_16x16x32_bf16 v[44:47], v[166:169], v[226:229], v[44:47]
	v_mfma_f32_16x16x32_bf16 v[28:31], v[166:169], v[234:237], v[28:31]
	v_mfma_f32_16x16x32_bf16 v[12:15], v[166:169], v[242:245], v[12:15]
	v_mfma_f32_16x16x32_bf16 v[56:59], v[174:177], v[218:221], v[56:59]
	v_mfma_f32_16x16x32_bf16 v[40:43], v[174:177], v[226:229], v[40:43]
	v_mfma_f32_16x16x32_bf16 v[24:27], v[174:177], v[234:237], v[24:27]
	v_mfma_f32_16x16x32_bf16 v[8:11], v[174:177], v[242:245], v[8:11]
	v_mfma_f32_16x16x32_bf16 v[52:55], v[178:181], v[214:217], v[52:55]
	v_mfma_f32_16x16x32_bf16 v[36:39], v[178:181], v[222:225], v[36:39]
	v_mfma_f32_16x16x32_bf16 v[20:23], v[178:181], v[230:233], v[20:23]
	v_mfma_f32_16x16x32_bf16 v[4:7], v[178:181], v[238:241], v[4:7]
	v_mfma_f32_16x16x32_bf16 v[48:51], v[186:189], v[214:217], v[48:51]
	v_mfma_f32_16x16x32_bf16 v[32:35], v[186:189], v[222:225], v[32:35]
	v_mfma_f32_16x16x32_bf16 v[16:19], v[186:189], v[230:233], v[16:19]
	v_mfma_f32_16x16x32_bf16 v[0:3], v[186:189], v[238:241], v[0:3]
	v_mfma_f32_16x16x32_bf16 v[52:55], v[182:185], v[218:221], v[52:55]
	v_mfma_f32_16x16x32_bf16 v[36:39], v[182:185], v[226:229], v[36:39]
	v_mfma_f32_16x16x32_bf16 v[20:23], v[182:185], v[234:237], v[20:23]
	v_mfma_f32_16x16x32_bf16 v[4:7], v[182:185], v[242:245], v[4:7]
	v_mfma_f32_16x16x32_bf16 v[48:51], v[210:213], v[218:221], v[48:51]
	v_mfma_f32_16x16x32_bf16 v[32:35], v[210:213], v[226:229], v[32:35]
	v_mfma_f32_16x16x32_bf16 v[16:19], v[210:213], v[234:237], v[16:19]
	v_mfma_f32_16x16x32_bf16 v[0:3], v[210:213], v[242:245], v[0:3]
	s_setprio 0
	s_barrier
	s_add_i32 s55, s55, 2
	s_add_u32 s0, s0, 0x100
	s_addc_u32 s1, s1, 0
	s_add_u32 s53, s53, 0x100
	s_addc_u32 s54, s54, 0
	s_cmp_gt_u32 s55, 13
; #define PG8_STAGE(bufoff, gbase, voff) do { _Pragma("unroll") for (int _i = 0; _i < 2; ++_i) \
;         __builtin_amdgcn_global_load_lds((const unsigned*)((const char*)(gbase) + (voff)[_i]), (PG8_LAS unsigned*)(lds + (bufoff) + ldsw + _i * 8192), 16, 0, 0); } while (0)
; #define PG8_LDA(dst, b, h) do { _Pragma("unroll") for (int m = 0; m < 4; ++m) _Pragma("unroll") for (int k = 0; k < 2; ++k) dst[m][k] = *(const PG8_LAS bf16x8*)(lds + PG8_SA(b, h) + aoff + m * 2048 + k * 1024); } while (0)
; #define PG8_LDB(dst, b, h) do { _Pragma("unroll") for (int n = 0; n < 2; ++n) _Pragma("unroll") for (int k = 0; k < 2; ++k) dst[n][k] = *(const PG8_LAS bf16x8*)(lds + PG8_SB(b, h) + boff + n * 2048 + k * 1024); } while (0)
; #define PG8_MMA(ai, bj, At, Bt) do { __builtin_amdgcn_s_setprio(1); _Pragma("unroll") for (int m = 0; m < 4; ++m) _Pragma("unroll") for (int n = 0; n < 2; ++n) _Pragma("unroll") for (int k = 0; k < 2; ++k) \
;         acc[ai][bj][m][n] = __builtin_amdgcn_mfma_f32_16x16x32_bf16(Bt[n][k], At[m][k], acc[ai][bj][m][n], 0, 0, 0); __builtin_amdgcn_s_setprio(0); } while (0)
; #define PG8_WAIT_V(n) asm volatile("s_waitcnt vmcnt(" #n ")" ::: "memory")
; #define PG8_WAIT_L(n) asm volatile("s_waitcnt lgkmcnt(" #n ")" ::: "memory")
; template <class Epi, class Sched, bool ALIGN_EPI = false, bool SP2 = false>
; __device__ __forceinline__ void gemm_phase(PG8_LAS unsigned char* lds, const Gemm g, const Sched& S, const Epi& E) {
;     ...
;             const bool last = (t == nt - 2);
;             const char* a1 = cA + (size_t)(t + 1) * kstep;
;             const char* a2 = last ? nA : cA + (size_t)(t + 2) * kstep; const char* b2 = last ? nB : cB + (size_t)(t + 2) * kstep;
;             const char* a3 = a2 + kstep; const char* b3 = b2 + kstep;
;             if (last && has_next) S.a_ready(nxt);
;             if constexpr (SP2) {
;             PG8_LDB(B0, 0, 0); PG8_LDB(B1, 0, 1); PG8_SCHED; PG8_LDA(At, 0, 0); PG8_STAGE(PG8_SA(1, 1), a1 + hstep, voffA);
;             PG8_WAIT_V(8); PG8_WAIT_L(0); PG8_BAR; PG8_MMA(0, 0, At, B0); PG8_MMA(0, 1, At, B1); PG8_BAR; PG8_SCHED;
;             PG8_LDA(At, 0, 1); PG8_STAGE(PG8_SB(0, 0), b2, voffB); PG8_STAGE(PG8_SB(0, 1), b2 + hstep, voffB); PG8_STAGE(PG8_SA(0, 0), a2, voffA);
;             PG8_WAIT_V(8); PG8_WAIT_L(0); PG8_BAR; PG8_MMA(1, 0, At, B0); PG8_MMA(1, 1, At, B1); PG8_BAR; PG8_SCHED;
.LBB0_1042:
	ds_read_b128 v[140:143], v254
	ds_read_b128 v[166:169], v254 offset:1024
	ds_read_b128 v[170:173], v254 offset:2048
	ds_read_b128 v[174:177], v254 offset:3072
	ds_read_b128 v[178:181], v254 offset:16384
	ds_read_b128 v[182:185], v254 offset:17408
	ds_read_b128 v[186:189], v254 offset:18432
	ds_read_b128 v[210:213], v254 offset:19456
	s_add_u32 s2, s0, 0xfffc0080
	s_addc_u32 s3, s1, -1
	s_cmp_eq_u32 s55, 12
	s_cselect_b32 s5, s23, s3
	s_cselect_b32 s4, s51, s2
	s_cselect_b32 s3, s21, s54
	s_cselect_b32 s2, s52, s53
	s_add_i32 m0, s31, 0xc000
	ds_read_b128 v[214:217], v163
	ds_read_b128 v[218:221], v163 offset:1024
	ds_read_b128 v[222:225], v163 offset:2048
	ds_read_b128 v[226:229], v163 offset:3072
	ds_read_b128 v[230:233], v163 offset:4096
	ds_read_b128 v[234:237], v163 offset:5120
	ds_read_b128 v[238:241], v163 offset:6144
	ds_read_b128 v[242:245], v163 offset:7168
	global_load_lds_dwordx4 v136, s[0:1]
	s_add_i32 m0, s31, 0xe000
	s_nop 0
	global_load_lds_dwordx4 v138, s[0:1]
	s_waitcnt vmcnt(8)
	s_waitcnt lgkmcnt(0)
	s_barrier
	s_setprio 1
	v_mfma_f32_16x16x32_bf16 v[124:127], v[140:143], v[214:217], v[124:127]
	v_mfma_f32_16x16x32_bf16 v[108:111], v[140:143], v[222:225], v[108:111]
	v_mfma_f32_16x16x32_bf16 v[92:95], v[140:143], v[230:233], v[92:95]
	v_mfma_f32_16x16x32_bf16 v[76:79], v[140:143], v[238:241], v[76:79]
	v_mfma_f32_16x16x32_bf16 v[120:123], v[170:173], v[214:217], v[120:123]
	v_mfma_f32_16x16x32_bf16 v[104:107], v[170:173], v[222:225], v[104:107]
	v_mfma_f32_16x16x32_bf16 v[88:91], v[170:173], v[230:233], v[88:91]
	v_mfma_f32_16x16x32_bf16 v[72:75], v[170:173], v[238:241], v[72:75]
	v_mfma_f32_16x16x32_bf16 v[124:127], v[166:169], v[218:221], v[124:127]
	v_mfma_f32_16x16x32_bf16 v[108:111], v[166:169], v[226:229], v[108:111]
	v_mfma_f32_16x16x32_bf16 v[92:95], v[166:169], v[234:237], v[92:95]
	v_mfma_f32_16x16x32_bf16 v[76:79], v[166:169], v[242:245], v[76:79]
	v_mfma_f32_16x16x32_bf16 v[120:123], v[174:177], v[218:221], v[120:123]
	v_mfma_f32_16x16x32_bf16 v[104:107], v[174:177], v[226:229], v[104:107]
	v_mfma_f32_16x16x32_bf16 v[88:91], v[174:177], v[234:237], v[88:91]
	v_mfma_f32_16x16x32_bf16 v[72:75], v[174:177], v[242:245], v[72:75]
	v_mfma_f32_16x16x32_bf16 v[116:119], v[178:181], v[214:217], v[116:119]
	v_mfma_f32_16x16x32_bf16 v[100:103], v[178:181], v[222:225], v[100:103]
	v_mfma_f32_16x16x32_bf16 v[84:87], v[178:181], v[230:233], v[84:87]
	v_mfma_f32_16x16x32_bf16 v[68:71], v[178:181], v[238:241], v[68:71]
	v_mfma_f32_16x16x32_bf16 v[112:115], v[186:189], v[214:217], v[112:115]
	v_mfma_f32_16x16x32_bf16 v[96:99], v[186:189], v[222:225], v[96:99]
	v_mfma_f32_16x16x32_bf16 v[80:83], v[186:189], v[230:233], v[80:83]
	v_mfma_f32_16x16x32_bf16 v[64:67], v[186:189], v[238:241], v[64:67]
	v_mfma_f32_16x16x32_bf16 v[116:119], v[182:185], v[218:221], v[116:119]
	v_mfma_f32_16x16x32_bf16 v[100:103], v[182:185], v[226:229], v[100:103]
	v_mfma_f32_16x16x32_bf16 v[84:87], v[182:185], v[234:237], v[84:87]
	v_mfma_f32_16x16x32_bf16 v[68:71], v[182:185], v[242:245], v[68:71]
	v_mfma_f32_16x16x32_bf16 v[112:115], v[210:213], v[218:221], v[112:115]
	v_mfma_f32_16x16x32_bf16 v[96:99], v[210:213], v[226:229], v[96:99]
	v_mfma_f32_16x16x32_bf16 v[80:83], v[210:213], v[234:237], v[80:83]
	v_mfma_f32_16x16x32_bf16 v[64:67], v[210:213], v[242:245], v[64:67]
	s_setprio 0
	s_barrier
	s_mov_b32 m0, s33
	s_add_u32 s56, s2, 0x40000
	s_addc_u32 s57, s3, 0
	ds_read_b128 v[214:217], v163 offset:16384
	ds_read_b128 v[218:221], v163 offset:17408
	ds_read_b128 v[222:225], v163 offset:18432
	ds_read_b128 v[226:229], v163 offset:19456
	ds_read_b128 v[230:233], v163 offset:20480
	ds_read_b128 v[234:237], v163 offset:21504
	ds_read_b128 v[238:241], v163 offset:22528
	ds_read_b128 v[242:245], v163 offset:23552
	global_load_lds_dwordx4 v132, s[2:3]
	s_mov_b32 m0, s34
	s_nop 0
	global_load_lds_dwordx4 v128, s[2:3]
	s_mov_b32 m0, s35
	s_nop 0
	global_load_lds_dwordx4 v132, s[56:57]
	s_mov_b32 m0, s36
	s_nop 0
	global_load_lds_dwordx4 v128, s[56:57]
	s_mov_b32 m0, s31
	s_nop 0
	global_load_lds_dwordx4 v134, s[4:5]
	s_mov_b32 m0, s37
	s_nop 0
	global_load_lds_dwordx4 v130, s[4:5]
	s_waitcnt vmcnt(8)
	s_waitcnt lgkmcnt(0)
	s_barrier
	s_setprio 1
	v_mfma_f32_16x16x32_bf16 v[60:63], v[140:143], v[214:217], v[60:63]
	v_mfma_f32_16x16x32_bf16 v[44:47], v[140:143], v[222:225], v[44:47]
	v_mfma_f32_16x16x32_bf16 v[28:31], v[140:143], v[230:233], v[28:31]
	v_mfma_f32_16x16x32_bf16 v[12:15], v[140:143], v[238:241], v[12:15]
	v_mfma_f32_16x16x32_bf16 v[56:59], v[170:173], v[214:217], v[56:59]
	v_mfma_f32_16x16x32_bf16 v[40:43], v[170:173], v[222:225], v[40:43]
	v_mfma_f32_16x16x32_bf16 v[24:27], v[170:173], v[230:233], v[24:27]
	v_mfma_f32_16x16x32_bf16 v[8:11], v[170:173], v[238:241], v[8:11]
	v_mfma_f32_16x16x32_bf16 v[60:63], v[166:169], v[218:221], v[60:63]
	v_mfma_f32_16x16x32_bf16 v[44:47], v[166:169], v[226:229], v[44:47]
	v_mfma_f32_16x16x32_bf16 v[28:31], v[166:169], v[234:237], v[28:31]
	v_mfma_f32_16x16x32_bf16 v[12:15], v[166:169], v[242:245], v[12:15]
	v_mfma_f32_16x16x32_bf16 v[56:59], v[174:177], v[218:221], v[56:59]
	v_mfma_f32_16x16x32_bf16 v[40:43], v[174:177], v[226:229], v[40:43]
	v_mfma_f32_16x16x32_bf16 v[24:27], v[174:177], v[234:237], v[24:27]
	v_mfma_f32_16x16x32_bf16 v[8:11], v[174:177], v[242:245], v[8:11]
	v_mfma_f32_16x16x32_bf16 v[52:55], v[178:181], v[214:217], v[52:55]
	v_mfma_f32_16x16x32_bf16 v[36:39], v[178:181], v[222:225], v[36:39]
	v_mfma_f32_16x16x32_bf16 v[20:23], v[178:181], v[230:233], v[20:23]
	v_mfma_f32_16x16x32_bf16 v[4:7], v[178:181], v[238:241], v[4:7]
	v_mfma_f32_16x16x32_bf16 v[48:51], v[186:189], v[214:217], v[48:51]
	v_mfma_f32_16x16x32_bf16 v[32:35], v[186:189], v[222:225], v[32:35]
	v_mfma_f32_16x16x32_bf16 v[16:19], v[186:189], v[230:233], v[16:19]
	v_mfma_f32_16x16x32_bf16 v[0:3], v[186:189], v[238:241], v[0:3]
	v_mfma_f32_16x16x32_bf16 v[52:55], v[182:185], v[218:221], v[52:55]
	v_mfma_f32_16x16x32_bf16 v[36:39], v[182:185], v[226:229], v[36:39]
	v_mfma_f32_16x16x32_bf16 v[20:23], v[182:185], v[234:237], v[20:23]
	v_mfma_f32_16x16x32_bf16 v[4:7], v[182:185], v[242:245], v[4:7]
	v_mfma_f32_16x16x32_bf16 v[48:51], v[210:213], v[218:221], v[48:51]
	v_mfma_f32_16x16x32_bf16 v[32:35], v[210:213], v[226:229], v[32:35]
	v_mfma_f32_16x16x32_bf16 v[16:19], v[210:213], v[234:237], v[16:19]
	v_mfma_f32_16x16x32_bf16 v[0:3], v[210:213], v[242:245], v[0:3]
	s_setprio 0
	s_barrier
; #define PG8_STAGE(bufoff, gbase, voff) do { _Pragma("unroll") for (int _i = 0; _i < 2; ++_i) \
;         __builtin_amdgcn_global_load_lds((const unsigned*)((const char*)(gbase) + (voff)[_i]), (PG8_LAS unsigned*)(lds + (bufoff) + ldsw + _i * 8192), 16, 0, 0); } while (0)
; #define PG8_LDA(dst, b, h) do { _Pragma("unroll") for (int m = 0; m < 4; ++m) _Pragma("unroll") for (int k = 0; k < 2; ++k) dst[m][k] = *(const PG8_LAS bf16x8*)(lds + PG8_SA(b, h) + aoff + m * 2048 + k * 1024); } while (0)
; #define PG8_LDB(dst, b, h) do { _Pragma("unroll") for (int n = 0; n < 2; ++n) _Pragma("unroll") for (int k = 0; k < 2; ++k) dst[n][k] = *(const PG8_LAS bf16x8*)(lds + PG8_SB(b, h) + boff + n * 2048 + k * 1024); } while (0)
; #define PG8_MMA(ai, bj, At, Bt) do { __builtin_amdgcn_s_setprio(1); _Pragma("unroll") for (int m = 0; m < 4; ++m) _Pragma("unroll") for (int n = 0; n < 2; ++n) _Pragma("unroll") for (int k = 0; k < 2; ++k) \
;         acc[ai][bj][m][n] = __builtin_amdgcn_mfma_f32_16x16x32_bf16(Bt[n][k], At[m][k], acc[ai][bj][m][n], 0, 0, 0); __builtin_amdgcn_s_setprio(0); } while (0)
; #define PG8_WAIT_V(n) asm volatile("s_waitcnt vmcnt(" #n ")" ::: "memory")
; #define PG8_WAIT_L(n) asm volatile("s_waitcnt lgkmcnt(" #n ")" ::: "memory")
; #define PG8_BAR __builtin_amdgcn_s_barrier()
; #define PG8_SCHED __builtin_amdgcn_sched_barrier(0)
; template <class Epi, class Sched, bool ALIGN_EPI = false, bool SP2 = false>
; __device__ __forceinline__ void gemm_phase(PG8_LAS unsigned char* lds, const Gemm g, const Sched& S, const Epi& E) {
;     ...
;             PG8_LDB(B0, 1, 0); PG8_LDB(B1, 1, 1); PG8_SCHED; PG8_LDA(At, 1, 0); PG8_STAGE(PG8_SA(0, 1), a2 + hstep, voffA);
;             PG8_WAIT_V(8); PG8_WAIT_L(0); PG8_BAR; PG8_MMA(0, 0, At, B0); PG8_MMA(0, 1, At, B1); PG8_BAR; PG8_SCHED;
;             PG8_LDA(At, 1, 1); PG8_STAGE(PG8_SB(1, 0), b3, voffB); PG8_STAGE(PG8_SB(1, 1), b3 + hstep, voffB); PG8_STAGE(PG8_SA(1, 0), a3, voffA);
;             PG8_WAIT_V(8); PG8_WAIT_L(0); PG8_BAR; PG8_MMA(1, 0, At, B0); PG8_MMA(1, 1, At, B1); PG8_BAR; PG8_SCHED;
;     ...
;         }
;         if constexpr (ALIGN_EPI) { if (wr == 0) PG8_BAR; }
	ds_read_b128 v[140:143], v254 offset:32768
	ds_read_b128 v[166:169], v254 offset:33792
	ds_read_b128 v[170:173], v254 offset:34816
	ds_read_b128 v[174:177], v254 offset:35840
	ds_read_b128 v[178:181], v254 offset:49152
	ds_read_b128 v[182:185], v254 offset:50176
	ds_read_b128 v[186:189], v254 offset:51200
	ds_read_b128 v[210:213], v254 offset:52224
	s_add_u32 s4, s4, 0x40000
	s_addc_u32 s5, s5, 0
	s_mov_b32 m0, s38
	ds_read_b128 v[214:217], v163 offset:32768
	ds_read_b128 v[218:221], v163 offset:33792
	ds_read_b128 v[222:225], v163 offset:34816
	ds_read_b128 v[226:229], v163 offset:35840
	ds_read_b128 v[230:233], v163 offset:36864
	ds_read_b128 v[234:237], v163 offset:37888
	ds_read_b128 v[238:241], v163 offset:38912
	ds_read_b128 v[242:245], v163 offset:39936
	global_load_lds_dwordx4 v134, s[4:5]
	s_mov_b32 m0, s39
	s_nop 0
	global_load_lds_dwordx4 v130, s[4:5]
	s_waitcnt vmcnt(8)
	s_waitcnt lgkmcnt(0)
	s_barrier
	s_setprio 1
	v_mfma_f32_16x16x32_bf16 v[124:127], v[140:143], v[214:217], v[124:127]
	v_mfma_f32_16x16x32_bf16 v[108:111], v[140:143], v[222:225], v[108:111]
	v_mfma_f32_16x16x32_bf16 v[92:95], v[140:143], v[230:233], v[92:95]
	v_mfma_f32_16x16x32_bf16 v[76:79], v[140:143], v[238:241], v[76:79]
	v_mfma_f32_16x16x32_bf16 v[120:123], v[170:173], v[214:217], v[120:123]
	v_mfma_f32_16x16x32_bf16 v[104:107], v[170:173], v[222:225], v[104:107]
	v_mfma_f32_16x16x32_bf16 v[88:91], v[170:173], v[230:233], v[88:91]
	v_mfma_f32_16x16x32_bf16 v[72:75], v[170:173], v[238:241], v[72:75]
	v_mfma_f32_16x16x32_bf16 v[124:127], v[166:169], v[218:221], v[124:127]
	v_mfma_f32_16x16x32_bf16 v[108:111], v[166:169], v[226:229], v[108:111]
	v_mfma_f32_16x16x32_bf16 v[92:95], v[166:169], v[234:237], v[92:95]
	v_mfma_f32_16x16x32_bf16 v[76:79], v[166:169], v[242:245], v[76:79]
	v_mfma_f32_16x16x32_bf16 v[120:123], v[174:177], v[218:221], v[120:123]
	v_mfma_f32_16x16x32_bf16 v[104:107], v[174:177], v[226:229], v[104:107]
	v_mfma_f32_16x16x32_bf16 v[88:91], v[174:177], v[234:237], v[88:91]
	v_mfma_f32_16x16x32_bf16 v[72:75], v[174:177], v[242:245], v[72:75]
	v_mfma_f32_16x16x32_bf16 v[116:119], v[178:181], v[214:217], v[116:119]
	v_mfma_f32_16x16x32_bf16 v[100:103], v[178:181], v[222:225], v[100:103]
	v_mfma_f32_16x16x32_bf16 v[84:87], v[178:181], v[230:233], v[84:87]
	v_mfma_f32_16x16x32_bf16 v[68:71], v[178:181], v[238:241], v[68:71]
	v_mfma_f32_16x16x32_bf16 v[112:115], v[186:189], v[214:217], v[112:115]
	v_mfma_f32_16x16x32_bf16 v[96:99], v[186:189], v[222:225], v[96:99]
	v_mfma_f32_16x16x32_bf16 v[80:83], v[186:189], v[230:233], v[80:83]
	v_mfma_f32_16x16x32_bf16 v[64:67], v[186:189], v[238:241], v[64:67]
	v_mfma_f32_16x16x32_bf16 v[116:119], v[182:185], v[218:221], v[116:119]
	v_mfma_f32_16x16x32_bf16 v[100:103], v[182:185], v[226:229], v[100:103]
	v_mfma_f32_16x16x32_bf16 v[84:87], v[182:185], v[234:237], v[84:87]
	v_mfma_f32_16x16x32_bf16 v[68:71], v[182:185], v[242:245], v[68:71]
	v_mfma_f32_16x16x32_bf16 v[112:115], v[210:213], v[218:221], v[112:115]
	v_mfma_f32_16x16x32_bf16 v[96:99], v[210:213], v[226:229], v[96:99]
	v_mfma_f32_16x16x32_bf16 v[80:83], v[210:213], v[234:237], v[80:83]
	v_mfma_f32_16x16x32_bf16 v[64:67], v[210:213], v[242:245], v[64:67]
	s_setprio 0
	s_barrier
	s_mov_b32 m0, s43
	s_add_u32 s2, s2, 0x40080
	s_addc_u32 s3, s3, 0
	ds_read_b128 v[214:217], v163 offset:49152
	ds_read_b128 v[218:221], v163 offset:50176
	ds_read_b128 v[222:225], v163 offset:51200
	ds_read_b128 v[226:229], v163 offset:52224
	ds_read_b128 v[230:233], v163 offset:53248
	ds_read_b128 v[234:237], v163 offset:54272
	ds_read_b128 v[238:241], v163 offset:55296
	ds_read_b128 v[242:245], v163 offset:56320
	s_add_u32 s98, s2, 0xfffc0000
	s_addc_u32 s99, s3, -1
	global_load_lds_dwordx4 v132, s[98:99]
	s_mov_b32 m0, s44
	s_nop 0
	global_load_lds_dwordx4 v128, s[98:99]
	s_mov_b32 m0, s48
	s_nop 0
	global_load_lds_dwordx4 v132, s[2:3]
	s_mov_b32 m0, s49
	s_nop 0
	global_load_lds_dwordx4 v128, s[2:3]
	s_mov_b32 m0, s45
	s_nop 0
	s_add_u32 s100, s4, 0xfffc0080
	s_addc_u32 s101, s5, -1
	global_load_lds_dwordx4 v134, s[100:101]
	s_mov_b32 m0, s47
	s_nop 0
	global_load_lds_dwordx4 v130, s[100:101]
	s_waitcnt vmcnt(8)
	s_waitcnt lgkmcnt(0)
	s_barrier
	s_setprio 1
	v_mfma_f32_16x16x32_bf16 v[60:63], v[140:143], v[214:217], v[60:63]
	v_mfma_f32_16x16x32_bf16 v[44:47], v[140:143], v[222:225], v[44:47]
	v_mfma_f32_16x16x32_bf16 v[28:31], v[140:143], v[230:233], v[28:31]
	v_mfma_f32_16x16x32_bf16 v[12:15], v[140:143], v[238:241], v[12:15]
	v_mfma_f32_16x16x32_bf16 v[56:59], v[170:173], v[214:217], v[56:59]
	v_mfma_f32_16x16x32_bf16 v[40:43], v[170:173], v[222:225], v[40:43]
	v_mfma_f32_16x16x32_bf16 v[24:27], v[170:173], v[230:233], v[24:27]
	v_mfma_f32_16x16x32_bf16 v[8:11], v[170:173], v[238:241], v[8:11]
	v_mfma_f32_16x16x32_bf16 v[60:63], v[166:169], v[218:221], v[60:63]
	v_mfma_f32_16x16x32_bf16 v[44:47], v[166:169], v[226:229], v[44:47]
	v_mfma_f32_16x16x32_bf16 v[28:31], v[166:169], v[234:237], v[28:31]
	v_mfma_f32_16x16x32_bf16 v[12:15], v[166:169], v[242:245], v[12:15]
	v_mfma_f32_16x16x32_bf16 v[56:59], v[174:177], v[218:221], v[56:59]
	v_mfma_f32_16x16x32_bf16 v[40:43], v[174:177], v[226:229], v[40:43]
	v_mfma_f32_16x16x32_bf16 v[24:27], v[174:177], v[234:237], v[24:27]
	v_mfma_f32_16x16x32_bf16 v[8:11], v[174:177], v[242:245], v[8:11]
	v_mfma_f32_16x16x32_bf16 v[52:55], v[178:181], v[214:217], v[52:55]
	v_mfma_f32_16x16x32_bf16 v[36:39], v[178:181], v[222:225], v[36:39]
	v_mfma_f32_16x16x32_bf16 v[20:23], v[178:181], v[230:233], v[20:23]
	v_mfma_f32_16x16x32_bf16 v[4:7], v[178:181], v[238:241], v[4:7]
	v_mfma_f32_16x16x32_bf16 v[48:51], v[186:189], v[214:217], v[48:51]
	v_mfma_f32_16x16x32_bf16 v[32:35], v[186:189], v[222:225], v[32:35]
	v_mfma_f32_16x16x32_bf16 v[16:19], v[186:189], v[230:233], v[16:19]
	v_mfma_f32_16x16x32_bf16 v[0:3], v[186:189], v[238:241], v[0:3]
	v_mfma_f32_16x16x32_bf16 v[52:55], v[182:185], v[218:221], v[52:55]
	v_mfma_f32_16x16x32_bf16 v[36:39], v[182:185], v[226:229], v[36:39]
	v_mfma_f32_16x16x32_bf16 v[20:23], v[182:185], v[234:237], v[20:23]
	v_mfma_f32_16x16x32_bf16 v[4:7], v[182:185], v[242:245], v[4:7]
	v_mfma_f32_16x16x32_bf16 v[48:51], v[210:213], v[218:221], v[48:51]
	v_mfma_f32_16x16x32_bf16 v[32:35], v[210:213], v[226:229], v[32:35]
	v_mfma_f32_16x16x32_bf16 v[16:19], v[210:213], v[234:237], v[16:19]
	v_mfma_f32_16x16x32_bf16 v[0:3], v[210:213], v[242:245], v[0:3]
	s_setprio 0
	s_barrier
	s_add_i32 s55, s55, 2
	s_add_u32 s0, s0, 0x100
	s_addc_u32 s1, s1, 0
	s_add_u32 s53, s53, 0x100
	s_addc_u32 s54, s54, 0
	s_cmp_gt_u32 s55, 13
	s_cbranch_scc0 .LBB0_1042
	s_and_b64 vcc, exec, s[18:19]
	s_cbranch_vccz .LBB0_1045
	s_barrier
